# attention: m0 save/restore around LDS-DMA removed; fmaxf canonicalising v_max x,x folded in row-max chain
# speedup vs baseline: 1.0032x; 1.0032x over previous
; #define WAIT_BAR(N) asm volatile("s_waitcnt vmcnt(" #N ") lgkmcnt(0)\n\ts_barrier":::"memory")
;   #define DMA_K(t,slot) glds16(ksrc+(long)(t)*KVBLK*KP,(unsigned)__builtin_amdgcn_readfirstlane(kdst+(slot)))
;   #define DMA_V(t,slot) glds16(vsrc+(long)(t)*KVBLK*KP,(unsigned)__builtin_amdgcn_readfirstlane(vdst+(slot)))
; template<int THRL,int L,int NT> __device__ __forceinline__ void attn_unit(long rowbase,int kvh,int qblk,const bf16*Q,const bf16*__restrict__ K,const bf16*__restrict__ V,bf16*O,char*shm,const int tid){
;   const int lane=tid&63,r32=lane&31,hi=lane>>5; const int wid=__builtin_amdgcn_readfirstlane(tid>>6);
;   const int q0=qblk*64, qh=wid>>1, rh=wid&1;
;   const bf16*Qw=Q+(rowbase+q0+rh*QBLK)*QP+(4*kvh+qh)*D;
;   const bf16*Kh=K+rowbase*KP+kvh*D,*Vh=V+rowbase*KP+kvh*D;
;   const unsigned lds0=(unsigned)(uintptr_t)shm;
;   float*wsf=(float*)(shm+LDS_WS)+wid*64;
;   const bf16*ksrc=Kh+(long)lane*KP+wid*8;
;   const bf16*vsrc=Vh+(long)(16*(wid&3)+(lane>>2))*KP+(wid>>2)*32+(lane&3)*8;
;   const unsigned kdst=lds0+LDS_K+wid*1024, vdst=lds0+LDS_V+wid*1024;
;     ...
;   const int vb0=(int)(lds0+LDS_V)+((lane>>4)&1)*32+(lane&3)*8+(4*hi+((lane&15)>>2))*64;
;   const char*Kbase=shm+LDS_K; bf16x8 kf[8];
;   const lds_cptr shm3=(lds_cptr)shm; const lds_cptr kp0=shm3+LDS_K+hi*1024+r32*16; const lds_cptr vp0=shm3+LDS_V+((lane>>4)&1)*32+(lane&3)*8+(4*hi+((lane&15)>>2))*64;
;   DMA_K(0,0);DMA_V(0,0);DMA_K(1,SLOTB);
;   bf16x8 qr[4];
;   #pragma unroll
;   for(int d0=0;d0<4;++d0)qr[d0]=*reinterpret_cast<const bf16x8*>(&Qw[(long)r32*QP+d0*16+hi*8]);
;   if(q0+rh*QBLK+r32>=L){
;     #pragma unroll
;     for(int d0=0;d0<4;++d0)qr[d0]=bf16x8{0,0,0,0,0,0,0,0}; }
;   float mhat=0.f,l_reg=0.f;f32x16 o[2];o[0]=f32x16{};o[1]=f32x16{};f32x16 negm=f32x16{};asm volatile("":"+v"(negm));
;     ...
;   bool resc=false;
;     ...
;   f32x16 pA0,pA1,pB0,pB1;
;   int sl_prev=0,sl_cur=0,sl_next=SLOTB;
;     ...
;   DMA_K(2,2*SLOTB);
;   WAIT_BAR(3);
; __device__ __forceinline__ void attention_phase(const PT a, unsigned char* ws, int l, unsigned char* lds_generic, int tid, bool dry = false) {
;     ...
;         else { const int u2 = u - ATT_UNITS_P, s = u2 / 132, rem = u2 - s * 132, kvh = rem / 33, qblk = rem - kvh * 33;
;             attn_body::attn_unit<8, LS, 33>((long)ROWS_P + (long)s * LS, kvh, qblk, Q, K, V, O, (char*)lds_generic, tidu); }
.LBB0_874:
	v_mov_b32_e32 v204, v1
	s_mov_b64 s[4:5], -1
	v_and_b32_e32 v198, 63, v204
	v_and_b32_e32 v200, 31, v204
	v_lshlrev_b32_e32 v199, 3, v204
	s_cmpk_gt_i32 s66, 0x40f
	v_bfe_u32 v201, v204, 5, 1
	v_bfe_u32 v203, v204, 2, 4
	v_lshlrev_b32_e32 v192, 9, v198
	v_and_b32_e32 v202, 24, v199
	v_lshlrev_b32_e32 v205, 11, v200
	s_cbranch_scc0 .LBB0_915
	s_add_i32 s4, s66, 0xfffffbf0
	s_mul_hi_u32 s5, s4, 0x3e0f83e1
	s_lshr_b32 s97, s5, 5
	s_mul_i32 s5, s97, 0xffffff7c
	s_add_i32 s5, s5, s4
	s_mul_hi_i32 s4, s5, 0x3e0f83e1
	s_lshr_b32 s15, s4, 31
	s_ashr_i32 s4, s4, 3
	s_add_i32 s60, s4, s15
	s_mul_i32 s4, s60, 0xffffffdf
	s_add_i32 s18, s4, s5
	s_mul_i32 s4, s97, 0x810
	s_mul_hi_u32 s5, s97, 0x810
	s_add_u32 s4, s4, 0x4040
	s_addc_u32 s5, s5, 0
	v_readfirstlane_b32 s15, v204
	s_lshl_b32 s67, s18, 6
	s_ashr_i32 s68, s15, 6
	s_ashr_i32 s18, s67, 31
	s_add_u32 s19, s4, s67
	s_addc_u32 s58, s5, s18
	s_lshl_b32 s18, s68, 5
	s_and_b32 s92, s18, 32
	s_add_u32 s18, s19, s92
	s_addc_u32 s19, s58, 0
	s_lshl_b64 s[18:19], s[18:19], 11
	s_add_u32 s58, s6, s18
	s_addc_u32 s59, s71, s19
	s_ashr_i32 s19, s15, 1
	s_lshl_b32 s18, s60, 8
	s_andn2_b32 s19, s19, 63
	s_add_i32 s18, s19, s18
	s_ashr_i32 s19, s18, 31
	s_lshl_b64 s[18:19], s[18:19], 1
	s_add_u32 s58, s58, s18
	s_addc_u32 s59, s59, s19
	s_lshl_b64 s[4:5], s[4:5], 9
	s_add_u32 s62, s72, s4
	s_addc_u32 s63, s73, s5
	s_lshl_b32 s18, s60, 6
	s_ashr_i32 s19, s18, 31
	s_lshl_b64 s[60:61], s[18:19], 1
	s_add_u32 s18, s62, s60
	s_addc_u32 s19, s63, s61
	s_add_u32 s4, s74, s4
	s_addc_u32 s5, s75, s5
	s_add_u32 s4, s4, s60
	s_addc_u32 s5, s5, s61
	s_lshl_b32 s62, s68, 3
	v_lshl_add_u64 v[2:3], s[18:19], 0, v[192:193]
	s_ashr_i32 s63, s62, 31
	s_lshl_b32 s18, s68, 4
	v_lshl_add_u64 v[186:187], s[62:63], 1, v[2:3]
	v_and_or_b32 v2, s18, 48, v203
	v_lshlrev_b32_e32 v2, 9, v2
	v_mov_b32_e32 v3, v193
	v_lshl_add_u64 v[2:3], s[4:5], 0, v[2:3]
	s_ashr_i32 s4, s15, 3
	s_and_b32 s64, s4, 0xffffffe0
	s_ashr_i32 s65, s64, 31
	s_lshl_b32 s69, s68, 10
	s_cmp_lg_u32 0, -1
	s_cselect_b32 s4, 0, 0
	v_lshl_add_u64 v[2:3], s[64:65], 1, v[2:3]
	v_lshlrev_b32_e32 v4, 1, v202
	v_mov_b32_e32 v5, v193
	s_add_i32 s94, s69, s4
	s_mov_b32 m0, s94
	s_nop 0
	global_load_lds_dwordx4 v[186:187], off
	v_lshl_add_u64 v[194:195], v[2:3], 0, v[4:5]
	s_add_i32 s93, s94, 0x6000
	s_mov_b32 m0, s93
	s_nop 0
	global_load_lds_dwordx4 v[194:195], off
	v_lshl_add_u64 v[2:3], v[186:187], 0, s[26:27]
	s_add_i32 s4, s94, 0x2000
	s_mov_b32 m0, s4
	s_nop 0
	global_load_lds_dwordx4 v[2:3], off
	v_lshl_or_b32 v2, v201, 4, v205
	global_load_dwordx4 v[142:145], v2, s[58:59]
	global_load_dwordx4 v[138:141], v2, s[58:59] offset:32
	global_load_dwordx4 v[134:137], v2, s[58:59] offset:64
	global_load_dwordx4 v[130:133], v2, s[58:59] offset:96
	s_or_b32 s67, s92, s67
	v_or_b32_e32 v2, s67, v200
	v_cmp_lt_i32_e32 vcc, s82, v2
	s_and_saveexec_b64 s[4:5], vcc
	s_cbranch_execz .LBB0_877
	s_waitcnt vmcnt(3)
	v_mov_b32_e32 v142, 0
	v_mov_b32_e32 v143, v142
	v_mov_b32_e32 v144, v142
	v_mov_b32_e32 v145, v142
	s_waitcnt vmcnt(2)
	v_mov_b32_e32 v138, v142
	v_mov_b32_e32 v139, v142
	v_mov_b32_e32 v140, v142
	v_mov_b32_e32 v141, v142
	s_waitcnt vmcnt(1)
	v_mov_b32_e32 v134, v142
	v_mov_b32_e32 v135, v142
	v_mov_b32_e32 v136, v142
	v_mov_b32_e32 v137, v142
	s_waitcnt vmcnt(0)
	v_mov_b32_e32 v130, v142
	v_mov_b32_e32 v131, v142
	v_mov_b32_e32 v132, v142
	v_mov_b32_e32 v133, v142
.LBB0_877:
	s_or_b64 exec, exec, s[4:5]
	s_and_b32 s4, s15, 0x3fffffc0
	s_lshl_b32 s4, s4, 2
	s_add_i32 s92, s4, 0
	s_cmp_lg_u32 0, -1
	s_cselect_b32 s4, 0, 0
	v_lshlrev_b32_e32 v2, 10, v201
	v_lshlrev_b32_e32 v3, 4, v200
	v_mov_b32_e32 v18, v193
	v_mov_b32_e32 v19, v193
	v_mov_b32_e32 v20, v193
	v_mov_b32_e32 v21, v193
	v_mov_b32_e32 v22, v193
	v_mov_b32_e32 v23, v193
	v_mov_b32_e32 v24, v193
	v_mov_b32_e32 v25, v193
	v_mov_b32_e32 v26, v193
	v_mov_b32_e32 v27, v193
	v_mov_b32_e32 v28, v193
	v_mov_b32_e32 v29, v193
	v_mov_b32_e32 v30, v193
	v_mov_b32_e32 v31, v193
	v_mov_b32_e32 v32, v193
	v_mov_b32_e32 v33, v193
	s_add_i32 s4, s4, s69
	v_add3_u32 v211, 0, v2, v3
	v_lshl_add_u64 v[2:3], v[186:187], 0, s[28:29]
	s_add_i32 s5, s4, 0x4000
	s_mov_b32 m0, s5
	s_nop 0
	global_load_lds_dwordx4 v[2:3], off
	s_waitcnt vmcnt(3) lgkmcnt(0)
	s_barrier
; #define WAIT_BAR(N) asm volatile("s_waitcnt vmcnt(" #N ") lgkmcnt(0)\n\ts_barrier":::"memory")
;   #define DMA_K(t,slot) glds16(ksrc+(long)(t)*KVBLK*KP,(unsigned)__builtin_amdgcn_readfirstlane(kdst+(slot)))
;   #define DMA_V(t,slot) glds16(vsrc+(long)(t)*KVBLK*KP,(unsigned)__builtin_amdgcn_readfirstlane(vdst+(slot)))
;   #define CMASK(P0,P1,t) do{ if((t)>=NT-2)kmask(P0,P1,L-64*(t),hi);}while(0)
;   #define START(P0,P1) do{ const float rm=rowmax(P0,P1); resc=false; \
;     { const float dl=rm; mhat=fadd_s(mhat,dl); \
;       _Pragma("unroll") for(int r=0;r<16;++r){P0[r]=fsub_s(P0[r],dl);P1[r]=fsub_s(P1[r],dl);} \
;       _Pragma("unroll") for(int r=0;r<16;++r)negm[r]=-mhat; asm volatile("":"+v"(negm)); } \
;     _Pragma("unroll") for(int r=0;r<16;++r)P0[r]=__builtin_amdgcn_exp2f(P0[r]); }while(0)
;   #define ROT() do{sl_prev=sl_cur;sl_cur=sl_next;sl_next=(sl_next==(NSLOT-1)*SLOTB)?0:sl_next+SLOTB;}while(0)
;   #define CMASK(P0,P1,t) do{}while(0)
;   #define CMASK(P0,P1,t) do{ if((t)>=NT-2)kmask(P0,P1,L-64*(t),hi);}while(0)
; template<int THRL,int L,int NT> __device__ __forceinline__ void attn_unit(long rowbase,int kvh,int qblk,const bf16*Q,const bf16*__restrict__ K,const bf16*__restrict__ V,bf16*O,char*shm,const int tid){
;     ...
;   qkt(pA0,pA1,Kbase,qr,negm,r32,hi);asm volatile("s_nop 15\n\ts_nop 7":"+v"(pA0),"+v"(pA1));CMASK(pA0,pA1,0);
;   START(pA0,pA1);
;   _Pragma("unroll") for(int r=0;r<16;++r)pA1[r]=__builtin_amdgcn_exp2f(pA1[r]);
;   WAIT_BAR(0);
;   DMA_K(3,0);DMA_V(1,SLOTB);
;   ROT();
;   kload8(kf,kp0+sl_cur);
;   WAIT_BAR(2);
	ds_read_b128 v[2:5], v211
	ds_read_b128 v[6:9], v211 offset:512
	s_waitcnt vmcnt(3) lgkmcnt(1)
	v_mfma_f32_32x32x16_bf16 v[34:49], v[2:5], v[142:145], v[18:33]
	s_add_i32 s4, s4, 0x8000
	s_lshl_b64 s[64:65], s[64:65], 1
	s_add_u32 s64, s64, s60
	s_mul_hi_u32 s19, s97, 0x102000
	s_mul_i32 s97, s97, 0x102000
	s_addc_u32 s65, s65, s61
	s_add_u32 s64, s64, s97
	s_waitcnt lgkmcnt(0)
	v_mfma_f32_32x32x16_bf16 v[18:33], v[6:9], v[142:145], v[18:33]
	ds_read_b128 v[2:5], v211 offset:2048
	ds_read_b128 v[6:9], v211 offset:2560
	s_addc_u32 s65, s65, s19
	s_lshl_b32 s15, s15, 7
	s_and_b32 s15, s15, 0x6000
	s_lshl_b64 s[62:63], s[62:63], 1
	s_mov_b32 s96, 0
	s_mov_b32 s95, -1
	s_waitcnt vmcnt(2) lgkmcnt(1)
	v_mfma_f32_32x32x16_bf16 v[34:49], v[2:5], v[138:141], v[34:49]
	ds_read_b128 v[10:13], v211 offset:4608
	ds_read_b128 v[2:5], v211 offset:4096
	ds_read_b128 v[50:53], v211 offset:6656
	ds_read_b128 v[14:17], v211 offset:6144
	s_movk_i32 s18, 0x4000
	v_lshl_add_u32 v208, v200, 2, s92
	v_lshlrev_b32_e32 v212, 4, v201
	v_mov_b32_e32 v182, 0
	s_waitcnt lgkmcnt(4)
	v_mfma_f32_32x32x16_bf16 v[18:33], v[6:9], v[138:141], v[18:33]
	v_lshlrev_b32_e32 v6, 1, v204
	v_and_b32_e32 v206, 32, v6
	v_lshlrev_b32_e32 v6, 4, v204
	v_and_b32_e32 v6, 0xc0, v6
	v_lshl_or_b32 v207, v201, 8, v6
	v_add_u32_e32 v6, 0, v206
	v_add3_u32 v209, v6, v202, v207
	s_waitcnt vmcnt(1) lgkmcnt(2)
	v_mfma_f32_32x32x16_bf16 v[34:49], v[2:5], v[134:137], v[34:49]
	v_mov_b32_e32 v2, v193
	v_mov_b32_e32 v3, v193
	v_mov_b32_e32 v4, v193
	v_mov_b32_e32 v5, v193
	v_mov_b32_e32 v6, v193
	v_mov_b32_e32 v7, v193
	v_mov_b32_e32 v8, v193
	v_mfma_f32_32x32x16_bf16 v[18:33], v[10:13], v[134:137], v[18:33]
	v_mov_b32_e32 v9, v193
	v_mov_b32_e32 v10, v193
	v_mov_b32_e32 v11, v193
	v_mov_b32_e32 v12, v193
	v_mov_b32_e32 v13, v193
	s_waitcnt vmcnt(0) lgkmcnt(0)
	v_mfma_f32_32x32x16_bf16 v[34:49], v[14:17], v[130:133], v[34:49]
	v_mov_b32_e32 v16, v193
	v_mov_b32_e32 v17, v193
	v_mov_b32_e32 v14, v193
	v_mov_b32_e32 v15, v193
	v_mfma_f32_32x32x16_bf16 v[18:33], v[50:53], v[130:133], v[18:33]
	s_nop 15
	s_nop 7
	s_nop 0
	v_max3_f32 v50, v34, v35, v18
	v_max3_f32 v51, v36, v37, v19
	s_nop 0
	v_max3_f32 v50, v50, v20, v21
	v_max3_f32 v51, v51, v40, v41
	s_nop 0
	v_max3_f32 v50, v50, v38, v39
	v_max3_f32 v51, v51, v24, v25
	s_nop 0
	v_max3_f32 v50, v50, v22, v23
	v_max3_f32 v51, v51, v44, v45
	s_nop 0
	v_max3_f32 v50, v50, v42, v43
	v_max3_f32 v51, v51, v28, v29
	s_nop 0
	v_max3_f32 v50, v50, v26, v27
	v_max3_f32 v51, v51, v48, v49
	s_nop 0
	v_max3_f32 v50, v50, v46, v47
	v_max3_f32 v51, v51, v32, v33
	s_nop 0
	v_max3_f32 v50, v50, v30, v31
	s_nop 0
	v_max_f32_e32 v50, v50, v51
	s_nop 0
	v_mov_b32_e32 v51, v50
	s_nop 1
	v_permlane32_swap_b32_e32 v50, v51
	v_max_f32_e32 v50, v50, v51
	s_nop 0
	v_add_f32_e32 v210, v193, v50
	v_sub_f32_e32 v51, v34, v50
	v_sub_f32_e32 v52, v35, v50
	v_sub_f32_e32 v53, v36, v50
	v_sub_f32_e32 v54, v37, v50
	v_sub_f32_e32 v55, v38, v50
	s_nop 0
	v_xor_b32_e32 v34, 0x80000000, v210
	v_sub_f32_e32 v56, v39, v50
	v_sub_f32_e32 v57, v40, v50
	v_sub_f32_e32 v58, v41, v50
	v_sub_f32_e32 v59, v42, v50
	v_sub_f32_e32 v60, v43, v50
	v_sub_f32_e32 v61, v44, v50
	v_sub_f32_e32 v62, v45, v50
	v_sub_f32_e32 v63, v46, v50
	v_sub_f32_e32 v64, v47, v50
	v_sub_f32_e32 v65, v48, v50
	v_sub_f32_e32 v81, v49, v50
	v_mov_b32_e32 v35, v34
	v_mov_b32_e32 v36, v34
	v_mov_b32_e32 v37, v34
	v_mov_b32_e32 v38, v34
	v_mov_b32_e32 v39, v34
	v_mov_b32_e32 v40, v34
	v_mov_b32_e32 v41, v34
	v_mov_b32_e32 v42, v34
	v_mov_b32_e32 v43, v34
	v_mov_b32_e32 v44, v34
	v_mov_b32_e32 v45, v34
	v_mov_b32_e32 v46, v34
	v_mov_b32_e32 v47, v34
	v_mov_b32_e32 v48, v34
	v_mov_b32_e32 v49, v34
	v_sub_f32_e32 v18, v18, v50
	v_sub_f32_e32 v19, v19, v50
	s_waitcnt vmcnt(0) lgkmcnt(0)
	s_barrier
	v_sub_f32_e32 v20, v20, v50
	v_sub_f32_e32 v21, v21, v50
	v_sub_f32_e32 v22, v22, v50
	v_sub_f32_e32 v23, v23, v50
	v_sub_f32_e32 v24, v24, v50
	v_sub_f32_e32 v25, v25, v50
	v_sub_f32_e32 v26, v26, v50
	v_sub_f32_e32 v27, v27, v50
	v_sub_f32_e32 v28, v28, v50
	v_sub_f32_e32 v29, v29, v50
	v_sub_f32_e32 v30, v30, v50
	v_sub_f32_e32 v31, v31, v50
	v_sub_f32_e32 v32, v32, v50
	v_sub_f32_e32 v33, v33, v50
	v_exp_f32_e32 v66, v51
	v_exp_f32_e32 v50, v18
	v_exp_f32_e32 v51, v19
	v_lshl_add_u64 v[18:19], v[186:187], 0, s[30:31]
	s_mov_b32 m0, s94
	s_nop 0
	global_load_lds_dwordx4 v[18:19], off
	v_lshl_add_u64 v[18:19], v[194:195], 0, s[26:27]
	s_mov_b32 m0, s4
	s_nop 0
	global_load_lds_dwordx4 v[18:19], off
	ds_read_b128 v[82:85], v211 offset:8192
	ds_read_b128 v[170:173], v211 offset:8704
	ds_read_b128 v[166:169], v211 offset:10240
	ds_read_b128 v[162:165], v211 offset:10752
	ds_read_b128 v[126:129], v211 offset:12288
	ds_read_b128 v[122:125], v211 offset:12800
	ds_read_b128 v[118:121], v211 offset:14336
	ds_read_b128 v[114:117], v211 offset:14848
	v_exp_f32_e32 v67, v52
	v_exp_f32_e32 v52, v20
	v_lshl_or_b32 v20, v203, 9, s15
	s_add_u32 s15, s76, s62
	v_and_b32_e32 v18, 3, v204
	s_addc_u32 s62, s77, s63
	v_lshlrev_b32_e32 v18, 4, v18
	v_mov_b32_e32 v19, v193
	s_add_u32 s15, s15, s60
	v_exp_f32_e32 v68, v53
	v_exp_f32_e32 v69, v54
	v_exp_f32_e32 v70, v55
	v_exp_f32_e32 v71, v56
	v_exp_f32_e32 v72, v57
	v_exp_f32_e32 v73, v58
	v_exp_f32_e32 v74, v59
	v_exp_f32_e32 v75, v60
	v_exp_f32_e32 v76, v61
	v_exp_f32_e32 v77, v62
	v_exp_f32_e32 v78, v63
	v_exp_f32_e32 v79, v64
	v_exp_f32_e32 v80, v65
	v_exp_f32_e32 v81, v81
	v_exp_f32_e32 v53, v21
	v_exp_f32_e32 v54, v22
	v_exp_f32_e32 v55, v23
	v_exp_f32_e32 v56, v24
	v_exp_f32_e32 v57, v25
	v_exp_f32_e32 v58, v26
	v_exp_f32_e32 v59, v27
	v_exp_f32_e32 v60, v28
	v_exp_f32_e32 v61, v29
	v_exp_f32_e32 v62, v30
	v_exp_f32_e32 v63, v31
	v_exp_f32_e32 v64, v32
	v_exp_f32_e32 v65, v33
	v_lshl_add_u64 v[18:19], s[64:65], 0, v[18:19]
	v_mov_b32_e32 v21, v193
	s_addc_u32 s61, s62, s61
	s_waitcnt vmcnt(2) lgkmcnt(0)
	s_barrier
	v_lshl_add_u64 v[18:19], v[18:19], 0, v[20:21]
	s_add_u32 s60, s15, s97
	v_lshl_add_u64 v[188:189], s[10:11], 0, v[18:19]
	s_addc_u32 s61, s61, s19
	v_mov_b64_e32 v[32:33], v[16:17]
	v_cmp_gt_u32_e64 s[4:5], 32, v198
	v_lshl_add_u64 v[196:197], s[60:61], 0, v[192:193]
	s_movk_i32 s64, 0x2000
	v_mov_b64_e32 v[30:31], v[14:15]
	v_mov_b64_e32 v[28:29], v[12:13]
	v_mov_b64_e32 v[26:27], v[10:11]
	v_mov_b64_e32 v[24:25], v[8:9]
	v_mov_b64_e32 v[22:23], v[6:7]
	v_mov_b64_e32 v[20:21], v[4:5]
	v_mov_b64_e32 v[18:19], v[2:3]
.LBB0_878:
	v_add_u32_e32 v183, s96, v209
	ds_read_b64_tr_b16 v[178:179], v183 offset:24576
	ds_read_b64_tr_b16 v[180:181], v183 offset:25088
	v_mfma_f32_32x32x16_bf16 v[98:113], v[82:85], v[142:145], v[34:49]
	v_add_f32_e32 v86, v66, v67
	v_add_f32_e32 v86, v68, v86
	v_add_f32_e32 v86, v69, v86
	v_add_f32_e32 v86, v70, v86
	v_add_f32_e32 v86, v71, v86
	v_cvt_pk_bf16_f32 v158, v66, v67
	v_cvt_pk_bf16_f32 v159, v68, v69
	ds_read_b64_tr_b16 v[174:175], v183 offset:28672
	ds_read_b64_tr_b16 v[176:177], v183 offset:29184
	v_add_f32_e32 v66, v72, v86
	v_mfma_f32_32x32x16_bf16 v[82:97], v[170:173], v[142:145], v[34:49]
	v_add_f32_e32 v66, v73, v66
	v_add_f32_e32 v66, v74, v66
	v_add_f32_e32 v66, v75, v66
	v_cvt_pk_bf16_f32 v160, v70, v71
	v_cvt_pk_bf16_f32 v161, v72, v73
	ds_read_b64_tr_b16 v[170:171], v183 offset:25600
	ds_read_b64_tr_b16 v[172:173], v183 offset:26112
	v_mfma_f32_32x32x16_bf16 v[98:113], v[166:169], v[138:141], v[98:113]
	v_add_f32_e32 v66, v76, v66
	v_add_f32_e32 v66, v77, v66
	v_add_f32_e32 v66, v78, v66
	v_add_f32_e32 v66, v79, v66
	v_cvt_pk_bf16_f32 v154, v74, v75
	v_cvt_pk_bf16_f32 v155, v76, v77
	ds_read_b64_tr_b16 v[74:75], v183 offset:29696
	ds_read_b64_tr_b16 v[76:77], v183 offset:30208
	v_mfma_f32_32x32x16_bf16 v[82:97], v[162:165], v[138:141], v[82:97]
	v_add_f32_e32 v66, v80, v66
	v_add_f32_e32 v66, v81, v66
	v_add_f32_e32 v66, v50, v66
	v_add_f32_e32 v66, v51, v66
	v_cvt_pk_bf16_f32 v156, v78, v79
	v_cvt_pk_bf16_f32 v157, v80, v81
	ds_read_b64_tr_b16 v[70:71], v183 offset:26624
	ds_read_b64_tr_b16 v[72:73], v183 offset:27136
	v_mfma_f32_32x32x16_bf16 v[98:113], v[126:129], v[134:137], v[98:113]
	v_add_f32_e32 v66, v52, v66
	v_add_f32_e32 v66, v53, v66
	v_add_f32_e32 v66, v54, v66
	v_add_f32_e32 v78, v55, v66
	v_cvt_pk_bf16_f32 v150, v50, v51
	v_cvt_pk_bf16_f32 v151, v52, v53
	ds_read_b64_tr_b16 v[66:67], v183 offset:30720
	ds_read_b64_tr_b16 v[68:69], v183 offset:31232
	v_mfma_f32_32x32x16_bf16 v[82:97], v[122:125], v[134:137], v[82:97]
	v_add_f32_e32 v50, v56, v78
	v_add_f32_e32 v50, v57, v50
	v_add_f32_e32 v50, v58, v50
	v_add_f32_e32 v50, v59, v50
	v_cvt_pk_bf16_f32 v152, v54, v55
	v_cvt_pk_bf16_f32 v153, v56, v57
	ds_read_b64_tr_b16 v[54:55], v183 offset:27648
	ds_read_b64_tr_b16 v[56:57], v183 offset:28160
	v_mfma_f32_32x32x16_bf16 v[98:113], v[118:121], v[130:133], v[98:113]
	v_add_f32_e32 v50, v60, v50
	v_add_f32_e32 v50, v61, v50
	v_add_f32_e32 v50, v62, v50
	v_add_f32_e32 v78, v63, v50
	v_cvt_pk_bf16_f32 v146, v58, v59
	v_cvt_pk_bf16_f32 v147, v60, v61
	ds_read_b64_tr_b16 v[50:51], v183 offset:31744
	ds_read_b64_tr_b16 v[52:53], v183 offset:32256
	v_mfma_f32_32x32x16_bf16 v[82:97], v[114:117], v[130:133], v[82:97]
	v_add_f32_e32 v58, v64, v78
	v_add_f32_e32 v58, v65, v58
	v_add_f32_e32 v60, 0, v58
	v_cvt_pk_bf16_f32 v148, v62, v63
	v_cvt_pk_bf16_f32 v149, v64, v65
	v_lshl_add_u64 v[58:59], v[196:197], 0, s[30:31]
	s_add_i32 s15, s64, s94
	s_mov_b32 m0, s15
	s_nop 0
	global_load_lds_dwordx4 v[58:59], off
	v_lshl_add_u64 v[58:59], v[188:189], 0, s[26:27]
	s_add_i32 s15, s18, s93
	s_mov_b32 m0, s15
	s_nop 0
	global_load_lds_dwordx4 v[58:59], off
	v_max_f32_e32 v58, v98, v99
	v_max3_f32 v59, v100, v101, v83
	v_max3_f32 v58, v58, v82, v84
	v_max3_f32 v58, v58, v85, v102
	v_max3_f32 v59, v59, v104, v105
	v_max3_f32 v58, v58, v103, v86
	v_max3_f32 v59, v59, v88, v89
	v_max3_f32 v58, v58, v87, v106
	v_max3_f32 v59, v59, v108, v109
	v_max3_f32 v58, v58, v107, v90
	v_max3_f32 v59, v59, v92, v93
	v_max3_f32 v58, v58, v91, v110
	v_max3_f32 v59, v59, v112, v113
	v_max3_f32 v58, v58, v111, v94
	v_max3_f32 v59, v59, v96, v97
	v_max3_f32 v58, v58, v95, v59
	v_mov_b32_e32 v59, v58
	s_nop 1
	v_permlane32_swap_b32_e32 v58, v59
	v_max_f32_e32 v58, v58, v59
	v_cmp_lt_f32_e32 vcc, s83, v58
	s_cmp_lg_u64 vcc, 0
	v_add_f32_e32 v213, v182, v60
	s_cselect_b64 s[60:61], -1, 0
	s_cbranch_vccnz .LBB0_886

.LBB0_881:
	s_add_i32 s15, s18, 0x2000
	s_cmpk_lg_i32 s18, 0x4000
	s_cselect_b32 s65, s15, 0
	v_add_u32_e32 v214, s64, v209
	ds_read_b64_tr_b16 v[126:127], v214 offset:24576
	ds_read_b64_tr_b16 v[128:129], v214 offset:25088
	v_mfma_f32_32x32x16_bf16 v[66:81], v[58:61], v[142:145], v[34:49]
	v_add_f32_e32 v50, v98, v99
	v_add_f32_e32 v50, v100, v50
	v_add_f32_e32 v50, v101, v50
	v_add_f32_e32 v50, v102, v50
	v_add_f32_e32 v50, v103, v50
	v_cvt_pk_bf16_f32 v158, v98, v99
	v_cvt_pk_bf16_f32 v159, v100, v101
	ds_read_b64_tr_b16 v[122:123], v214 offset:28672
	ds_read_b64_tr_b16 v[124:125], v214 offset:29184
	v_add_f32_e32 v50, v104, v50
	v_add_f32_e32 v50, v105, v50
	v_add_f32_e32 v50, v106, v50
	v_add_f32_e32 v98, v107, v50
	v_mfma_f32_32x32x16_bf16 v[50:65], v[114:117], v[142:145], v[34:49]
	v_cvt_pk_bf16_f32 v160, v102, v103
	v_cvt_pk_bf16_f32 v161, v104, v105
	ds_read_b64_tr_b16 v[118:119], v214 offset:25600
	ds_read_b64_tr_b16 v[120:121], v214 offset:26112
	v_mfma_f32_32x32x16_bf16 v[66:81], v[182:185], v[138:141], v[66:81]
	v_add_f32_e32 v98, v108, v98
	v_add_f32_e32 v98, v109, v98
	v_add_f32_e32 v98, v110, v98
	v_add_f32_e32 v98, v111, v98
	v_cvt_pk_bf16_f32 v154, v106, v107
	v_cvt_pk_bf16_f32 v155, v108, v109
	ds_read_b64_tr_b16 v[114:115], v214 offset:29696
	ds_read_b64_tr_b16 v[116:117], v214 offset:30208
	v_mfma_f32_32x32x16_bf16 v[50:65], v[174:177], v[138:141], v[50:65]
	v_add_f32_e32 v98, v112, v98
	v_add_f32_e32 v98, v113, v98
	v_add_f32_e32 v98, v82, v98
	v_add_f32_e32 v98, v83, v98
	v_cvt_pk_bf16_f32 v156, v110, v111
	v_cvt_pk_bf16_f32 v157, v112, v113
	ds_read_b64_tr_b16 v[106:107], v214 offset:26624
	ds_read_b64_tr_b16 v[108:109], v214 offset:27136
	v_mfma_f32_32x32x16_bf16 v[66:81], v[178:181], v[134:137], v[66:81]
	v_add_f32_e32 v98, v84, v98
	v_add_f32_e32 v98, v85, v98
	v_add_f32_e32 v98, v86, v98
	v_add_f32_e32 v98, v87, v98
	v_cvt_pk_bf16_f32 v150, v82, v83
	v_cvt_pk_bf16_f32 v151, v84, v85
	ds_read_b64_tr_b16 v[102:103], v214 offset:30720
	ds_read_b64_tr_b16 v[104:105], v214 offset:31232
	v_mfma_f32_32x32x16_bf16 v[50:65], v[166:169], v[134:137], v[50:65]
	v_add_f32_e32 v82, v88, v98
	v_add_f32_e32 v82, v89, v82
	v_add_f32_e32 v82, v90, v82
	v_add_f32_e32 v82, v91, v82
	v_cvt_pk_bf16_f32 v152, v86, v87
	v_cvt_pk_bf16_f32 v153, v88, v89
	ds_read_b64_tr_b16 v[98:99], v214 offset:27648
	ds_read_b64_tr_b16 v[100:101], v214 offset:28160
	v_mfma_f32_32x32x16_bf16 v[66:81], v[170:173], v[130:133], v[66:81]
	v_add_f32_e32 v82, v92, v82
	v_add_f32_e32 v82, v93, v82
	v_add_f32_e32 v82, v94, v82
	v_add_f32_e32 v82, v95, v82
	v_cvt_pk_bf16_f32 v146, v90, v91
	v_cvt_pk_bf16_f32 v147, v92, v93
	ds_read_b64_tr_b16 v[86:87], v214 offset:31744
	ds_read_b64_tr_b16 v[88:89], v214 offset:32256
	v_mfma_f32_32x32x16_bf16 v[50:65], v[162:165], v[130:133], v[50:65]
	v_add_f32_e32 v82, v96, v82
	v_add_f32_e32 v82, v97, v82
	v_add_f32_e32 v84, 0, v82
	v_cvt_pk_bf16_f32 v148, v94, v95
	v_cvt_pk_bf16_f32 v149, v96, v97
	v_lshl_add_u64 v[82:83], v[196:197], 0, s[34:35]
	s_add_i32 s15, s18, s94
	s_mov_b32 m0, s15
	s_nop 0
	global_load_lds_dwordx4 v[82:83], off
	v_max_f32_e32 v82, v66, v67
	s_nop 1
	v_max3_f32 v83, v68, v69, v51
	v_max3_f32 v82, v82, v50, v52
	v_max3_f32 v82, v82, v53, v70
	v_max3_f32 v83, v83, v72, v73
	v_max3_f32 v82, v82, v71, v54
	v_max3_f32 v83, v83, v56, v57
	v_max3_f32 v82, v82, v55, v74
	v_max3_f32 v83, v83, v76, v77
	v_max3_f32 v82, v82, v75, v58
	v_max3_f32 v83, v83, v60, v61
	v_max3_f32 v82, v82, v59, v78
	v_max3_f32 v83, v83, v80, v81
	v_max3_f32 v82, v82, v79, v62
	v_max3_f32 v83, v83, v64, v65
	v_max3_f32 v82, v82, v63, v83
	v_mov_b32_e32 v83, v82
	s_nop 1
	v_permlane32_swap_b32_e32 v82, v83
	v_max_f32_e32 v82, v82, v83
	v_lshl_add_u64 v[188:189], v[188:189], 0, s[28:29]
	s_add_i32 s15, s65, s93
	s_mov_b32 m0, s15
	s_nop 0
	global_load_lds_dwordx4 v[188:189], off
	v_cmp_lt_f32_e32 vcc, s83, v82
	s_cmp_lg_u64 vcc, 0
	v_add_f32_e32 v182, v213, v84
	s_cselect_b64 s[60:61], -1, 0
	s_cbranch_vccnz .LBB0_889

;   #define RESC() do{ if(resc){ asm volatile("s_waitcnt lgkmcnt(0)":::"memory"); \
;       _Pragma("unroll") for(int d_=0;d_<2;++d_) _Pragma("unroll") for(int r=0;r<16;++r)o[d_][r]*=wsf[crow(r,hi)]; } }while(0)
;   #define ROT() do{sl_prev=sl_cur;sl_cur=sl_next;sl_next=(sl_next==(NSLOT-1)*SLOTB)?0:sl_next+SLOTB;}while(0)
;   #define ENDW(tt) do{ if((tt)+3<NT){WAIT_BAR(2);} else if((tt)+2<NT){WAIT_BAR(1);} else {WAIT_BAR(0);} }while(0)
; template<int THRL,int L,int NT> __device__ __forceinline__ void attn_unit(long rowbase,int kvh,int qblk,const bf16*Q,const bf16*__restrict__ K,const bf16*__restrict__ V,bf16*O,char*shm,const int tid){
;     ...
;   for(;t+1<NT;t+=2){
;     STEP(pB0,pB1,pA0,pA1,t,(t+3<NT),(t+1<NT),(t+1<NT));       ENDW(t);   RESC(); ROT();
;     STEP(pA0,pA1,pB0,pB1,t+1,(t+4<NT),(t+2<NT),(t+2<NT));     ENDW(t+1); RESC(); ROT();
.LBB0_892:
	ds_read_b64_tr_b16 v[178:179], v209 offset:32768
	ds_read_b64_tr_b16 v[180:181], v209 offset:33280
	s_waitcnt lgkmcnt(9)
	v_mfma_f32_32x32x16_bf16 v[98:113], v[82:85], v[142:145], v[34:49]
	v_add_f32_e32 v86, v66, v67
	v_add_f32_e32 v86, v68, v86
	v_add_f32_e32 v86, v69, v86
	v_add_f32_e32 v86, v70, v86
	v_add_f32_e32 v86, v71, v86
	v_cvt_pk_bf16_f32 v158, v66, v67
	v_cvt_pk_bf16_f32 v159, v68, v69
	ds_read_b64_tr_b16 v[174:175], v209 offset:36864
	ds_read_b64_tr_b16 v[176:177], v209 offset:37376
	v_add_f32_e32 v66, v72, v86
	s_waitcnt lgkmcnt(10)
	v_mfma_f32_32x32x16_bf16 v[82:97], v[170:173], v[142:145], v[34:49]
	v_add_f32_e32 v66, v73, v66
	v_add_f32_e32 v66, v74, v66
	v_add_f32_e32 v66, v75, v66
	v_cvt_pk_bf16_f32 v160, v70, v71
	v_cvt_pk_bf16_f32 v161, v72, v73
	ds_read_b64_tr_b16 v[170:171], v209 offset:33792
	ds_read_b64_tr_b16 v[172:173], v209 offset:34304
	s_waitcnt lgkmcnt(11)
	v_mfma_f32_32x32x16_bf16 v[98:113], v[166:169], v[138:141], v[98:113]
	v_add_f32_e32 v66, v76, v66
	v_add_f32_e32 v66, v77, v66
	v_add_f32_e32 v66, v78, v66
	v_add_f32_e32 v66, v79, v66
	v_cvt_pk_bf16_f32 v154, v74, v75
	v_cvt_pk_bf16_f32 v155, v76, v77
	ds_read_b64_tr_b16 v[74:75], v209 offset:37888
	ds_read_b64_tr_b16 v[76:77], v209 offset:38400
	s_waitcnt lgkmcnt(12)
	v_mfma_f32_32x32x16_bf16 v[82:97], v[162:165], v[138:141], v[82:97]
	v_add_f32_e32 v66, v80, v66
	v_add_f32_e32 v66, v81, v66
	v_add_f32_e32 v66, v50, v66
	v_add_f32_e32 v66, v51, v66
	v_cvt_pk_bf16_f32 v156, v78, v79
	v_cvt_pk_bf16_f32 v157, v80, v81
	ds_read_b64_tr_b16 v[70:71], v209 offset:34816
	ds_read_b64_tr_b16 v[72:73], v209 offset:35328
	s_waitcnt lgkmcnt(13)
	v_mfma_f32_32x32x16_bf16 v[98:113], v[126:129], v[134:137], v[98:113]
	v_add_f32_e32 v66, v52, v66
	v_add_f32_e32 v66, v53, v66
	v_add_f32_e32 v66, v54, v66
	v_add_f32_e32 v78, v55, v66
	v_cvt_pk_bf16_f32 v150, v50, v51
	v_cvt_pk_bf16_f32 v151, v52, v53
	ds_read_b64_tr_b16 v[66:67], v209 offset:38912
	ds_read_b64_tr_b16 v[68:69], v209 offset:39424
	s_waitcnt lgkmcnt(14)
	v_mfma_f32_32x32x16_bf16 v[82:97], v[122:125], v[134:137], v[82:97]
	v_add_f32_e32 v50, v56, v78
	v_add_f32_e32 v50, v57, v50
	v_add_f32_e32 v50, v58, v50
	v_add_f32_e32 v50, v59, v50
	v_cvt_pk_bf16_f32 v152, v54, v55
	v_cvt_pk_bf16_f32 v153, v56, v57
	ds_read_b64_tr_b16 v[54:55], v209 offset:35840
	ds_read_b64_tr_b16 v[56:57], v209 offset:36352
	s_waitcnt lgkmcnt(14)
	v_mfma_f32_32x32x16_bf16 v[98:113], v[118:121], v[130:133], v[98:113]
	v_add_f32_e32 v50, v60, v50
	v_add_f32_e32 v50, v61, v50
	v_add_f32_e32 v50, v62, v50
	v_add_f32_e32 v78, v63, v50
	v_cvt_pk_bf16_f32 v146, v58, v59
	v_cvt_pk_bf16_f32 v147, v60, v61
	ds_read_b64_tr_b16 v[50:51], v209 offset:39936
	ds_read_b64_tr_b16 v[52:53], v209 offset:40448
	v_mfma_f32_32x32x16_bf16 v[82:97], v[114:117], v[130:133], v[82:97]
	v_add_f32_e32 v58, v64, v78
	v_add_f32_e32 v58, v65, v58
	v_add_f32_e32 v58, 0, v58
	v_cvt_pk_bf16_f32 v148, v62, v63
	v_cvt_pk_bf16_f32 v149, v64, v65
	s_cmp_lg_u32 0, -1
	s_cselect_b32 s15, 0, 0
	v_add_f32_e32 v197, v182, v58
	v_lshl_add_u64 v[58:59], v[186:187], 0, s[36:37]
	s_add_i32 s15, s15, s69
	s_addk_i32 s15, 0x4000
	s_mov_b32 m0, s15
	s_nop 0
	global_load_lds_dwordx4 v[58:59], off
	v_lshl_add_u64 v[58:59], v[194:195], 0, s[38:39]
	s_mov_b32 m0, s93
	s_nop 0
	global_load_lds_dwordx4 v[58:59], off
	v_max_f32_e32 v58, v98, v99
	v_max3_f32 v59, v100, v101, v83
	v_max3_f32 v58, v58, v82, v84
	v_max3_f32 v58, v58, v85, v102
	v_max3_f32 v59, v59, v104, v105
	v_max3_f32 v58, v58, v103, v86
	v_max3_f32 v59, v59, v88, v89
	v_max3_f32 v58, v58, v87, v106
	v_max3_f32 v59, v59, v108, v109
	v_max3_f32 v58, v58, v107, v90
	v_max3_f32 v59, v59, v92, v93
	v_max3_f32 v58, v58, v91, v110
	v_max3_f32 v59, v59, v112, v113
	v_max3_f32 v58, v58, v111, v94
	v_max3_f32 v59, v59, v96, v97
	v_max3_f32 v58, v58, v95, v59
	v_mov_b32_e32 v59, v58
	s_nop 1
	v_permlane32_swap_b32_e32 v58, v59
	v_max_f32_e32 v58, v58, v59
	v_cmp_lt_f32_e32 vcc, s83, v58
	s_cmp_lg_u64 vcc, 0
	s_cselect_b64 s[60:61], -1, 0
	s_cbranch_vccnz .LBB0_999

;   #define RESC() do{ if(resc){ asm volatile("s_waitcnt lgkmcnt(0)":::"memory"); \
;       _Pragma("unroll") for(int d_=0;d_<2;++d_) _Pragma("unroll") for(int r=0;r<16;++r)o[d_][r]*=wsf[crow(r,hi)]; } }while(0)
;   #define ROT() do{sl_prev=sl_cur;sl_cur=sl_next;sl_next=(sl_next==(NSLOT-1)*SLOTB)?0:sl_next+SLOTB;}while(0)
;   #define ENDW(tt) do{ if((tt)+3<NT){WAIT_BAR(2);} else if((tt)+2<NT){WAIT_BAR(1);} else {WAIT_BAR(0);} }while(0)
; template<int THRL,int L,int NT> __device__ __forceinline__ void attn_unit(long rowbase,int kvh,int qblk,const bf16*Q,const bf16*__restrict__ K,const bf16*__restrict__ V,bf16*O,char*shm,const int tid){
;     ...
;   for(;t+1<NT;t+=2){
;     STEP(pB0,pB1,pA0,pA1,t,(t+3<NT),(t+1<NT),(t+1<NT));       ENDW(t);   RESC(); ROT();
;     STEP(pA0,pA1,pB0,pB1,t+1,(t+4<NT),(t+2<NT),(t+2<NT));     ENDW(t+1); RESC(); ROT();
.LBB0_895:
	ds_read_b64_tr_b16 v[166:167], v209 offset:40960
	ds_read_b64_tr_b16 v[168:169], v209 offset:41472
	v_mfma_f32_32x32x16_bf16 v[114:129], v[58:61], v[142:145], v[34:49]
	v_add_f32_e32 v50, v98, v99
	v_add_f32_e32 v50, v100, v50
	v_add_f32_e32 v50, v101, v50
	v_add_f32_e32 v50, v102, v50
	v_add_f32_e32 v50, v103, v50
	v_cvt_pk_bf16_f32 v158, v98, v99
	v_cvt_pk_bf16_f32 v159, v100, v101
	ds_read_b64_tr_b16 v[162:163], v209 offset:45056
	ds_read_b64_tr_b16 v[164:165], v209 offset:45568
	v_add_f32_e32 v50, v104, v50
	v_add_f32_e32 v50, v105, v50
	v_add_f32_e32 v50, v106, v50
	v_add_f32_e32 v66, v107, v50
	v_mfma_f32_32x32x16_bf16 v[50:65], v[182:185], v[142:145], v[34:49]
	v_cvt_pk_bf16_f32 v160, v102, v103
	v_cvt_pk_bf16_f32 v161, v104, v105
	ds_read_b64_tr_b16 v[102:103], v209 offset:41984
	ds_read_b64_tr_b16 v[104:105], v209 offset:42496
	v_mfma_f32_32x32x16_bf16 v[114:129], v[186:189], v[138:141], v[114:129]
	v_add_f32_e32 v66, v108, v66
	v_add_f32_e32 v66, v109, v66
	v_add_f32_e32 v66, v110, v66
	v_add_f32_e32 v66, v111, v66
	v_cvt_pk_bf16_f32 v154, v106, v107
	v_cvt_pk_bf16_f32 v155, v108, v109
	ds_read_b64_tr_b16 v[98:99], v209 offset:46080
	ds_read_b64_tr_b16 v[100:101], v209 offset:46592
	v_mfma_f32_32x32x16_bf16 v[50:65], v[78:81], v[138:141], v[50:65]
	v_add_f32_e32 v66, v112, v66
	v_add_f32_e32 v66, v113, v66
	v_add_f32_e32 v66, v82, v66
	v_add_f32_e32 v66, v83, v66
	v_cvt_pk_bf16_f32 v156, v110, v111
	v_cvt_pk_bf16_f32 v157, v112, v113
	ds_read_b64_tr_b16 v[78:79], v209 offset:43008
	ds_read_b64_tr_b16 v[80:81], v209 offset:43520
	v_mfma_f32_32x32x16_bf16 v[114:129], v[74:77], v[134:137], v[114:129]
	v_add_f32_e32 v66, v84, v66
	v_add_f32_e32 v66, v85, v66
	v_add_f32_e32 v66, v86, v66
	v_add_f32_e32 v66, v87, v66
	v_cvt_pk_bf16_f32 v150, v82, v83
	v_cvt_pk_bf16_f32 v151, v84, v85
	ds_read_b64_tr_b16 v[74:75], v209 offset:47104
	ds_read_b64_tr_b16 v[76:77], v209 offset:47616
	v_mfma_f32_32x32x16_bf16 v[50:65], v[174:177], v[134:137], v[50:65]
	v_add_f32_e32 v66, v88, v66
	v_add_f32_e32 v66, v89, v66
	v_add_f32_e32 v66, v90, v66
	v_add_f32_e32 v66, v91, v66
	v_cvt_pk_bf16_f32 v152, v86, v87
	v_cvt_pk_bf16_f32 v153, v88, v89
	ds_read_b64_tr_b16 v[70:71], v209 offset:44032
	ds_read_b64_tr_b16 v[72:73], v209 offset:44544
	v_mfma_f32_32x32x16_bf16 v[114:129], v[178:181], v[130:133], v[114:129]
	v_add_f32_e32 v66, v92, v66
	v_add_f32_e32 v66, v93, v66
	v_add_f32_e32 v66, v94, v66
	v_add_f32_e32 v82, v95, v66
	v_cvt_pk_bf16_f32 v146, v90, v91
	v_cvt_pk_bf16_f32 v147, v92, v93
	ds_read_b64_tr_b16 v[66:67], v209 offset:48128
	ds_read_b64_tr_b16 v[68:69], v209 offset:48640
	v_mfma_f32_32x32x16_bf16 v[50:65], v[170:173], v[130:133], v[50:65]
	v_add_f32_e32 v82, v96, v82
	v_add_f32_e32 v82, v97, v82
	v_add_f32_e32 v82, 0, v82
	v_cvt_pk_bf16_f32 v148, v94, v95
	v_cvt_pk_bf16_f32 v149, v96, v97
	s_cmp_lg_u32 0, -1
	s_cselect_b32 s15, 0, 0
	v_add_f32_e32 v182, v197, v82
	v_lshl_add_u64 v[82:83], v[194:195], 0, s[40:41]
	s_add_i32 s15, s15, s69
	s_add_i32 s15, s15, 0x8000
	s_mov_b32 m0, s15
	s_nop 0
	global_load_lds_dwordx4 v[82:83], off
	v_max_f32_e32 v82, v114, v115
	v_max3_f32 v83, v116, v117, v51
	v_max3_f32 v82, v82, v50, v52
	v_max3_f32 v82, v82, v53, v118
	v_max3_f32 v83, v83, v120, v121
	v_max3_f32 v82, v82, v119, v54
	v_max3_f32 v83, v83, v56, v57
	v_max3_f32 v82, v82, v55, v122
	v_max3_f32 v83, v83, v124, v125
	v_max3_f32 v82, v82, v123, v58
	v_max3_f32 v83, v83, v60, v61
	v_max3_f32 v82, v82, v59, v126
	v_max3_f32 v83, v83, v128, v129
	v_max3_f32 v82, v82, v127, v62
	v_max3_f32 v83, v83, v64, v65
	v_max3_f32 v82, v82, v63, v83
	v_mov_b32_e32 v83, v82
	s_nop 1
	v_permlane32_swap_b32_e32 v82, v83
	v_max_f32_e32 v82, v82, v83
	v_cmp_lt_f32_e32 vcc, s83, v82
	s_cmp_lg_u64 vcc, 0
	s_cselect_b64 s[60:61], -1, 0
	s_cbranch_vccnz .LBB0_1002

;   #define RESC() do{ if(resc){ asm volatile("s_waitcnt lgkmcnt(0)":::"memory"); \
;       _Pragma("unroll") for(int d_=0;d_<2;++d_) _Pragma("unroll") for(int r=0;r<16;++r)o[d_][r]*=wsf[crow(r,hi)]; } }while(0)
;   #define ROT() do{sl_prev=sl_cur;sl_cur=sl_next;sl_next=(sl_next==(NSLOT-1)*SLOTB)?0:sl_next+SLOTB;}while(0)
;   #define ENDW(tt) do{ if((tt)+3<NT){WAIT_BAR(2);} else if((tt)+2<NT){WAIT_BAR(1);} else {WAIT_BAR(0);} }while(0)
; template<int THRL,int L,int NT> __device__ __forceinline__ void attn_unit(long rowbase,int kvh,int qblk,const bf16*Q,const bf16*__restrict__ K,const bf16*__restrict__ V,bf16*O,char*shm,const int tid){
;     ...
;   for(;t+1<NT;t+=2){
;     STEP(pB0,pB1,pA0,pA1,t,(t+3<NT),(t+1<NT),(t+1<NT));       ENDW(t);   RESC(); ROT();
;     STEP(pA0,pA1,pB0,pB1,t+1,(t+4<NT),(t+2<NT),(t+2<NT));     ENDW(t+1); RESC(); ROT();
.LBB0_898:
	ds_read_b64_tr_b16 v[162:163], v209 offset:24576
	ds_read_b64_tr_b16 v[164:165], v209 offset:25088
	v_mfma_f32_32x32x16_bf16 v[82:97], v[110:113], v[142:145], v[34:49]
	v_add_f32_e32 v66, v114, v115
	v_add_f32_e32 v66, v116, v66
	v_add_f32_e32 v66, v117, v66
	v_add_f32_e32 v66, v118, v66
	v_add_f32_e32 v66, v119, v66
	v_cvt_pk_bf16_f32 v158, v114, v115
	v_cvt_pk_bf16_f32 v159, v116, v117
	ds_read_b64_tr_b16 v[114:115], v209 offset:28672
	ds_read_b64_tr_b16 v[116:117], v209 offset:29184
	v_add_f32_e32 v66, v120, v66
	v_add_f32_e32 v66, v121, v66
	v_add_f32_e32 v66, v122, v66
	v_add_f32_e32 v146, v123, v66
	v_mfma_f32_32x32x16_bf16 v[66:81], v[106:109], v[142:145], v[34:49]
	v_cvt_pk_bf16_f32 v160, v118, v119
	v_cvt_pk_bf16_f32 v161, v120, v121
	ds_read_b64_tr_b16 v[110:111], v209 offset:25600
	ds_read_b64_tr_b16 v[112:113], v209 offset:26112
	v_mfma_f32_32x32x16_bf16 v[82:97], v[178:181], v[138:141], v[82:97]
	v_add_f32_e32 v106, v124, v146
	v_add_f32_e32 v106, v125, v106
	v_add_f32_e32 v106, v126, v106
	v_add_f32_e32 v118, v127, v106
	v_cvt_pk_bf16_f32 v154, v122, v123
	v_cvt_pk_bf16_f32 v155, v124, v125
	ds_read_b64_tr_b16 v[106:107], v209 offset:29696
	ds_read_b64_tr_b16 v[108:109], v209 offset:30208
	v_mfma_f32_32x32x16_bf16 v[66:81], v[102:105], v[138:141], v[66:81]
	v_add_f32_e32 v118, v128, v118
	v_add_f32_e32 v118, v129, v118
	v_add_f32_e32 v118, v50, v118
	v_add_f32_e32 v118, v51, v118
	v_cvt_pk_bf16_f32 v156, v126, v127
	v_cvt_pk_bf16_f32 v157, v128, v129
	ds_read_b64_tr_b16 v[102:103], v209 offset:26624
	ds_read_b64_tr_b16 v[104:105], v209 offset:27136
	v_mfma_f32_32x32x16_bf16 v[82:97], v[98:101], v[134:137], v[82:97]
	v_add_f32_e32 v118, v52, v118
	v_add_f32_e32 v118, v53, v118
	v_add_f32_e32 v118, v54, v118
	v_add_f32_e32 v118, v55, v118
	v_cvt_pk_bf16_f32 v150, v50, v51
	v_cvt_pk_bf16_f32 v151, v52, v53
	ds_read_b64_tr_b16 v[98:99], v209 offset:30720
	ds_read_b64_tr_b16 v[100:101], v209 offset:31232
	v_mfma_f32_32x32x16_bf16 v[66:81], v[170:173], v[134:137], v[66:81]
	v_add_f32_e32 v50, v56, v118
	v_add_f32_e32 v50, v57, v50
	v_add_f32_e32 v50, v58, v50
	v_add_f32_e32 v50, v59, v50
	v_cvt_pk_bf16_f32 v152, v54, v55
	v_cvt_pk_bf16_f32 v153, v56, v57
	ds_read_b64_tr_b16 v[54:55], v209 offset:27648
	ds_read_b64_tr_b16 v[56:57], v209 offset:28160
	v_mfma_f32_32x32x16_bf16 v[82:97], v[174:177], v[130:133], v[82:97]
	v_add_f32_e32 v50, v60, v50
	v_add_f32_e32 v50, v61, v50
	v_add_f32_e32 v50, v62, v50
	v_add_f32_e32 v118, v63, v50
	v_cvt_pk_bf16_f32 v146, v58, v59
	v_cvt_pk_bf16_f32 v147, v60, v61
	ds_read_b64_tr_b16 v[50:51], v209 offset:31744
	ds_read_b64_tr_b16 v[52:53], v209 offset:32256
	v_mfma_f32_32x32x16_bf16 v[66:81], v[166:169], v[130:133], v[66:81]
	v_add_f32_e32 v58, v64, v118
	v_add_f32_e32 v58, v65, v58
	v_add_f32_e32 v58, 0, v58
	v_cvt_pk_bf16_f32 v148, v62, v63
	v_cvt_pk_bf16_f32 v149, v64, v65
	s_cmp_lg_u32 0, -1
	s_cselect_b32 s15, 0, 0
	v_add_f32_e32 v118, v182, v58
	v_lshl_add_u64 v[58:59], v[194:195], 0, s[36:37]
	s_add_i32 s15, s15, s69
	s_add_i32 s15, s15, 0xa000
	s_mov_b32 m0, s15
	s_nop 0
	global_load_lds_dwordx4 v[58:59], off
	v_max_f32_e32 v58, v82, v83
	v_max3_f32 v59, v84, v85, v67
	v_max3_f32 v58, v58, v66, v68
	v_max3_f32 v58, v58, v69, v86
	v_max3_f32 v59, v59, v88, v89
	v_max3_f32 v58, v58, v87, v70
	v_max3_f32 v59, v59, v72, v73
	v_max3_f32 v58, v58, v71, v90
	v_max3_f32 v59, v59, v92, v93
	v_max3_f32 v58, v58, v91, v74
	v_max3_f32 v59, v59, v76, v77
	v_max3_f32 v58, v58, v75, v94
	v_max3_f32 v59, v59, v96, v97
	v_max3_f32 v58, v58, v95, v78
	v_max3_f32 v59, v59, v80, v81
	v_max3_f32 v58, v58, v79, v59
	v_mov_b32_e32 v59, v58
	s_nop 1
	v_permlane32_swap_b32_e32 v58, v59
	v_max_f32_e32 v58, v58, v59
	v_cmp_lt_f32_e32 vcc, s83, v58
	s_cmp_lg_u64 vcc, 0
	s_cselect_b64 s[60:61], -1, 0
	s_cbranch_vccnz .LBB0_1005

;   #define RESC() do{ if(resc){ asm volatile("s_waitcnt lgkmcnt(0)":::"memory"); \
;       _Pragma("unroll") for(int d_=0;d_<2;++d_) _Pragma("unroll") for(int r=0;r<16;++r)o[d_][r]*=wsf[crow(r,hi)]; } }while(0)
; __device__ __forceinline__ void kmask(f32x16&p0,f32x16&p1,int rem,int hi){
;   const float NEG=-INFINITY;
;   #pragma unroll
;   for(int r=0;r<16;++r){int kv=4*hi+(r&3)+8*(r>>2); if(kv>=rem)p0[r]=NEG; if(kv+32>=rem)p1[r]=NEG;}
; }
; template<int THRL,int L,int NT> __device__ __forceinline__ void attn_unit(long rowbase,int kvh,int qblk,const bf16*Q,const bf16*__restrict__ K,const bf16*__restrict__ V,bf16*O,char*shm,const int tid){
;     ...
;   if constexpr((NT&1)==0){
;     STEP(pB0,pB1,pA0,pA1,NT-1,false,false,false); RESC();
.LBB0_901:
	ds_read_b64_tr_b16 v[62:63], v209 offset:32768
	ds_read_b64_tr_b16 v[64:65], v209 offset:33280
	v_mfma_f32_32x32x16_bf16 v[34:49], v[114:117], v[142:145], v[34:49]
	v_add_f32_e32 v50, v82, v83
	v_add_f32_e32 v50, v84, v50
	v_add_f32_e32 v50, v85, v50
	v_add_f32_e32 v50, v86, v50
	v_add_f32_e32 v50, v87, v50
	v_cvt_pk_bf16_f32 v158, v82, v83
	v_cvt_pk_bf16_f32 v159, v84, v85
	ds_read_b64_tr_b16 v[102:103], v209 offset:36864
	ds_read_b64_tr_b16 v[104:105], v209 offset:37376
	v_add_f32_e32 v50, v88, v50
	v_add_f32_e32 v50, v89, v50
	v_add_f32_e32 v50, v90, v50
	v_add_f32_e32 v50, v91, v50
	v_cvt_pk_bf16_f32 v160, v86, v87
	v_cvt_pk_bf16_f32 v161, v88, v89
	ds_read_b64_tr_b16 v[98:99], v209 offset:33792
	ds_read_b64_tr_b16 v[100:101], v209 offset:34304
	v_mfma_f32_32x32x16_bf16 v[34:49], v[110:113], v[138:141], v[34:49]
	v_add_f32_e32 v50, v92, v50
	v_add_f32_e32 v50, v93, v50
	v_add_f32_e32 v50, v94, v50
	v_add_f32_e32 v50, v95, v50
	v_cvt_pk_bf16_f32 v154, v90, v91
	v_cvt_pk_bf16_f32 v155, v92, v93
	ds_read_b64_tr_b16 v[90:91], v209 offset:37888
	ds_read_b64_tr_b16 v[92:93], v209 offset:38400
	v_add_f32_e32 v50, v96, v50
	v_add_f32_e32 v50, v97, v50
	v_add_f32_e32 v50, v66, v50
	v_add_f32_e32 v50, v67, v50
	v_cvt_pk_bf16_f32 v156, v94, v95
	v_cvt_pk_bf16_f32 v157, v96, v97
	ds_read_b64_tr_b16 v[86:87], v209 offset:34816
	ds_read_b64_tr_b16 v[88:89], v209 offset:35328
	v_mfma_f32_32x32x16_bf16 v[34:49], v[106:109], v[134:137], v[34:49]
	v_add_f32_e32 v50, v68, v50
	v_add_f32_e32 v50, v69, v50
	v_add_f32_e32 v50, v70, v50
	v_add_f32_e32 v50, v71, v50
	v_cvt_pk_bf16_f32 v150, v66, v67
	v_cvt_pk_bf16_f32 v151, v68, v69
	ds_read_b64_tr_b16 v[82:83], v209 offset:38912
	ds_read_b64_tr_b16 v[84:85], v209 offset:39424
	v_add_f32_e32 v50, v72, v50
	v_add_f32_e32 v50, v73, v50
	v_add_f32_e32 v50, v74, v50
	v_add_f32_e32 v50, v75, v50
	v_cvt_pk_bf16_f32 v152, v70, v71
	v_cvt_pk_bf16_f32 v153, v72, v73
	ds_read_b64_tr_b16 v[70:71], v209 offset:35840
	ds_read_b64_tr_b16 v[72:73], v209 offset:36352
	v_mfma_f32_32x32x16_bf16 v[34:49], v[58:61], v[130:133], v[34:49]
	v_add_f32_e32 v50, v76, v50
	v_add_f32_e32 v50, v77, v50
	v_add_f32_e32 v50, v78, v50
	v_add_f32_e32 v50, v79, v50
	v_cvt_pk_bf16_f32 v146, v74, v75
	v_cvt_pk_bf16_f32 v147, v76, v77
	ds_read_b64_tr_b16 v[66:67], v209 offset:39936
	ds_read_b64_tr_b16 v[68:69], v209 offset:40448
	s_nop 3
	v_add_f32_e32 v42, v80, v50
	v_add_f32_e32 v42, v81, v42
	v_add_f32_e32 v42, 0, v42
	v_cvt_pk_bf16_f32 v148, v78, v79
	v_cvt_pk_bf16_f32 v149, v80, v81
	v_max_f32_e32 v44, v37, v37
	v_max_f32_e32 v45, v36, v36
	v_add_f32_e32 v74, v118, v42
	v_mov_b32_e32 v42, 0xff800000
	v_max_f32_e32 v44, v45, v44
	v_max3_f32 v43, v34, v35, v42
	v_max3_f32 v44, v44, v42, v40
	v_max3_f32 v43, v43, v38, v39
	v_max3_f32 v44, v44, v41, v42
	v_max3_f32 v43, v43, v42, v44
	v_mov_b32_e32 v44, v43
	s_nop 1
	v_permlane32_swap_b32_e32 v43, v44
	v_max_f32_e32 v43, v43, v44
	v_cmp_lt_f32_e32 vcc, s83, v43
	s_cmp_lg_u64 vcc, 0
	s_cselect_b64 s[60:61], -1, 0
	s_cbranch_vccnz .LBB0_1008

; #define WAIT_BAR(N) asm volatile("s_waitcnt vmcnt(" #N ") lgkmcnt(0)\n\ts_barrier":::"memory")
;   #define DMA_K(t,slot) glds16(ksrc+(long)(t)*KVBLK*KP,(unsigned)__builtin_amdgcn_readfirstlane(kdst+(slot)))
;   #define CMASK(P0,P1,t) do{ if((t)>=NT-2)kmask(P0,P1,L-64*(t),hi);}while(0)
; template<int THRL,int L,int NT> __device__ __forceinline__ void attn_unit(long rowbase,int kvh,int qblk,const bf16*Q,const bf16*__restrict__ K,const bf16*__restrict__ V,bf16*O,char*shm,const int tid){
;   const int lane=tid&63,r32=lane&31,hi=lane>>5; const int wid=__builtin_amdgcn_readfirstlane(tid>>6);
;   const int q0=qblk*64, qh=wid>>1, rh=wid&1;
;   const bf16*Qw=Q+(rowbase+q0+rh*QBLK)*QP+(4*kvh+qh)*D;
;   const bf16*Kh=K+rowbase*KP+kvh*D,*Vh=V+rowbase*KP+kvh*D;
;   const unsigned lds0=(unsigned)(uintptr_t)shm;
;   float*wsf=(float*)(shm+LDS_WS)+wid*64;
;   const bf16*ksrc=Kh+(long)lane*KP+wid*8;
;   const bf16*vsrc=Vh+(long)(16*(wid&3)+(lane>>2))*KP+(wid>>2)*32+(lane&3)*8;
;   const unsigned kdst=lds0+LDS_K+wid*1024, vdst=lds0+LDS_V+wid*1024;
;     ...
;   const int vb0=(int)(lds0+LDS_V)+((lane>>4)&1)*32+(lane&3)*8+(4*hi+((lane&15)>>2))*64;
;   const char*Kbase=shm+LDS_K; bf16x8 kf[8];
;   const lds_cptr shm3=(lds_cptr)shm; const lds_cptr kp0=shm3+LDS_K+hi*1024+r32*16; const lds_cptr vp0=shm3+LDS_V+((lane>>4)&1)*32+(lane&3)*8+(4*hi+((lane&15)>>2))*64;
;   DMA_K(0,0);DMA_V(0,0);DMA_K(1,SLOTB);
;   bf16x8 qr[4];
;   #pragma unroll
;   for(int d0=0;d0<4;++d0)qr[d0]=*reinterpret_cast<const bf16x8*>(&Qw[(long)r32*QP+d0*16+hi*8]);
;   if(q0+rh*QBLK+r32>=L){
;     #pragma unroll
;     for(int d0=0;d0<4;++d0)qr[d0]=bf16x8{0,0,0,0,0,0,0,0}; }
;   float mhat=0.f,l_reg=0.f;f32x16 o[2];o[0]=f32x16{};o[1]=f32x16{};f32x16 negm=f32x16{};asm volatile("":"+v"(negm));
;     ...
;   bool resc=false;
;     ...
;   f32x16 pA0,pA1,pB0,pB1;
;   int sl_prev=0,sl_cur=0,sl_next=SLOTB;
;     ...
;   DMA_K(2,2*SLOTB);
;   WAIT_BAR(3);
;   qkt(pA0,pA1,Kbase,qr,negm,r32,hi);asm volatile("s_nop 15\n\ts_nop 7":"+v"(pA0),"+v"(pA1));CMASK(pA0,pA1,0);
; __device__ __forceinline__ void attention_phase(const PT a, unsigned char* ws, int l, unsigned char* lds_generic, int tid, bool dry = false) {
;     ...
;         if (u < ATT_UNITS_P) { const int s = u / 260, rem = u - s * 260, kvh = rem / 65, qblk = rem - kvh * 65;
;             attn_body::attn_unit<8, LP, 65>((long)s * LP, kvh, qblk, Q, K, V, O, (char*)lds_generic, tidu); }
.LBB0_915:
	s_and_b64 vcc, exec, s[4:5]
	s_cbranch_vccz .LBB0_956
	s_mul_hi_i32 s4, s66, 0x7e07e07f
	s_lshr_b32 s5, s4, 31
	s_ashr_i32 s4, s4, 7
	s_add_i32 s97, s4, s5
	s_mul_i32 s4, s97, 0xfffffefc
	s_add_i32 s4, s4, s66
	s_mul_hi_i32 s5, s4, 0x7e07e07f
	s_lshr_b32 s15, s5, 31
	s_ashr_i32 s5, s5, 5
	s_add_i32 s18, s5, s15
	s_mul_i32 s5, s18, 0xffffffbf
	s_add_i32 s5, s5, s4
	v_readfirstlane_b32 s15, v204
	s_lshl_b32 s66, s5, 6
	s_mul_i32 s19, s97, 0x1010
	s_ashr_i32 s67, s15, 6
	s_ashr_i32 s5, s66, 31
	s_mul_hi_i32 s4, s97, 0x1010
	s_add_u32 s19, s19, s66
	s_addc_u32 s5, s4, s5
	s_lshl_b32 s4, s67, 5
	s_and_b32 s92, s4, 32
	s_add_u32 s4, s19, s92
	s_addc_u32 s5, s5, 0
	s_lshl_b64 s[4:5], s[4:5], 11
	s_add_u32 s19, s6, s4
	s_addc_u32 s59, s71, s5
	s_ashr_i32 s5, s15, 1
	s_lshl_b32 s4, s18, 8
	s_andn2_b32 s5, s5, 63
	s_add_i32 s4, s5, s4
	s_ashr_i32 s5, s4, 31
	s_lshl_b64 s[4:5], s[4:5], 1
	s_add_u32 s58, s19, s4
	s_addc_u32 s59, s59, s5
	s_mul_hi_i32 s96, s97, 0x202000
	s_mul_i32 s97, s97, 0x202000
	s_add_u32 s19, s72, s97
	s_addc_u32 s62, s73, s96
	s_lshl_b32 s4, s18, 6
	s_ashr_i32 s5, s4, 31
	s_lshl_b64 s[60:61], s[4:5], 1
	s_add_u32 s4, s19, s60
	s_addc_u32 s5, s62, s61
	s_add_u32 s18, s74, s97
	s_addc_u32 s19, s75, s96
	s_add_u32 s18, s18, s60
	s_addc_u32 s19, s19, s61
	s_lshl_b32 s62, s67, 3
	v_lshl_add_u64 v[2:3], s[4:5], 0, v[192:193]
	s_ashr_i32 s63, s62, 31
	s_lshl_b32 s4, s67, 4
	v_lshl_add_u64 v[186:187], s[62:63], 1, v[2:3]
	v_and_or_b32 v2, s4, 48, v203
	s_ashr_i32 s4, s15, 3
	s_and_b32 s64, s4, 0xffffffe0
	s_ashr_i32 s65, s64, 31
	s_lshl_b32 s68, s67, 10
	v_lshlrev_b32_e32 v2, 9, v2
	v_mov_b32_e32 v3, v193
	s_cmp_lg_u32 0, -1
	v_lshl_add_u64 v[2:3], s[18:19], 0, v[2:3]
	s_cselect_b32 s4, 0, 0
	v_lshl_add_u64 v[2:3], s[64:65], 1, v[2:3]
	v_lshlrev_b32_e32 v4, 1, v202
	v_mov_b32_e32 v5, v193
	s_add_i32 s93, s68, s4
	s_mov_b32 m0, s93
	s_nop 0
	global_load_lds_dwordx4 v[186:187], off
	v_lshl_add_u64 v[194:195], v[2:3], 0, v[4:5]
	s_add_i32 s69, s93, 0x6000
	s_mov_b32 m0, s69
	s_nop 0
	global_load_lds_dwordx4 v[194:195], off
	v_lshl_add_u64 v[2:3], v[186:187], 0, s[26:27]
	s_add_i32 s4, s93, 0x2000
	s_mov_b32 m0, s4
	s_nop 0
	global_load_lds_dwordx4 v[2:3], off
	v_lshl_or_b32 v2, v201, 4, v205
	global_load_dwordx4 v[142:145], v2, s[58:59]
	global_load_dwordx4 v[138:141], v2, s[58:59] offset:32
	global_load_dwordx4 v[134:137], v2, s[58:59] offset:64
	global_load_dwordx4 v[130:133], v2, s[58:59] offset:96
	s_or_b32 s66, s92, s66
	v_or_b32_e32 v2, s66, v200
	v_cmp_lt_i32_e32 vcc, s85, v2
	s_and_saveexec_b64 s[4:5], vcc
	s_cbranch_execz .LBB0_918
	s_waitcnt vmcnt(3)
	v_mov_b32_e32 v142, 0
	v_mov_b32_e32 v143, v142
	v_mov_b32_e32 v144, v142
	v_mov_b32_e32 v145, v142
	s_waitcnt vmcnt(2)
	v_mov_b32_e32 v138, v142
	v_mov_b32_e32 v139, v142
	v_mov_b32_e32 v140, v142
	v_mov_b32_e32 v141, v142
	s_waitcnt vmcnt(1)
	v_mov_b32_e32 v134, v142
	v_mov_b32_e32 v135, v142
	v_mov_b32_e32 v136, v142
	v_mov_b32_e32 v137, v142
	s_waitcnt vmcnt(0)
	v_mov_b32_e32 v130, v142
	v_mov_b32_e32 v131, v142
	v_mov_b32_e32 v132, v142
	v_mov_b32_e32 v133, v142
.LBB0_918:
	s_or_b64 exec, exec, s[4:5]
	s_and_b32 s4, s15, 0x3fffffc0
	s_lshl_b32 s4, s4, 2
	s_add_i32 s92, s4, 0
	s_cmp_lg_u32 0, -1
	s_cselect_b32 s4, 0, 0
	v_lshlrev_b32_e32 v2, 10, v201
	v_lshlrev_b32_e32 v3, 4, v200
	v_mov_b32_e32 v18, v193
	v_mov_b32_e32 v19, v193
	v_mov_b32_e32 v20, v193
	v_mov_b32_e32 v21, v193
	v_mov_b32_e32 v22, v193
	v_mov_b32_e32 v23, v193
	v_mov_b32_e32 v24, v193
	v_mov_b32_e32 v25, v193
	v_mov_b32_e32 v26, v193
	v_mov_b32_e32 v27, v193
	v_mov_b32_e32 v28, v193
	v_mov_b32_e32 v29, v193
	v_mov_b32_e32 v30, v193
	v_mov_b32_e32 v31, v193
	v_mov_b32_e32 v32, v193
	v_mov_b32_e32 v33, v193
	s_add_i32 s4, s4, s68
	v_add3_u32 v210, 0, v2, v3
	v_lshl_add_u64 v[2:3], v[186:187], 0, s[28:29]
	s_add_i32 s5, s4, 0x4000
	s_mov_b32 m0, s5
	s_nop 0
	global_load_lds_dwordx4 v[2:3], off
	s_waitcnt vmcnt(3) lgkmcnt(0)
	s_barrier
	ds_read_b128 v[2:5], v210
	ds_read_b128 v[6:9], v210 offset:512
	s_waitcnt vmcnt(3) lgkmcnt(1)
	v_mfma_f32_32x32x16_bf16 v[34:49], v[2:5], v[142:145], v[18:33]
	s_add_i32 s4, s4, 0x8000
	s_lshl_b64 s[64:65], s[64:65], 1
	s_add_u32 s19, s64, s60
	s_addc_u32 s65, s65, s61
	s_add_u32 s64, s19, s97
	s_addc_u32 s65, s65, s96
	s_lshl_b32 s15, s15, 7
	s_waitcnt lgkmcnt(0)
	v_mfma_f32_32x32x16_bf16 v[18:33], v[6:9], v[142:145], v[18:33]
	ds_read_b128 v[2:5], v210 offset:2048
	ds_read_b128 v[6:9], v210 offset:2560
	s_and_b32 s15, s15, 0x6000
	s_lshl_b64 s[62:63], s[62:63], 1
	s_mov_b32 s18, 0
	s_mov_b32 s94, -1
	s_movk_i32 s95, 0x4000
	v_lshl_add_u32 v207, v200, 2, s92
	s_waitcnt vmcnt(2) lgkmcnt(1)
	v_mfma_f32_32x32x16_bf16 v[34:49], v[2:5], v[138:141], v[34:49]
	ds_read_b128 v[10:13], v210 offset:4608
	ds_read_b128 v[2:5], v210 offset:4096
	ds_read_b128 v[50:53], v210 offset:6656
	ds_read_b128 v[14:17], v210 offset:6144
	v_lshlrev_b32_e32 v211, 4, v201
	v_mov_b32_e32 v182, 0
	s_waitcnt lgkmcnt(4)
	v_mfma_f32_32x32x16_bf16 v[18:33], v[6:9], v[138:141], v[18:33]
	v_lshlrev_b32_e32 v6, 1, v204
	v_and_b32_e32 v205, 32, v6
	v_lshlrev_b32_e32 v6, 4, v204
	v_and_b32_e32 v6, 0xc0, v6
	v_lshl_or_b32 v206, v201, 8, v6
	v_add_u32_e32 v6, 0, v205
	v_add3_u32 v208, v6, v202, v206
	s_waitcnt vmcnt(1) lgkmcnt(2)
	v_mfma_f32_32x32x16_bf16 v[34:49], v[2:5], v[134:137], v[34:49]
	v_mov_b32_e32 v2, v193
	v_mov_b32_e32 v3, v193
	v_mov_b32_e32 v4, v193
	v_mov_b32_e32 v5, v193
	v_mov_b32_e32 v6, v193
	v_mov_b32_e32 v7, v193
	v_mov_b32_e32 v8, v193
	v_mfma_f32_32x32x16_bf16 v[18:33], v[10:13], v[134:137], v[18:33]
	v_mov_b32_e32 v9, v193
	v_mov_b32_e32 v10, v193
	v_mov_b32_e32 v11, v193
	v_mov_b32_e32 v12, v193
	v_mov_b32_e32 v13, v193
	s_waitcnt vmcnt(0) lgkmcnt(0)
; #define WAIT_BAR(N) asm volatile("s_waitcnt vmcnt(" #N ") lgkmcnt(0)\n\ts_barrier":::"memory")
;   #define DMA_K(t,slot) glds16(ksrc+(long)(t)*KVBLK*KP,(unsigned)__builtin_amdgcn_readfirstlane(kdst+(slot)))
;   #define DMA_V(t,slot) glds16(vsrc+(long)(t)*KVBLK*KP,(unsigned)__builtin_amdgcn_readfirstlane(vdst+(slot)))
;   #define CMASK(P0,P1,t) do{ if((t)>=NT-2)kmask(P0,P1,L-64*(t),hi);}while(0)
;   #define START(P0,P1) do{ const float rm=rowmax(P0,P1); resc=false; \
;     { const float dl=rm; mhat=fadd_s(mhat,dl); \
;       _Pragma("unroll") for(int r=0;r<16;++r){P0[r]=fsub_s(P0[r],dl);P1[r]=fsub_s(P1[r],dl);} \
;       _Pragma("unroll") for(int r=0;r<16;++r)negm[r]=-mhat; asm volatile("":"+v"(negm)); } \
;     _Pragma("unroll") for(int r=0;r<16;++r)P0[r]=__builtin_amdgcn_exp2f(P0[r]); }while(0)
;   #define ROT() do{sl_prev=sl_cur;sl_cur=sl_next;sl_next=(sl_next==(NSLOT-1)*SLOTB)?0:sl_next+SLOTB;}while(0)
;   #define CMASK(P0,P1,t) do{}while(0)
;   #define CMASK(P0,P1,t) do{ if((t)>=NT-2)kmask(P0,P1,L-64*(t),hi);}while(0)
; template<int THRL,int L,int NT> __device__ __forceinline__ void attn_unit(long rowbase,int kvh,int qblk,const bf16*Q,const bf16*__restrict__ K,const bf16*__restrict__ V,bf16*O,char*shm,const int tid){
;     ...
;   qkt(pA0,pA1,Kbase,qr,negm,r32,hi);asm volatile("s_nop 15\n\ts_nop 7":"+v"(pA0),"+v"(pA1));CMASK(pA0,pA1,0);
;   START(pA0,pA1);
;   _Pragma("unroll") for(int r=0;r<16;++r)pA1[r]=__builtin_amdgcn_exp2f(pA1[r]);
;   WAIT_BAR(0);
;   DMA_K(3,0);DMA_V(1,SLOTB);
;   ROT();
;   kload8(kf,kp0+sl_cur);
;   WAIT_BAR(2);
	v_mfma_f32_32x32x16_bf16 v[34:49], v[14:17], v[130:133], v[34:49]
	v_mov_b32_e32 v16, v193
	v_mov_b32_e32 v17, v193
	v_mov_b32_e32 v14, v193
	v_mov_b32_e32 v15, v193
	v_mfma_f32_32x32x16_bf16 v[18:33], v[50:53], v[130:133], v[18:33]
	s_nop 15
	s_nop 7
	s_nop 0
	v_max3_f32 v50, v34, v35, v18
	v_max3_f32 v51, v36, v37, v19
	s_nop 0
	v_max3_f32 v50, v50, v20, v21
	v_max3_f32 v51, v51, v40, v41
	s_nop 0
	v_max3_f32 v50, v50, v38, v39
	v_max3_f32 v51, v51, v24, v25
	s_nop 0
	v_max3_f32 v50, v50, v22, v23
	v_max3_f32 v51, v51, v44, v45
	s_nop 0
	v_max3_f32 v50, v50, v42, v43
	v_max3_f32 v51, v51, v28, v29
	s_nop 0
	v_max3_f32 v50, v50, v26, v27
	v_max3_f32 v51, v51, v48, v49
	s_nop 0
	v_max3_f32 v50, v50, v46, v47
	v_max3_f32 v51, v51, v32, v33
	s_nop 0
	v_max3_f32 v50, v50, v30, v31
	s_nop 0
	v_max_f32_e32 v50, v50, v51
	s_nop 0
	v_mov_b32_e32 v51, v50
	s_nop 1
	v_permlane32_swap_b32_e32 v50, v51
	v_max_f32_e32 v50, v50, v51
	s_nop 0
	v_add_f32_e32 v209, v193, v50
	v_sub_f32_e32 v51, v34, v50
	v_sub_f32_e32 v52, v35, v50
	v_sub_f32_e32 v53, v36, v50
	v_sub_f32_e32 v54, v37, v50
	v_sub_f32_e32 v55, v38, v50
	s_nop 0
	v_xor_b32_e32 v34, 0x80000000, v209
	v_sub_f32_e32 v56, v39, v50
	v_sub_f32_e32 v57, v40, v50
	v_sub_f32_e32 v58, v41, v50
	v_sub_f32_e32 v59, v42, v50
	v_sub_f32_e32 v60, v43, v50
	v_sub_f32_e32 v61, v44, v50
	v_sub_f32_e32 v62, v45, v50
	v_sub_f32_e32 v63, v46, v50
	v_sub_f32_e32 v64, v47, v50
	v_sub_f32_e32 v65, v48, v50
	v_sub_f32_e32 v81, v49, v50
	v_mov_b32_e32 v35, v34
	v_mov_b32_e32 v36, v34
	v_mov_b32_e32 v37, v34
	v_mov_b32_e32 v38, v34
	v_mov_b32_e32 v39, v34
	v_mov_b32_e32 v40, v34
	v_mov_b32_e32 v41, v34
	v_mov_b32_e32 v42, v34
	v_mov_b32_e32 v43, v34
	v_mov_b32_e32 v44, v34
	v_mov_b32_e32 v45, v34
	v_mov_b32_e32 v46, v34
	v_mov_b32_e32 v47, v34
	v_mov_b32_e32 v48, v34
	v_mov_b32_e32 v49, v34
	v_sub_f32_e32 v18, v18, v50
	v_sub_f32_e32 v19, v19, v50
	s_waitcnt vmcnt(0) lgkmcnt(0)
	s_barrier
	v_sub_f32_e32 v20, v20, v50
	v_sub_f32_e32 v21, v21, v50
	v_sub_f32_e32 v22, v22, v50
	v_sub_f32_e32 v23, v23, v50
	v_sub_f32_e32 v24, v24, v50
	v_sub_f32_e32 v25, v25, v50
	v_sub_f32_e32 v26, v26, v50
	v_sub_f32_e32 v27, v27, v50
	v_sub_f32_e32 v28, v28, v50
	v_sub_f32_e32 v29, v29, v50
	v_sub_f32_e32 v30, v30, v50
	v_sub_f32_e32 v31, v31, v50
	v_sub_f32_e32 v32, v32, v50
	v_sub_f32_e32 v33, v33, v50
	v_exp_f32_e32 v66, v51
	v_exp_f32_e32 v50, v18
	v_exp_f32_e32 v51, v19
	v_lshl_add_u64 v[18:19], v[186:187], 0, s[30:31]
	s_mov_b32 m0, s93
	s_nop 0
	global_load_lds_dwordx4 v[18:19], off
	v_lshl_add_u64 v[18:19], v[194:195], 0, s[26:27]
	s_mov_b32 m0, s4
	s_nop 0
	global_load_lds_dwordx4 v[18:19], off
	ds_read_b128 v[82:85], v210 offset:8192
	ds_read_b128 v[170:173], v210 offset:8704
	ds_read_b128 v[166:169], v210 offset:10240
	ds_read_b128 v[162:165], v210 offset:10752
	ds_read_b128 v[126:129], v210 offset:12288
	ds_read_b128 v[122:125], v210 offset:12800
	ds_read_b128 v[118:121], v210 offset:14336
	ds_read_b128 v[114:117], v210 offset:14848
	v_exp_f32_e32 v67, v52
	v_exp_f32_e32 v52, v20
	v_lshl_or_b32 v20, v203, 9, s15
	s_add_u32 s15, s78, s62
	v_and_b32_e32 v18, 3, v204
	s_addc_u32 s19, s79, s63
	v_lshlrev_b32_e32 v18, 4, v18
	v_mov_b32_e32 v19, v193
	s_add_u32 s15, s15, s60
	v_exp_f32_e32 v68, v53
	v_exp_f32_e32 v69, v54
	v_exp_f32_e32 v70, v55
	v_exp_f32_e32 v71, v56
	v_exp_f32_e32 v72, v57
	v_exp_f32_e32 v73, v58
	v_exp_f32_e32 v74, v59
	v_exp_f32_e32 v75, v60
	v_exp_f32_e32 v76, v61
	v_exp_f32_e32 v77, v62
	v_exp_f32_e32 v78, v63
	v_exp_f32_e32 v79, v64
	v_exp_f32_e32 v80, v65
	v_exp_f32_e32 v81, v81
	v_exp_f32_e32 v53, v21
	v_exp_f32_e32 v54, v22
	v_exp_f32_e32 v55, v23
	v_exp_f32_e32 v56, v24
	v_exp_f32_e32 v57, v25
	v_exp_f32_e32 v58, v26
	v_exp_f32_e32 v59, v27
	v_exp_f32_e32 v60, v28
	v_exp_f32_e32 v61, v29
	v_exp_f32_e32 v62, v30
	v_exp_f32_e32 v63, v31
	v_exp_f32_e32 v64, v32
	v_exp_f32_e32 v65, v33
	v_lshl_add_u64 v[18:19], s[64:65], 0, v[18:19]
	v_mov_b32_e32 v21, v193
	s_addc_u32 s19, s19, s61
	s_waitcnt vmcnt(2) lgkmcnt(0)
	s_barrier
	v_lshl_add_u64 v[18:19], v[18:19], 0, v[20:21]
	s_add_u32 s60, s15, s97
	v_lshl_add_u64 v[188:189], s[24:25], 0, v[18:19]
	s_addc_u32 s61, s19, s96
	v_mov_b64_e32 v[32:33], v[16:17]
	v_cmp_gt_u32_e64 s[4:5], 32, v198
	v_lshl_add_u64 v[196:197], s[60:61], 0, v[192:193]
	s_movk_i32 s64, 0x2000
	v_mov_b64_e32 v[30:31], v[14:15]
	v_mov_b64_e32 v[28:29], v[12:13]
	v_mov_b64_e32 v[26:27], v[10:11]
	v_mov_b64_e32 v[24:25], v[8:9]
	v_mov_b64_e32 v[22:23], v[6:7]
	v_mov_b64_e32 v[20:21], v[4:5]
	v_mov_b64_e32 v[18:19], v[2:3]
.LBB0_919:
	v_add_u32_e32 v183, s18, v208
	ds_read_b64_tr_b16 v[178:179], v183 offset:24576
	ds_read_b64_tr_b16 v[180:181], v183 offset:25088
	v_mfma_f32_32x32x16_bf16 v[98:113], v[82:85], v[142:145], v[34:49]
	v_add_f32_e32 v86, v66, v67
	v_add_f32_e32 v86, v68, v86
	v_add_f32_e32 v86, v69, v86
	v_add_f32_e32 v86, v70, v86
	v_add_f32_e32 v86, v71, v86
	v_cvt_pk_bf16_f32 v158, v66, v67
	v_cvt_pk_bf16_f32 v159, v68, v69
	ds_read_b64_tr_b16 v[174:175], v183 offset:28672
	ds_read_b64_tr_b16 v[176:177], v183 offset:29184
	v_add_f32_e32 v66, v72, v86
	v_mfma_f32_32x32x16_bf16 v[82:97], v[170:173], v[142:145], v[34:49]
	v_add_f32_e32 v66, v73, v66
	v_add_f32_e32 v66, v74, v66
	v_add_f32_e32 v66, v75, v66
	v_cvt_pk_bf16_f32 v160, v70, v71
	v_cvt_pk_bf16_f32 v161, v72, v73
	ds_read_b64_tr_b16 v[170:171], v183 offset:25600
	ds_read_b64_tr_b16 v[172:173], v183 offset:26112
	v_mfma_f32_32x32x16_bf16 v[98:113], v[166:169], v[138:141], v[98:113]
	v_add_f32_e32 v66, v76, v66
	v_add_f32_e32 v66, v77, v66
	v_add_f32_e32 v66, v78, v66
	v_add_f32_e32 v66, v79, v66
	v_cvt_pk_bf16_f32 v154, v74, v75
	v_cvt_pk_bf16_f32 v155, v76, v77
	ds_read_b64_tr_b16 v[74:75], v183 offset:29696
	ds_read_b64_tr_b16 v[76:77], v183 offset:30208
	v_mfma_f32_32x32x16_bf16 v[82:97], v[162:165], v[138:141], v[82:97]
	v_add_f32_e32 v66, v80, v66
	v_add_f32_e32 v66, v81, v66
	v_add_f32_e32 v66, v50, v66
	v_add_f32_e32 v66, v51, v66
	v_cvt_pk_bf16_f32 v156, v78, v79
	v_cvt_pk_bf16_f32 v157, v80, v81
	ds_read_b64_tr_b16 v[70:71], v183 offset:26624
	ds_read_b64_tr_b16 v[72:73], v183 offset:27136
	v_mfma_f32_32x32x16_bf16 v[98:113], v[126:129], v[134:137], v[98:113]
	v_add_f32_e32 v66, v52, v66
	v_add_f32_e32 v66, v53, v66
	v_add_f32_e32 v66, v54, v66
	v_add_f32_e32 v78, v55, v66
	v_cvt_pk_bf16_f32 v150, v50, v51
	v_cvt_pk_bf16_f32 v151, v52, v53
	ds_read_b64_tr_b16 v[66:67], v183 offset:30720
	ds_read_b64_tr_b16 v[68:69], v183 offset:31232
	v_mfma_f32_32x32x16_bf16 v[82:97], v[122:125], v[134:137], v[82:97]
	v_add_f32_e32 v50, v56, v78
	v_add_f32_e32 v50, v57, v50
	v_add_f32_e32 v50, v58, v50
	v_add_f32_e32 v50, v59, v50
	v_cvt_pk_bf16_f32 v152, v54, v55
	v_cvt_pk_bf16_f32 v153, v56, v57
	ds_read_b64_tr_b16 v[54:55], v183 offset:27648
	ds_read_b64_tr_b16 v[56:57], v183 offset:28160
	v_mfma_f32_32x32x16_bf16 v[98:113], v[118:121], v[130:133], v[98:113]
	v_add_f32_e32 v50, v60, v50
	v_add_f32_e32 v50, v61, v50
	v_add_f32_e32 v50, v62, v50
	v_add_f32_e32 v78, v63, v50
	v_cvt_pk_bf16_f32 v146, v58, v59
	v_cvt_pk_bf16_f32 v147, v60, v61
	ds_read_b64_tr_b16 v[50:51], v183 offset:31744
	ds_read_b64_tr_b16 v[52:53], v183 offset:32256
	v_mfma_f32_32x32x16_bf16 v[82:97], v[114:117], v[130:133], v[82:97]
	v_add_f32_e32 v58, v64, v78
	v_add_f32_e32 v58, v65, v58
	v_add_f32_e32 v60, 0, v58
	v_cvt_pk_bf16_f32 v148, v62, v63
	v_cvt_pk_bf16_f32 v149, v64, v65
	v_lshl_add_u64 v[58:59], v[196:197], 0, s[30:31]
	s_add_i32 s15, s64, s93
	s_mov_b32 m0, s15
	s_nop 0
	global_load_lds_dwordx4 v[58:59], off
	v_lshl_add_u64 v[58:59], v[188:189], 0, s[26:27]
	s_add_i32 s15, s95, s69
	s_mov_b32 m0, s15
	s_nop 0
	global_load_lds_dwordx4 v[58:59], off
	v_max_f32_e32 v58, v98, v99
	v_max3_f32 v59, v100, v101, v83
	v_max3_f32 v58, v58, v82, v84
	v_max3_f32 v58, v58, v85, v102
	v_max3_f32 v59, v59, v104, v105
	v_max3_f32 v58, v58, v103, v86
	v_max3_f32 v59, v59, v88, v89
	v_max3_f32 v58, v58, v87, v106
	v_max3_f32 v59, v59, v108, v109
	v_max3_f32 v58, v58, v107, v90
	v_max3_f32 v59, v59, v92, v93
	v_max3_f32 v58, v58, v91, v110
	v_max3_f32 v59, v59, v112, v113
	v_max3_f32 v58, v58, v111, v94
	v_max3_f32 v59, v59, v96, v97
	v_max3_f32 v58, v58, v95, v59
	v_mov_b32_e32 v59, v58
	s_nop 1
	v_permlane32_swap_b32_e32 v58, v59
	v_max_f32_e32 v58, v58, v59
	v_cmp_lt_f32_e32 vcc, s83, v58
	s_cmp_lg_u64 vcc, 0
	v_add_f32_e32 v192, v182, v60
	s_cselect_b64 s[60:61], -1, 0
	s_cbranch_vccnz .LBB0_927

.LBB0_922:
	s_add_i32 s15, s95, 0x2000
	s_cmpk_lg_i32 s95, 0x4000
	s_cselect_b32 s65, s15, 0
	v_add_u32_e32 v203, s64, v208
	ds_read_b64_tr_b16 v[126:127], v203 offset:24576
	ds_read_b64_tr_b16 v[128:129], v203 offset:25088
	v_mfma_f32_32x32x16_bf16 v[66:81], v[58:61], v[142:145], v[34:49]
	v_add_f32_e32 v50, v98, v99
	v_add_f32_e32 v50, v100, v50
	v_add_f32_e32 v50, v101, v50
	v_add_f32_e32 v50, v102, v50
	v_add_f32_e32 v50, v103, v50
	v_cvt_pk_bf16_f32 v158, v98, v99
	v_cvt_pk_bf16_f32 v159, v100, v101
	ds_read_b64_tr_b16 v[122:123], v203 offset:28672
	ds_read_b64_tr_b16 v[124:125], v203 offset:29184
	v_add_f32_e32 v50, v104, v50
	v_add_f32_e32 v50, v105, v50
	v_add_f32_e32 v50, v106, v50
	v_add_f32_e32 v98, v107, v50
	v_mfma_f32_32x32x16_bf16 v[50:65], v[114:117], v[142:145], v[34:49]
	v_cvt_pk_bf16_f32 v160, v102, v103
	v_cvt_pk_bf16_f32 v161, v104, v105
	ds_read_b64_tr_b16 v[118:119], v203 offset:25600
	ds_read_b64_tr_b16 v[120:121], v203 offset:26112
	v_mfma_f32_32x32x16_bf16 v[66:81], v[182:185], v[138:141], v[66:81]
	v_add_f32_e32 v98, v108, v98
	v_add_f32_e32 v98, v109, v98
	v_add_f32_e32 v98, v110, v98
	v_add_f32_e32 v98, v111, v98
	v_cvt_pk_bf16_f32 v154, v106, v107
	v_cvt_pk_bf16_f32 v155, v108, v109
	ds_read_b64_tr_b16 v[114:115], v203 offset:29696
	ds_read_b64_tr_b16 v[116:117], v203 offset:30208
	v_mfma_f32_32x32x16_bf16 v[50:65], v[174:177], v[138:141], v[50:65]
	v_add_f32_e32 v98, v112, v98
	v_add_f32_e32 v98, v113, v98
	v_add_f32_e32 v98, v82, v98
	v_add_f32_e32 v98, v83, v98
	v_cvt_pk_bf16_f32 v156, v110, v111
	v_cvt_pk_bf16_f32 v157, v112, v113
	ds_read_b64_tr_b16 v[106:107], v203 offset:26624
	ds_read_b64_tr_b16 v[108:109], v203 offset:27136
	v_mfma_f32_32x32x16_bf16 v[66:81], v[178:181], v[134:137], v[66:81]
	v_add_f32_e32 v98, v84, v98
	v_add_f32_e32 v98, v85, v98
	v_add_f32_e32 v98, v86, v98
	v_add_f32_e32 v98, v87, v98
	v_cvt_pk_bf16_f32 v150, v82, v83
	v_cvt_pk_bf16_f32 v151, v84, v85
	ds_read_b64_tr_b16 v[102:103], v203 offset:30720
	ds_read_b64_tr_b16 v[104:105], v203 offset:31232
	v_mfma_f32_32x32x16_bf16 v[50:65], v[166:169], v[134:137], v[50:65]
	v_add_f32_e32 v82, v88, v98
	v_add_f32_e32 v82, v89, v82
	v_add_f32_e32 v82, v90, v82
	v_add_f32_e32 v82, v91, v82
	v_cvt_pk_bf16_f32 v152, v86, v87
	v_cvt_pk_bf16_f32 v153, v88, v89
	ds_read_b64_tr_b16 v[98:99], v203 offset:27648
	ds_read_b64_tr_b16 v[100:101], v203 offset:28160
	v_mfma_f32_32x32x16_bf16 v[66:81], v[170:173], v[130:133], v[66:81]
	v_add_f32_e32 v82, v92, v82
	v_add_f32_e32 v82, v93, v82
	v_add_f32_e32 v82, v94, v82
	v_add_f32_e32 v82, v95, v82
	v_cvt_pk_bf16_f32 v146, v90, v91
	v_cvt_pk_bf16_f32 v147, v92, v93
	ds_read_b64_tr_b16 v[86:87], v203 offset:31744
	ds_read_b64_tr_b16 v[88:89], v203 offset:32256
	v_mfma_f32_32x32x16_bf16 v[50:65], v[162:165], v[130:133], v[50:65]
	v_add_f32_e32 v82, v96, v82
	v_add_f32_e32 v82, v97, v82
	v_add_f32_e32 v84, 0, v82
	v_cvt_pk_bf16_f32 v148, v94, v95
	v_cvt_pk_bf16_f32 v149, v96, v97
	v_lshl_add_u64 v[82:83], v[196:197], 0, s[34:35]
	s_add_i32 s15, s95, s93
	s_mov_b32 m0, s15
	s_nop 0
	global_load_lds_dwordx4 v[82:83], off
	v_max_f32_e32 v82, v66, v67
	s_nop 1
	v_max3_f32 v83, v68, v69, v51
	v_max3_f32 v82, v82, v50, v52
	v_max3_f32 v82, v82, v53, v70
	v_max3_f32 v83, v83, v72, v73
	v_max3_f32 v82, v82, v71, v54
	v_max3_f32 v83, v83, v56, v57
	v_max3_f32 v82, v82, v55, v74
	v_max3_f32 v83, v83, v76, v77
	v_max3_f32 v82, v82, v75, v58
	v_max3_f32 v83, v83, v60, v61
	v_max3_f32 v82, v82, v59, v78
	v_max3_f32 v83, v83, v80, v81
	v_max3_f32 v82, v82, v79, v62
	v_max3_f32 v83, v83, v64, v65
	v_max3_f32 v82, v82, v63, v83
	v_mov_b32_e32 v83, v82
	s_nop 1
	v_permlane32_swap_b32_e32 v82, v83
	v_max_f32_e32 v82, v82, v83
	v_lshl_add_u64 v[188:189], v[188:189], 0, s[28:29]
	s_add_i32 s15, s65, s69
	s_mov_b32 m0, s15
	s_nop 0
	global_load_lds_dwordx4 v[188:189], off
	v_cmp_lt_f32_e32 vcc, s83, v82
	s_cmp_lg_u64 vcc, 0
	v_add_f32_e32 v182, v192, v84
	s_cselect_b64 s[60:61], -1, 0
	s_cbranch_vccnz .LBB0_930

.LBB0_933:
	ds_read_b64_tr_b16 v[178:179], v208 offset:24576
	ds_read_b64_tr_b16 v[180:181], v208 offset:25088
	s_waitcnt lgkmcnt(9)
	v_mfma_f32_32x32x16_bf16 v[98:113], v[82:85], v[142:145], v[34:49]
	v_add_f32_e32 v86, v66, v67
	v_add_f32_e32 v86, v68, v86
	v_add_f32_e32 v86, v69, v86
	v_add_f32_e32 v86, v70, v86
	v_add_f32_e32 v86, v71, v86
	v_cvt_pk_bf16_f32 v158, v66, v67
	v_cvt_pk_bf16_f32 v159, v68, v69
	ds_read_b64_tr_b16 v[174:175], v208 offset:28672
	ds_read_b64_tr_b16 v[176:177], v208 offset:29184
	v_add_f32_e32 v66, v72, v86
	s_waitcnt lgkmcnt(10)
	v_mfma_f32_32x32x16_bf16 v[82:97], v[170:173], v[142:145], v[34:49]
	v_add_f32_e32 v66, v73, v66
	v_add_f32_e32 v66, v74, v66
	v_add_f32_e32 v66, v75, v66
	v_cvt_pk_bf16_f32 v160, v70, v71
	v_cvt_pk_bf16_f32 v161, v72, v73
	ds_read_b64_tr_b16 v[170:171], v208 offset:25600
	ds_read_b64_tr_b16 v[172:173], v208 offset:26112
	s_waitcnt lgkmcnt(11)
	v_mfma_f32_32x32x16_bf16 v[98:113], v[166:169], v[138:141], v[98:113]
	v_add_f32_e32 v66, v76, v66
	v_add_f32_e32 v66, v77, v66
	v_add_f32_e32 v66, v78, v66
	v_add_f32_e32 v66, v79, v66
	v_cvt_pk_bf16_f32 v154, v74, v75
	v_cvt_pk_bf16_f32 v155, v76, v77
	ds_read_b64_tr_b16 v[74:75], v208 offset:29696
	ds_read_b64_tr_b16 v[76:77], v208 offset:30208
	s_waitcnt lgkmcnt(12)
	v_mfma_f32_32x32x16_bf16 v[82:97], v[162:165], v[138:141], v[82:97]
	v_add_f32_e32 v66, v80, v66
	v_add_f32_e32 v66, v81, v66
	v_add_f32_e32 v66, v50, v66
	v_add_f32_e32 v66, v51, v66
	v_cvt_pk_bf16_f32 v156, v78, v79
	v_cvt_pk_bf16_f32 v157, v80, v81
	ds_read_b64_tr_b16 v[70:71], v208 offset:26624
	ds_read_b64_tr_b16 v[72:73], v208 offset:27136
	s_waitcnt lgkmcnt(13)
	v_mfma_f32_32x32x16_bf16 v[98:113], v[126:129], v[134:137], v[98:113]
	v_add_f32_e32 v66, v52, v66
	v_add_f32_e32 v66, v53, v66
	v_add_f32_e32 v66, v54, v66
	v_add_f32_e32 v78, v55, v66
	v_cvt_pk_bf16_f32 v150, v50, v51
	v_cvt_pk_bf16_f32 v151, v52, v53
	ds_read_b64_tr_b16 v[66:67], v208 offset:30720
	ds_read_b64_tr_b16 v[68:69], v208 offset:31232
	s_waitcnt lgkmcnt(14)
	v_mfma_f32_32x32x16_bf16 v[82:97], v[122:125], v[134:137], v[82:97]
	v_add_f32_e32 v50, v56, v78
	v_add_f32_e32 v50, v57, v50
	v_add_f32_e32 v50, v58, v50
	v_add_f32_e32 v50, v59, v50
	v_cvt_pk_bf16_f32 v152, v54, v55
	v_cvt_pk_bf16_f32 v153, v56, v57
	ds_read_b64_tr_b16 v[54:55], v208 offset:27648
	ds_read_b64_tr_b16 v[56:57], v208 offset:28160
	s_waitcnt lgkmcnt(14)
	v_mfma_f32_32x32x16_bf16 v[98:113], v[118:121], v[130:133], v[98:113]
	v_add_f32_e32 v50, v60, v50
	v_add_f32_e32 v50, v61, v50
	v_add_f32_e32 v50, v62, v50
	v_add_f32_e32 v78, v63, v50
	v_cvt_pk_bf16_f32 v146, v58, v59
	v_cvt_pk_bf16_f32 v147, v60, v61
	ds_read_b64_tr_b16 v[50:51], v208 offset:31744
	ds_read_b64_tr_b16 v[52:53], v208 offset:32256
	v_mfma_f32_32x32x16_bf16 v[82:97], v[114:117], v[130:133], v[82:97]
	v_add_f32_e32 v58, v64, v78
	v_add_f32_e32 v58, v65, v58
	v_add_f32_e32 v58, 0, v58
	v_cvt_pk_bf16_f32 v148, v62, v63
	v_cvt_pk_bf16_f32 v149, v64, v65
	s_cmp_lg_u32 0, -1
	s_cselect_b32 s15, 0, 0
	v_add_f32_e32 v196, v182, v58
	v_lshl_add_u64 v[58:59], v[186:187], 0, s[42:43]
	s_add_i32 s15, s15, s68
	s_add_i32 s18, s15, 0x2000
	s_mov_b32 m0, s18
	s_nop 0
	global_load_lds_dwordx4 v[58:59], off
	v_lshl_add_u64 v[58:59], v[194:195], 0, s[44:45]
	s_add_i32 s15, s15, 0xa000
	s_mov_b32 m0, s15
	s_nop 0
	global_load_lds_dwordx4 v[58:59], off
	v_max_f32_e32 v58, v98, v99
	v_max3_f32 v59, v100, v101, v83
	v_max3_f32 v58, v58, v82, v84
	v_max3_f32 v58, v58, v85, v102
	v_max3_f32 v59, v59, v104, v105
	v_max3_f32 v58, v58, v103, v86
	v_max3_f32 v59, v59, v88, v89
	v_max3_f32 v58, v58, v87, v106
	v_max3_f32 v59, v59, v108, v109
	v_max3_f32 v58, v58, v107, v90
	v_max3_f32 v59, v59, v92, v93
	v_max3_f32 v58, v58, v91, v110
	v_max3_f32 v59, v59, v112, v113
	v_max3_f32 v58, v58, v111, v94
	v_max3_f32 v59, v59, v96, v97
	v_max3_f32 v58, v58, v95, v59
	v_mov_b32_e32 v59, v58
	s_nop 1
	v_permlane32_swap_b32_e32 v58, v59
	v_max_f32_e32 v58, v58, v59
	v_cmp_lt_f32_e32 vcc, s83, v58
	s_cmp_lg_u64 vcc, 0
	s_cselect_b64 s[60:61], -1, 0
	s_cbranch_vccnz .LBB0_1011

.LBB0_936:
	ds_read_b64_tr_b16 v[166:167], v208 offset:32768
	ds_read_b64_tr_b16 v[168:169], v208 offset:33280
	v_mfma_f32_32x32x16_bf16 v[114:129], v[58:61], v[142:145], v[34:49]
	v_add_f32_e32 v50, v98, v99
	v_add_f32_e32 v50, v100, v50
	v_add_f32_e32 v50, v101, v50
	v_add_f32_e32 v50, v102, v50
	v_add_f32_e32 v50, v103, v50
	v_cvt_pk_bf16_f32 v158, v98, v99
	v_cvt_pk_bf16_f32 v159, v100, v101
	ds_read_b64_tr_b16 v[162:163], v208 offset:36864
	ds_read_b64_tr_b16 v[164:165], v208 offset:37376
	v_add_f32_e32 v50, v104, v50
	v_add_f32_e32 v50, v105, v50
	v_add_f32_e32 v50, v106, v50
	v_add_f32_e32 v66, v107, v50
	v_mfma_f32_32x32x16_bf16 v[50:65], v[182:185], v[142:145], v[34:49]
	v_cvt_pk_bf16_f32 v160, v102, v103
	v_cvt_pk_bf16_f32 v161, v104, v105
	ds_read_b64_tr_b16 v[102:103], v208 offset:33792
	ds_read_b64_tr_b16 v[104:105], v208 offset:34304
	v_mfma_f32_32x32x16_bf16 v[114:129], v[186:189], v[138:141], v[114:129]
	v_add_f32_e32 v66, v108, v66
	v_add_f32_e32 v66, v109, v66
	v_add_f32_e32 v66, v110, v66
	v_add_f32_e32 v66, v111, v66
	v_cvt_pk_bf16_f32 v154, v106, v107
	v_cvt_pk_bf16_f32 v155, v108, v109
	ds_read_b64_tr_b16 v[98:99], v208 offset:37888
	ds_read_b64_tr_b16 v[100:101], v208 offset:38400
	v_mfma_f32_32x32x16_bf16 v[50:65], v[78:81], v[138:141], v[50:65]
	v_add_f32_e32 v66, v112, v66
	v_add_f32_e32 v66, v113, v66
	v_add_f32_e32 v66, v82, v66
	v_add_f32_e32 v66, v83, v66
	v_cvt_pk_bf16_f32 v156, v110, v111
	v_cvt_pk_bf16_f32 v157, v112, v113
	ds_read_b64_tr_b16 v[78:79], v208 offset:34816
	ds_read_b64_tr_b16 v[80:81], v208 offset:35328
	v_mfma_f32_32x32x16_bf16 v[114:129], v[74:77], v[134:137], v[114:129]
	v_add_f32_e32 v66, v84, v66
	v_add_f32_e32 v66, v85, v66
	v_add_f32_e32 v66, v86, v66
	v_add_f32_e32 v66, v87, v66
	v_cvt_pk_bf16_f32 v150, v82, v83
	v_cvt_pk_bf16_f32 v151, v84, v85
	ds_read_b64_tr_b16 v[74:75], v208 offset:38912
	ds_read_b64_tr_b16 v[76:77], v208 offset:39424
	v_mfma_f32_32x32x16_bf16 v[50:65], v[174:177], v[134:137], v[50:65]
	v_add_f32_e32 v66, v88, v66
	v_add_f32_e32 v66, v89, v66
	v_add_f32_e32 v66, v90, v66
	v_add_f32_e32 v66, v91, v66
	v_cvt_pk_bf16_f32 v152, v86, v87
	v_cvt_pk_bf16_f32 v153, v88, v89
	ds_read_b64_tr_b16 v[70:71], v208 offset:35840
	ds_read_b64_tr_b16 v[72:73], v208 offset:36352
	v_mfma_f32_32x32x16_bf16 v[114:129], v[178:181], v[130:133], v[114:129]
	v_add_f32_e32 v66, v92, v66
	v_add_f32_e32 v66, v93, v66
	v_add_f32_e32 v66, v94, v66
	v_add_f32_e32 v82, v95, v66
	v_cvt_pk_bf16_f32 v146, v90, v91
	v_cvt_pk_bf16_f32 v147, v92, v93
	ds_read_b64_tr_b16 v[66:67], v208 offset:39936
	ds_read_b64_tr_b16 v[68:69], v208 offset:40448
	v_mfma_f32_32x32x16_bf16 v[50:65], v[170:173], v[130:133], v[50:65]
	v_add_f32_e32 v82, v96, v82
	v_add_f32_e32 v82, v97, v82
	v_add_f32_e32 v82, 0, v82
	v_cvt_pk_bf16_f32 v148, v94, v95
	v_cvt_pk_bf16_f32 v149, v96, v97
	s_nop 0
	v_add_f32_e32 v182, v196, v82
	v_lshl_add_u64 v[82:83], v[194:195], 0, s[46:47]
	s_mov_b32 m0, s69
	s_nop 0
	global_load_lds_dwordx4 v[82:83], off
	v_max_f32_e32 v82, v114, v115
	s_nop 0
	v_max3_f32 v83, v116, v117, v51
	v_max3_f32 v82, v82, v50, v52
	v_max3_f32 v82, v82, v53, v118
	v_max3_f32 v83, v83, v120, v121
	v_max3_f32 v82, v82, v119, v54
	v_max3_f32 v83, v83, v56, v57
	v_max3_f32 v82, v82, v55, v122
	v_max3_f32 v83, v83, v124, v125
	v_max3_f32 v82, v82, v123, v58
	v_max3_f32 v83, v83, v60, v61
	v_max3_f32 v82, v82, v59, v126
	v_max3_f32 v83, v83, v128, v129
	v_max3_f32 v82, v82, v127, v62
	v_max3_f32 v83, v83, v64, v65
	v_max3_f32 v82, v82, v63, v83
	v_mov_b32_e32 v83, v82
	s_nop 1
	v_permlane32_swap_b32_e32 v82, v83
	v_max_f32_e32 v82, v82, v83
	v_cmp_lt_f32_e32 vcc, s83, v82
	s_cmp_lg_u64 vcc, 0
	s_cselect_b64 s[60:61], -1, 0
	s_cbranch_vccnz .LBB0_1014

.LBB0_939:
	ds_read_b64_tr_b16 v[162:163], v208 offset:40960
	ds_read_b64_tr_b16 v[164:165], v208 offset:41472
	v_mfma_f32_32x32x16_bf16 v[82:97], v[110:113], v[142:145], v[34:49]
	v_add_f32_e32 v66, v114, v115
	v_add_f32_e32 v66, v116, v66
	v_add_f32_e32 v66, v117, v66
	v_add_f32_e32 v66, v118, v66
	v_add_f32_e32 v66, v119, v66
	v_cvt_pk_bf16_f32 v158, v114, v115
	v_cvt_pk_bf16_f32 v159, v116, v117
	ds_read_b64_tr_b16 v[114:115], v208 offset:45056
	ds_read_b64_tr_b16 v[116:117], v208 offset:45568
	v_add_f32_e32 v66, v120, v66
	v_add_f32_e32 v66, v121, v66
	v_add_f32_e32 v66, v122, v66
	v_add_f32_e32 v146, v123, v66
	v_mfma_f32_32x32x16_bf16 v[66:81], v[106:109], v[142:145], v[34:49]
	v_cvt_pk_bf16_f32 v160, v118, v119
	v_cvt_pk_bf16_f32 v161, v120, v121
	ds_read_b64_tr_b16 v[110:111], v208 offset:41984
	ds_read_b64_tr_b16 v[112:113], v208 offset:42496
	v_mfma_f32_32x32x16_bf16 v[82:97], v[178:181], v[138:141], v[82:97]
	v_add_f32_e32 v106, v124, v146
	v_add_f32_e32 v106, v125, v106
	v_add_f32_e32 v106, v126, v106
	v_add_f32_e32 v118, v127, v106
	v_cvt_pk_bf16_f32 v154, v122, v123
	v_cvt_pk_bf16_f32 v155, v124, v125
	ds_read_b64_tr_b16 v[106:107], v208 offset:46080
	ds_read_b64_tr_b16 v[108:109], v208 offset:46592
	v_mfma_f32_32x32x16_bf16 v[66:81], v[102:105], v[138:141], v[66:81]
	v_add_f32_e32 v118, v128, v118
	v_add_f32_e32 v118, v129, v118
	v_add_f32_e32 v118, v50, v118
	v_add_f32_e32 v118, v51, v118
	v_cvt_pk_bf16_f32 v156, v126, v127
	v_cvt_pk_bf16_f32 v157, v128, v129
	ds_read_b64_tr_b16 v[102:103], v208 offset:43008
	ds_read_b64_tr_b16 v[104:105], v208 offset:43520
	v_mfma_f32_32x32x16_bf16 v[82:97], v[98:101], v[134:137], v[82:97]
	v_add_f32_e32 v118, v52, v118
	v_add_f32_e32 v118, v53, v118
	v_add_f32_e32 v118, v54, v118
	v_add_f32_e32 v118, v55, v118
	v_cvt_pk_bf16_f32 v150, v50, v51
	v_cvt_pk_bf16_f32 v151, v52, v53
	ds_read_b64_tr_b16 v[98:99], v208 offset:47104
	ds_read_b64_tr_b16 v[100:101], v208 offset:47616
	v_mfma_f32_32x32x16_bf16 v[66:81], v[170:173], v[134:137], v[66:81]
	v_add_f32_e32 v50, v56, v118
	v_add_f32_e32 v50, v57, v50
	v_add_f32_e32 v50, v58, v50
	v_add_f32_e32 v50, v59, v50
	v_cvt_pk_bf16_f32 v152, v54, v55
	v_cvt_pk_bf16_f32 v153, v56, v57
	ds_read_b64_tr_b16 v[54:55], v208 offset:44032
	ds_read_b64_tr_b16 v[56:57], v208 offset:44544
	v_mfma_f32_32x32x16_bf16 v[82:97], v[174:177], v[130:133], v[82:97]
	v_add_f32_e32 v50, v60, v50
	v_add_f32_e32 v50, v61, v50
	v_add_f32_e32 v50, v62, v50
	v_add_f32_e32 v118, v63, v50
	v_cvt_pk_bf16_f32 v146, v58, v59
	v_cvt_pk_bf16_f32 v147, v60, v61
	ds_read_b64_tr_b16 v[50:51], v208 offset:48128
	ds_read_b64_tr_b16 v[52:53], v208 offset:48640
	v_mfma_f32_32x32x16_bf16 v[66:81], v[166:169], v[130:133], v[66:81]
	v_add_f32_e32 v58, v64, v118
	v_add_f32_e32 v58, v65, v58
	v_add_f32_e32 v58, 0, v58
	v_cvt_pk_bf16_f32 v148, v62, v63
	v_cvt_pk_bf16_f32 v149, v64, v65
	s_cmp_lg_u32 0, -1
	s_cselect_b32 s15, 0, 0
	v_add_f32_e32 v118, v182, v58
	v_lshl_add_u64 v[58:59], v[194:195], 0, s[42:43]
	s_add_i32 s15, s15, s68
	s_add_i32 s15, s15, 0x8000
	s_mov_b32 m0, s15
	s_nop 0
	global_load_lds_dwordx4 v[58:59], off
	v_max_f32_e32 v58, v82, v83
	v_max3_f32 v59, v84, v85, v67
	v_max3_f32 v58, v58, v66, v68
	v_max3_f32 v58, v58, v69, v86
	v_max3_f32 v59, v59, v88, v89
	v_max3_f32 v58, v58, v87, v70
	v_max3_f32 v59, v59, v72, v73
	v_max3_f32 v58, v58, v71, v90
	v_max3_f32 v59, v59, v92, v93
	v_max3_f32 v58, v58, v91, v74
	v_max3_f32 v59, v59, v76, v77
	v_max3_f32 v58, v58, v75, v94
	v_max3_f32 v59, v59, v96, v97
	v_max3_f32 v58, v58, v95, v78
	v_max3_f32 v59, v59, v80, v81
	v_max3_f32 v58, v58, v79, v59
	v_mov_b32_e32 v59, v58
	s_nop 1
	v_permlane32_swap_b32_e32 v58, v59
	v_max_f32_e32 v58, v58, v59
	v_cmp_lt_f32_e32 vcc, s83, v58
	s_cmp_lg_u64 vcc, 0
	s_cselect_b64 s[60:61], -1, 0
	s_cbranch_vccnz .LBB0_1017

; __device__ __forceinline__ void kmask(f32x16&p0,f32x16&p1,int rem,int hi){
;   const float NEG=-INFINITY;
;   #pragma unroll
;   for(int r=0;r<16;++r){int kv=4*hi+(r&3)+8*(r>>2); if(kv>=rem)p0[r]=NEG; if(kv+32>=rem)p1[r]=NEG;}
; }
.LBB0_942:
	ds_read_b64_tr_b16 v[62:63], v208 offset:24576
	ds_read_b64_tr_b16 v[64:65], v208 offset:25088
	v_mfma_f32_32x32x16_bf16 v[34:49], v[114:117], v[142:145], v[34:49]
	v_add_f32_e32 v50, v82, v83
	v_add_f32_e32 v50, v84, v50
	v_add_f32_e32 v50, v85, v50
	v_add_f32_e32 v50, v86, v50
	v_add_f32_e32 v50, v87, v50
	v_cvt_pk_bf16_f32 v158, v82, v83
	v_cvt_pk_bf16_f32 v159, v84, v85
	ds_read_b64_tr_b16 v[102:103], v208 offset:28672
	ds_read_b64_tr_b16 v[104:105], v208 offset:29184
	v_add_f32_e32 v50, v88, v50
	v_add_f32_e32 v50, v89, v50
	v_add_f32_e32 v50, v90, v50
	v_add_f32_e32 v50, v91, v50
	v_cvt_pk_bf16_f32 v160, v86, v87
	v_cvt_pk_bf16_f32 v161, v88, v89
	ds_read_b64_tr_b16 v[98:99], v208 offset:25600
	ds_read_b64_tr_b16 v[100:101], v208 offset:26112
	v_mfma_f32_32x32x16_bf16 v[34:49], v[110:113], v[138:141], v[34:49]
	v_add_f32_e32 v50, v92, v50
	v_add_f32_e32 v50, v93, v50
	v_add_f32_e32 v50, v94, v50
	v_add_f32_e32 v50, v95, v50
	v_cvt_pk_bf16_f32 v154, v90, v91
	v_cvt_pk_bf16_f32 v155, v92, v93
	ds_read_b64_tr_b16 v[90:91], v208 offset:29696
	ds_read_b64_tr_b16 v[92:93], v208 offset:30208
	v_add_f32_e32 v50, v96, v50
	v_add_f32_e32 v50, v97, v50
	v_add_f32_e32 v50, v66, v50
	v_add_f32_e32 v50, v67, v50
	v_cvt_pk_bf16_f32 v156, v94, v95
	v_cvt_pk_bf16_f32 v157, v96, v97
	ds_read_b64_tr_b16 v[86:87], v208 offset:26624
	ds_read_b64_tr_b16 v[88:89], v208 offset:27136
	v_mfma_f32_32x32x16_bf16 v[34:49], v[106:109], v[134:137], v[34:49]
	v_add_f32_e32 v50, v68, v50
	v_add_f32_e32 v50, v69, v50
	v_add_f32_e32 v50, v70, v50
	v_add_f32_e32 v50, v71, v50
	v_cvt_pk_bf16_f32 v150, v66, v67
	v_cvt_pk_bf16_f32 v151, v68, v69
	ds_read_b64_tr_b16 v[82:83], v208 offset:30720
	ds_read_b64_tr_b16 v[84:85], v208 offset:31232
	v_add_f32_e32 v50, v72, v50
	v_add_f32_e32 v50, v73, v50
	v_add_f32_e32 v50, v74, v50
	v_add_f32_e32 v50, v75, v50
	v_cvt_pk_bf16_f32 v152, v70, v71
	v_cvt_pk_bf16_f32 v153, v72, v73
	ds_read_b64_tr_b16 v[70:71], v208 offset:27648
	ds_read_b64_tr_b16 v[72:73], v208 offset:28160
	v_mfma_f32_32x32x16_bf16 v[34:49], v[58:61], v[130:133], v[34:49]
	v_add_f32_e32 v50, v76, v50
	v_add_f32_e32 v50, v77, v50
	v_add_f32_e32 v50, v78, v50
	v_add_f32_e32 v50, v79, v50
	v_cvt_pk_bf16_f32 v146, v74, v75
	v_cvt_pk_bf16_f32 v147, v76, v77
	ds_read_b64_tr_b16 v[66:67], v208 offset:31744
	ds_read_b64_tr_b16 v[68:69], v208 offset:32256
	s_nop 3
	v_add_f32_e32 v42, v80, v50
	v_add_f32_e32 v42, v81, v42
	v_add_f32_e32 v42, 0, v42
	v_cvt_pk_bf16_f32 v148, v78, v79
	v_cvt_pk_bf16_f32 v149, v80, v81
	v_max_f32_e32 v44, v37, v37
	v_max_f32_e32 v45, v36, v36
	v_add_f32_e32 v74, v118, v42
	v_mov_b32_e32 v42, 0xff800000
	v_max_f32_e32 v44, v45, v44
	v_max3_f32 v43, v34, v35, v42
	v_max3_f32 v44, v44, v42, v40
	v_max3_f32 v43, v43, v38, v39
	v_max3_f32 v44, v44, v41, v42
	v_max3_f32 v43, v43, v42, v44
	v_mov_b32_e32 v44, v43
	s_nop 1
	v_permlane32_swap_b32_e32 v43, v44
	v_max_f32_e32 v43, v43, v44
	v_cmp_lt_f32_e32 vcc, s83, v43
	s_cmp_lg_u64 vcc, 0
	s_cselect_b64 s[60:61], -1, 0
	s_cbranch_vccnz .LBB0_1020

; #define WAIT_BAR(N) asm volatile("s_waitcnt vmcnt(" #N ") lgkmcnt(0)\n\ts_barrier":::"memory")
;   #define DMA_K(t,slot) glds16(ksrc+(long)(t)*KVBLK*KP,(unsigned)__builtin_amdgcn_readfirstlane(kdst+(slot)))
;   #define DMA_V(t,slot) glds16(vsrc+(long)(t)*KVBLK*KP,(unsigned)__builtin_amdgcn_readfirstlane(vdst+(slot)))
; template<int THRL,int L,int NT> __device__ __forceinline__ void attn_unit(long rowbase,int kvh,int qblk,const bf16*Q,const bf16*__restrict__ K,const bf16*__restrict__ V,bf16*O,char*shm,const int tid){
;   const int lane=tid&63,r32=lane&31,hi=lane>>5; const int wid=__builtin_amdgcn_readfirstlane(tid>>6);
;   const int q0=qblk*64, qh=wid>>1, rh=wid&1;
;   const bf16*Qw=Q+(rowbase+q0+rh*QBLK)*QP+(4*kvh+qh)*D;
;   const bf16*Kh=K+rowbase*KP+kvh*D,*Vh=V+rowbase*KP+kvh*D;
;   const unsigned lds0=(unsigned)(uintptr_t)shm;
;   float*wsf=(float*)(shm+LDS_WS)+wid*64;
;   const bf16*ksrc=Kh+(long)lane*KP+wid*8;
;   const bf16*vsrc=Vh+(long)(16*(wid&3)+(lane>>2))*KP+(wid>>2)*32+(lane&3)*8;
;   const unsigned kdst=lds0+LDS_K+wid*1024, vdst=lds0+LDS_V+wid*1024;
;     ...
;   const int vb0=(int)(lds0+LDS_V)+((lane>>4)&1)*32+(lane&3)*8+(4*hi+((lane&15)>>2))*64;
;   const char*Kbase=shm+LDS_K; bf16x8 kf[8];
;   const lds_cptr shm3=(lds_cptr)shm; const lds_cptr kp0=shm3+LDS_K+hi*1024+r32*16; const lds_cptr vp0=shm3+LDS_V+((lane>>4)&1)*32+(lane&3)*8+(4*hi+((lane&15)>>2))*64;
;   DMA_K(0,0);DMA_V(0,0);DMA_K(1,SLOTB);
;   bf16x8 qr[4];
;   #pragma unroll
;   for(int d0=0;d0<4;++d0)qr[d0]=*reinterpret_cast<const bf16x8*>(&Qw[(long)r32*QP+d0*16+hi*8]);
;   if(q0+rh*QBLK+r32>=L){
;     #pragma unroll
;     for(int d0=0;d0<4;++d0)qr[d0]=bf16x8{0,0,0,0,0,0,0,0}; }
;   float mhat=0.f,l_reg=0.f;f32x16 o[2];o[0]=f32x16{};o[1]=f32x16{};f32x16 negm=f32x16{};asm volatile("":"+v"(negm));
;     ...
;   bool resc=false;
;     ...
;   f32x16 pA0,pA1,pB0,pB1;
;   int sl_prev=0,sl_cur=0,sl_next=SLOTB;
;     ...
;   DMA_K(2,2*SLOTB);
;   WAIT_BAR(3);
; __device__ __forceinline__ void attention_phase(const PT a, unsigned char* ws, int l, unsigned char* lds_generic, int tid, bool dry = false) {
;     ...
;         else { const int u2 = u - ATT_UNITS_P, s = u2 / 132, rem = u2 - s * 132, kvh = rem / 33, qblk = rem - kvh * 33;
;             attn_body::attn_unit<8, LS, 33>((long)ROWS_P + (long)s * LS, kvh, qblk, Q, K, V, O, (char*)lds_generic, tidu); }
.LBB0_2473:
	v_mov_b32_e32 v204, v1
	s_mov_b64 s[4:5], -1
	v_and_b32_e32 v198, 63, v204
	v_and_b32_e32 v200, 31, v204
	v_lshlrev_b32_e32 v199, 3, v204
	s_cmpk_gt_i32 s66, 0x40f
	v_bfe_u32 v201, v204, 5, 1
	v_bfe_u32 v203, v204, 2, 4
	v_lshlrev_b32_e32 v192, 9, v198
	v_and_b32_e32 v202, 24, v199
	v_lshlrev_b32_e32 v205, 11, v200
	s_cbranch_scc0 .LBB0_2514
	s_add_i32 s4, s66, 0xfffffbf0
	s_mul_hi_u32 s5, s4, 0x3e0f83e1
	s_lshr_b32 s97, s5, 5
	s_mul_i32 s5, s97, 0xffffff7c
	s_add_i32 s5, s5, s4
	s_mul_hi_i32 s4, s5, 0x3e0f83e1
	s_lshr_b32 s15, s4, 31
	s_ashr_i32 s4, s4, 3
	s_add_i32 s60, s4, s15
	s_mul_i32 s4, s60, 0xffffffdf
	s_add_i32 s18, s4, s5
	s_mul_i32 s4, s97, 0x810
	s_mul_hi_u32 s5, s97, 0x810
	s_add_u32 s4, s4, 0x4040
	s_addc_u32 s5, s5, 0
	v_readfirstlane_b32 s15, v204
	s_lshl_b32 s67, s18, 6
	s_ashr_i32 s68, s15, 6
	s_ashr_i32 s18, s67, 31
	s_add_u32 s19, s4, s67
	s_addc_u32 s58, s5, s18
	s_lshl_b32 s18, s68, 5
	s_and_b32 s92, s18, 32
	s_add_u32 s18, s19, s92
	s_addc_u32 s19, s58, 0
	s_lshl_b64 s[18:19], s[18:19], 11
	s_add_u32 s58, s6, s18
	s_addc_u32 s59, s71, s19
	s_ashr_i32 s19, s15, 1
	s_lshl_b32 s18, s60, 8
	s_andn2_b32 s19, s19, 63
	s_add_i32 s18, s19, s18
	s_ashr_i32 s19, s18, 31
	s_lshl_b64 s[18:19], s[18:19], 1
	s_add_u32 s58, s58, s18
	s_addc_u32 s59, s59, s19
	s_lshl_b64 s[4:5], s[4:5], 9
	s_add_u32 s62, s72, s4
	s_addc_u32 s63, s73, s5
	s_lshl_b32 s18, s60, 6
	s_ashr_i32 s19, s18, 31
	s_lshl_b64 s[60:61], s[18:19], 1
	s_add_u32 s18, s62, s60
	s_addc_u32 s19, s63, s61
	s_add_u32 s4, s74, s4
	s_addc_u32 s5, s75, s5
	s_add_u32 s4, s4, s60
	s_addc_u32 s5, s5, s61
	s_lshl_b32 s62, s68, 3
	v_lshl_add_u64 v[2:3], s[18:19], 0, v[192:193]
	s_ashr_i32 s63, s62, 31
	s_lshl_b32 s18, s68, 4
	v_lshl_add_u64 v[186:187], s[62:63], 1, v[2:3]
	v_and_or_b32 v2, s18, 48, v203
	v_lshlrev_b32_e32 v2, 9, v2
	v_mov_b32_e32 v3, v193
	v_lshl_add_u64 v[2:3], s[4:5], 0, v[2:3]
	s_ashr_i32 s4, s15, 3
	s_and_b32 s64, s4, 0xffffffe0
	s_ashr_i32 s65, s64, 31
	s_lshl_b32 s69, s68, 10
	s_cmp_lg_u32 0, -1
	s_cselect_b32 s4, 0, 0
	v_lshl_add_u64 v[2:3], s[64:65], 1, v[2:3]
	v_lshlrev_b32_e32 v4, 1, v202
	v_mov_b32_e32 v5, v193
	s_add_i32 s94, s69, s4
	s_mov_b32 m0, s94
	s_nop 0
	global_load_lds_dwordx4 v[186:187], off
	v_lshl_add_u64 v[194:195], v[2:3], 0, v[4:5]
	s_add_i32 s93, s94, 0x6000
	s_mov_b32 m0, s93
	s_nop 0
	global_load_lds_dwordx4 v[194:195], off
	v_lshl_add_u64 v[2:3], v[186:187], 0, s[26:27]
	s_add_i32 s4, s94, 0x2000
	s_mov_b32 m0, s4
	s_nop 0
	global_load_lds_dwordx4 v[2:3], off
	v_lshl_or_b32 v2, v201, 4, v205
	global_load_dwordx4 v[142:145], v2, s[58:59]
	global_load_dwordx4 v[138:141], v2, s[58:59] offset:32
	global_load_dwordx4 v[134:137], v2, s[58:59] offset:64
	global_load_dwordx4 v[130:133], v2, s[58:59] offset:96
	s_or_b32 s67, s92, s67
	v_or_b32_e32 v2, s67, v200
	s_movk_i32 s4, 0x80f
	v_cmp_lt_i32_e32 vcc, s4, v2
	s_and_saveexec_b64 s[4:5], vcc
	s_cbranch_execz .LBB0_2476
	s_waitcnt vmcnt(3)
	v_mov_b32_e32 v142, 0
	v_mov_b32_e32 v143, v142
	v_mov_b32_e32 v144, v142
	v_mov_b32_e32 v145, v142
	s_waitcnt vmcnt(2)
	v_mov_b32_e32 v138, v142
	v_mov_b32_e32 v139, v142
	v_mov_b32_e32 v140, v142
	v_mov_b32_e32 v141, v142
	s_waitcnt vmcnt(1)
	v_mov_b32_e32 v134, v142
	v_mov_b32_e32 v135, v142
	v_mov_b32_e32 v136, v142
	v_mov_b32_e32 v137, v142
	s_waitcnt vmcnt(0)
	v_mov_b32_e32 v130, v142
	v_mov_b32_e32 v131, v142
	v_mov_b32_e32 v132, v142
	v_mov_b32_e32 v133, v142
.LBB0_2476:
	s_or_b64 exec, exec, s[4:5]
	s_and_b32 s4, s15, 0x3fffffc0
	s_lshl_b32 s4, s4, 2
	s_add_i32 s92, s4, 0
	s_cmp_lg_u32 0, -1
	s_cselect_b32 s4, 0, 0
	v_lshlrev_b32_e32 v2, 10, v201
	v_lshlrev_b32_e32 v3, 4, v200
	v_mov_b32_e32 v18, v193
	v_mov_b32_e32 v19, v193
	v_mov_b32_e32 v20, v193
	v_mov_b32_e32 v21, v193
	v_mov_b32_e32 v22, v193
	v_mov_b32_e32 v23, v193
	v_mov_b32_e32 v24, v193
	v_mov_b32_e32 v25, v193
	v_mov_b32_e32 v26, v193
	v_mov_b32_e32 v27, v193
	v_mov_b32_e32 v28, v193
	v_mov_b32_e32 v29, v193
	v_mov_b32_e32 v30, v193
	v_mov_b32_e32 v31, v193
	v_mov_b32_e32 v32, v193
	v_mov_b32_e32 v33, v193
	s_add_i32 s4, s4, s69
	v_add3_u32 v211, 0, v2, v3
	v_lshl_add_u64 v[2:3], v[186:187], 0, s[28:29]
	s_add_i32 s5, s4, 0x4000
	s_mov_b32 m0, s5
	s_nop 0
	global_load_lds_dwordx4 v[2:3], off
	s_waitcnt vmcnt(3) lgkmcnt(0)
	s_barrier
; #define WAIT_BAR(N) asm volatile("s_waitcnt vmcnt(" #N ") lgkmcnt(0)\n\ts_barrier":::"memory")
;   #define DMA_K(t,slot) glds16(ksrc+(long)(t)*KVBLK*KP,(unsigned)__builtin_amdgcn_readfirstlane(kdst+(slot)))
;   #define DMA_V(t,slot) glds16(vsrc+(long)(t)*KVBLK*KP,(unsigned)__builtin_amdgcn_readfirstlane(vdst+(slot)))
;   #define CMASK(P0,P1,t) do{ if((t)>=NT-2)kmask(P0,P1,L-64*(t),hi);}while(0)
;   #define START(P0,P1) do{ const float rm=rowmax(P0,P1); resc=false; \
;     { const float dl=rm; mhat=fadd_s(mhat,dl); \
;       _Pragma("unroll") for(int r=0;r<16;++r){P0[r]=fsub_s(P0[r],dl);P1[r]=fsub_s(P1[r],dl);} \
;       _Pragma("unroll") for(int r=0;r<16;++r)negm[r]=-mhat; asm volatile("":"+v"(negm)); } \
;     _Pragma("unroll") for(int r=0;r<16;++r)P0[r]=__builtin_amdgcn_exp2f(P0[r]); }while(0)
;   #define ROT() do{sl_prev=sl_cur;sl_cur=sl_next;sl_next=(sl_next==(NSLOT-1)*SLOTB)?0:sl_next+SLOTB;}while(0)
;   #define CMASK(P0,P1,t) do{}while(0)
;   #define CMASK(P0,P1,t) do{ if((t)>=NT-2)kmask(P0,P1,L-64*(t),hi);}while(0)
; template<int THRL,int L,int NT> __device__ __forceinline__ void attn_unit(long rowbase,int kvh,int qblk,const bf16*Q,const bf16*__restrict__ K,const bf16*__restrict__ V,bf16*O,char*shm,const int tid){
;     ...
;   qkt(pA0,pA1,Kbase,qr,negm,r32,hi);asm volatile("s_nop 15\n\ts_nop 7":"+v"(pA0),"+v"(pA1));CMASK(pA0,pA1,0);
;   START(pA0,pA1);
;   _Pragma("unroll") for(int r=0;r<16;++r)pA1[r]=__builtin_amdgcn_exp2f(pA1[r]);
;   WAIT_BAR(0);
;   DMA_K(3,0);DMA_V(1,SLOTB);
;   ROT();
;   kload8(kf,kp0+sl_cur);
;   WAIT_BAR(2);
	ds_read_b128 v[2:5], v211
	ds_read_b128 v[6:9], v211 offset:512
	s_waitcnt vmcnt(3) lgkmcnt(1)
	v_mfma_f32_32x32x16_bf16 v[34:49], v[2:5], v[142:145], v[18:33]
	s_add_i32 s4, s4, 0x8000
	s_lshl_b64 s[64:65], s[64:65], 1
	s_add_u32 s64, s64, s60
	s_mul_hi_u32 s19, s97, 0x102000
	s_mul_i32 s97, s97, 0x102000
	s_addc_u32 s65, s65, s61
	s_add_u32 s64, s64, s97
	s_waitcnt lgkmcnt(0)
	v_mfma_f32_32x32x16_bf16 v[18:33], v[6:9], v[142:145], v[18:33]
	ds_read_b128 v[2:5], v211 offset:2048
	ds_read_b128 v[6:9], v211 offset:2560
	s_addc_u32 s65, s65, s19
	s_lshl_b32 s15, s15, 7
	s_and_b32 s15, s15, 0x6000
	s_lshl_b64 s[62:63], s[62:63], 1
	s_mov_b32 s18, 0
	s_mov_b32 s95, -1
	s_waitcnt vmcnt(2) lgkmcnt(1)
	v_mfma_f32_32x32x16_bf16 v[34:49], v[2:5], v[138:141], v[34:49]
	ds_read_b128 v[10:13], v211 offset:4608
	ds_read_b128 v[2:5], v211 offset:4096
	ds_read_b128 v[50:53], v211 offset:6656
	ds_read_b128 v[14:17], v211 offset:6144
	s_movk_i32 s96, 0x4000
	v_lshl_add_u32 v208, v200, 2, s92
	v_lshlrev_b32_e32 v212, 4, v201
	v_mov_b32_e32 v182, 0
	s_waitcnt lgkmcnt(4)
	v_mfma_f32_32x32x16_bf16 v[18:33], v[6:9], v[138:141], v[18:33]
	v_lshlrev_b32_e32 v6, 1, v204
	v_and_b32_e32 v206, 32, v6
	v_lshlrev_b32_e32 v6, 4, v204
	v_and_b32_e32 v6, 0xc0, v6
	v_lshl_or_b32 v207, v201, 8, v6
	v_add_u32_e32 v6, 0, v206
	v_add3_u32 v209, v6, v202, v207
	s_waitcnt vmcnt(1) lgkmcnt(2)
	v_mfma_f32_32x32x16_bf16 v[34:49], v[2:5], v[134:137], v[34:49]
	v_mov_b32_e32 v2, v193
	v_mov_b32_e32 v3, v193
	v_mov_b32_e32 v4, v193
	v_mov_b32_e32 v5, v193
	v_mov_b32_e32 v6, v193
	v_mov_b32_e32 v7, v193
	v_mov_b32_e32 v8, v193
	v_mfma_f32_32x32x16_bf16 v[18:33], v[10:13], v[134:137], v[18:33]
	v_mov_b32_e32 v9, v193
	v_mov_b32_e32 v10, v193
	v_mov_b32_e32 v11, v193
	v_mov_b32_e32 v12, v193
	v_mov_b32_e32 v13, v193
	s_waitcnt vmcnt(0) lgkmcnt(0)
	v_mfma_f32_32x32x16_bf16 v[34:49], v[14:17], v[130:133], v[34:49]
	v_mov_b32_e32 v16, v193
	v_mov_b32_e32 v17, v193
	v_mov_b32_e32 v14, v193
	v_mov_b32_e32 v15, v193
	v_mfma_f32_32x32x16_bf16 v[18:33], v[50:53], v[130:133], v[18:33]
	s_nop 15
	s_nop 7
	s_nop 0
	v_max3_f32 v50, v34, v35, v18
	v_max3_f32 v51, v36, v37, v19
	s_nop 0
	v_max3_f32 v50, v50, v20, v21
	v_max3_f32 v51, v51, v40, v41
	s_nop 0
	v_max3_f32 v50, v50, v38, v39
	v_max3_f32 v51, v51, v24, v25
	s_nop 0
	v_max3_f32 v50, v50, v22, v23
	v_max3_f32 v51, v51, v44, v45
	s_nop 0
	v_max3_f32 v50, v50, v42, v43
	v_max3_f32 v51, v51, v28, v29
	s_nop 0
	v_max3_f32 v50, v50, v26, v27
	v_max3_f32 v51, v51, v48, v49
	s_nop 0
	v_max3_f32 v50, v50, v46, v47
	v_max3_f32 v51, v51, v32, v33
	s_nop 0
	v_max3_f32 v50, v50, v30, v31
	s_nop 0
	v_max_f32_e32 v50, v50, v51
	s_nop 0
	v_mov_b32_e32 v51, v50
	s_nop 1
	v_permlane32_swap_b32_e32 v50, v51
	v_max_f32_e32 v50, v50, v51
	s_nop 0
	v_add_f32_e32 v210, v193, v50
	v_sub_f32_e32 v51, v34, v50
	v_sub_f32_e32 v52, v35, v50
	v_sub_f32_e32 v53, v36, v50
	v_sub_f32_e32 v54, v37, v50
	v_sub_f32_e32 v55, v38, v50
	s_nop 0
	v_xor_b32_e32 v34, 0x80000000, v210
	v_sub_f32_e32 v56, v39, v50
	v_sub_f32_e32 v57, v40, v50
	v_sub_f32_e32 v58, v41, v50
	v_sub_f32_e32 v59, v42, v50
	v_sub_f32_e32 v60, v43, v50
	v_sub_f32_e32 v61, v44, v50
	v_sub_f32_e32 v62, v45, v50
	v_sub_f32_e32 v63, v46, v50
	v_sub_f32_e32 v64, v47, v50
	v_sub_f32_e32 v65, v48, v50
	v_sub_f32_e32 v81, v49, v50
	v_mov_b32_e32 v35, v34
	v_mov_b32_e32 v36, v34
	v_mov_b32_e32 v37, v34
	v_mov_b32_e32 v38, v34
	v_mov_b32_e32 v39, v34
	v_mov_b32_e32 v40, v34
	v_mov_b32_e32 v41, v34
	v_mov_b32_e32 v42, v34
	v_mov_b32_e32 v43, v34
	v_mov_b32_e32 v44, v34
	v_mov_b32_e32 v45, v34
	v_mov_b32_e32 v46, v34
	v_mov_b32_e32 v47, v34
	v_mov_b32_e32 v48, v34
	v_mov_b32_e32 v49, v34
	v_sub_f32_e32 v18, v18, v50
	v_sub_f32_e32 v19, v19, v50
	s_waitcnt vmcnt(0) lgkmcnt(0)
	s_barrier
	v_sub_f32_e32 v20, v20, v50
	v_sub_f32_e32 v21, v21, v50
	v_sub_f32_e32 v22, v22, v50
	v_sub_f32_e32 v23, v23, v50
	v_sub_f32_e32 v24, v24, v50
	v_sub_f32_e32 v25, v25, v50
	v_sub_f32_e32 v26, v26, v50
	v_sub_f32_e32 v27, v27, v50
	v_sub_f32_e32 v28, v28, v50
	v_sub_f32_e32 v29, v29, v50
	v_sub_f32_e32 v30, v30, v50
	v_sub_f32_e32 v31, v31, v50
	v_sub_f32_e32 v32, v32, v50
	v_sub_f32_e32 v33, v33, v50
	v_exp_f32_e32 v66, v51
	v_exp_f32_e32 v50, v18
	v_exp_f32_e32 v51, v19
	v_lshl_add_u64 v[18:19], v[186:187], 0, s[30:31]
	s_mov_b32 m0, s94
	s_nop 0
	global_load_lds_dwordx4 v[18:19], off
	v_lshl_add_u64 v[18:19], v[194:195], 0, s[26:27]
	s_mov_b32 m0, s4
	s_nop 0
	global_load_lds_dwordx4 v[18:19], off
	ds_read_b128 v[82:85], v211 offset:8192
	ds_read_b128 v[170:173], v211 offset:8704
	ds_read_b128 v[166:169], v211 offset:10240
	ds_read_b128 v[162:165], v211 offset:10752
	ds_read_b128 v[126:129], v211 offset:12288
	ds_read_b128 v[122:125], v211 offset:12800
	ds_read_b128 v[118:121], v211 offset:14336
	ds_read_b128 v[114:117], v211 offset:14848
	v_exp_f32_e32 v67, v52
	v_exp_f32_e32 v52, v20
	v_lshl_or_b32 v20, v203, 9, s15
	s_add_u32 s15, s76, s62
	v_and_b32_e32 v18, 3, v204
	s_addc_u32 s62, s77, s63
	v_lshlrev_b32_e32 v18, 4, v18
	v_mov_b32_e32 v19, v193
	s_add_u32 s15, s15, s60
	v_exp_f32_e32 v68, v53
	v_exp_f32_e32 v69, v54
	v_exp_f32_e32 v70, v55
	v_exp_f32_e32 v71, v56
	v_exp_f32_e32 v72, v57
	v_exp_f32_e32 v73, v58
	v_exp_f32_e32 v74, v59
	v_exp_f32_e32 v75, v60
	v_exp_f32_e32 v76, v61
	v_exp_f32_e32 v77, v62
	v_exp_f32_e32 v78, v63
	v_exp_f32_e32 v79, v64
	v_exp_f32_e32 v80, v65
	v_exp_f32_e32 v81, v81
	v_exp_f32_e32 v53, v21
	v_exp_f32_e32 v54, v22
	v_exp_f32_e32 v55, v23
	v_exp_f32_e32 v56, v24
	v_exp_f32_e32 v57, v25
	v_exp_f32_e32 v58, v26
	v_exp_f32_e32 v59, v27
	v_exp_f32_e32 v60, v28
	v_exp_f32_e32 v61, v29
	v_exp_f32_e32 v62, v30
	v_exp_f32_e32 v63, v31
	v_exp_f32_e32 v64, v32
	v_exp_f32_e32 v65, v33
	v_lshl_add_u64 v[18:19], s[64:65], 0, v[18:19]
	v_mov_b32_e32 v21, v193
	s_addc_u32 s61, s62, s61
	s_waitcnt vmcnt(2) lgkmcnt(0)
	s_barrier
	v_lshl_add_u64 v[18:19], v[18:19], 0, v[20:21]
	s_add_u32 s60, s15, s97
	v_lshl_add_u64 v[188:189], s[10:11], 0, v[18:19]
	s_addc_u32 s61, s61, s19
	v_mov_b64_e32 v[32:33], v[16:17]
	v_cmp_gt_u32_e64 s[4:5], 32, v198
	v_lshl_add_u64 v[196:197], s[60:61], 0, v[192:193]
	s_movk_i32 s64, 0x2000
	v_mov_b64_e32 v[30:31], v[14:15]
	v_mov_b64_e32 v[28:29], v[12:13]
	v_mov_b64_e32 v[26:27], v[10:11]
	v_mov_b64_e32 v[24:25], v[8:9]
	v_mov_b64_e32 v[22:23], v[6:7]
	v_mov_b64_e32 v[20:21], v[4:5]
	v_mov_b64_e32 v[18:19], v[2:3]
.LBB0_2477:
	v_add_u32_e32 v183, s18, v209
	ds_read_b64_tr_b16 v[178:179], v183 offset:24576
	ds_read_b64_tr_b16 v[180:181], v183 offset:25088
	v_mfma_f32_32x32x16_bf16 v[98:113], v[82:85], v[142:145], v[34:49]
	v_add_f32_e32 v86, v66, v67
	v_add_f32_e32 v86, v68, v86
	v_add_f32_e32 v86, v69, v86
	v_add_f32_e32 v86, v70, v86
	v_add_f32_e32 v86, v71, v86
	v_cvt_pk_bf16_f32 v158, v66, v67
	v_cvt_pk_bf16_f32 v159, v68, v69
	ds_read_b64_tr_b16 v[174:175], v183 offset:28672
	ds_read_b64_tr_b16 v[176:177], v183 offset:29184
	v_add_f32_e32 v66, v72, v86
	v_mfma_f32_32x32x16_bf16 v[82:97], v[170:173], v[142:145], v[34:49]
	v_add_f32_e32 v66, v73, v66
	v_add_f32_e32 v66, v74, v66
	v_add_f32_e32 v66, v75, v66
	v_cvt_pk_bf16_f32 v160, v70, v71
	v_cvt_pk_bf16_f32 v161, v72, v73
	ds_read_b64_tr_b16 v[170:171], v183 offset:25600
	ds_read_b64_tr_b16 v[172:173], v183 offset:26112
	v_mfma_f32_32x32x16_bf16 v[98:113], v[166:169], v[138:141], v[98:113]
	v_add_f32_e32 v66, v76, v66
	v_add_f32_e32 v66, v77, v66
	v_add_f32_e32 v66, v78, v66
	v_add_f32_e32 v66, v79, v66
	v_cvt_pk_bf16_f32 v154, v74, v75
	v_cvt_pk_bf16_f32 v155, v76, v77
	ds_read_b64_tr_b16 v[74:75], v183 offset:29696
	ds_read_b64_tr_b16 v[76:77], v183 offset:30208
	v_mfma_f32_32x32x16_bf16 v[82:97], v[162:165], v[138:141], v[82:97]
	v_add_f32_e32 v66, v80, v66
	v_add_f32_e32 v66, v81, v66
	v_add_f32_e32 v66, v50, v66
	v_add_f32_e32 v66, v51, v66
	v_cvt_pk_bf16_f32 v156, v78, v79
	v_cvt_pk_bf16_f32 v157, v80, v81
	ds_read_b64_tr_b16 v[70:71], v183 offset:26624
	ds_read_b64_tr_b16 v[72:73], v183 offset:27136
	v_mfma_f32_32x32x16_bf16 v[98:113], v[126:129], v[134:137], v[98:113]
	v_add_f32_e32 v66, v52, v66
	v_add_f32_e32 v66, v53, v66
	v_add_f32_e32 v66, v54, v66
	v_add_f32_e32 v78, v55, v66
	v_cvt_pk_bf16_f32 v150, v50, v51
	v_cvt_pk_bf16_f32 v151, v52, v53
	ds_read_b64_tr_b16 v[66:67], v183 offset:30720
	ds_read_b64_tr_b16 v[68:69], v183 offset:31232
	v_mfma_f32_32x32x16_bf16 v[82:97], v[122:125], v[134:137], v[82:97]
	v_add_f32_e32 v50, v56, v78
	v_add_f32_e32 v50, v57, v50
	v_add_f32_e32 v50, v58, v50
	v_add_f32_e32 v50, v59, v50
	v_cvt_pk_bf16_f32 v152, v54, v55
	v_cvt_pk_bf16_f32 v153, v56, v57
	ds_read_b64_tr_b16 v[54:55], v183 offset:27648
	ds_read_b64_tr_b16 v[56:57], v183 offset:28160
	v_mfma_f32_32x32x16_bf16 v[98:113], v[118:121], v[130:133], v[98:113]
	v_add_f32_e32 v50, v60, v50
	v_add_f32_e32 v50, v61, v50
	v_add_f32_e32 v50, v62, v50
	v_add_f32_e32 v78, v63, v50
	v_cvt_pk_bf16_f32 v146, v58, v59
	v_cvt_pk_bf16_f32 v147, v60, v61
	ds_read_b64_tr_b16 v[50:51], v183 offset:31744
	ds_read_b64_tr_b16 v[52:53], v183 offset:32256
	v_mfma_f32_32x32x16_bf16 v[82:97], v[114:117], v[130:133], v[82:97]
	v_add_f32_e32 v58, v64, v78
	v_add_f32_e32 v58, v65, v58
	v_add_f32_e32 v60, 0, v58
	v_cvt_pk_bf16_f32 v148, v62, v63
	v_cvt_pk_bf16_f32 v149, v64, v65
	v_lshl_add_u64 v[58:59], v[196:197], 0, s[30:31]
	s_add_i32 s15, s64, s94
	s_mov_b32 m0, s15
	s_nop 0
	global_load_lds_dwordx4 v[58:59], off
	v_lshl_add_u64 v[58:59], v[188:189], 0, s[26:27]
	s_add_i32 s15, s96, s93
	s_mov_b32 m0, s15
	s_nop 0
	global_load_lds_dwordx4 v[58:59], off
	v_max_f32_e32 v58, v98, v99
	v_max3_f32 v59, v100, v101, v83
	v_max3_f32 v58, v58, v82, v84
	v_max3_f32 v58, v58, v85, v102
	v_max3_f32 v59, v59, v104, v105
	v_max3_f32 v58, v58, v103, v86
	v_max3_f32 v59, v59, v88, v89
	v_max3_f32 v58, v58, v87, v106
	v_max3_f32 v59, v59, v108, v109
	v_max3_f32 v58, v58, v107, v90
	v_max3_f32 v59, v59, v92, v93
	v_max3_f32 v58, v58, v91, v110
	v_max3_f32 v59, v59, v112, v113
	v_max3_f32 v58, v58, v111, v94
	v_max3_f32 v59, v59, v96, v97
	v_max3_f32 v58, v58, v95, v59
	v_mov_b32_e32 v59, v58
	s_nop 1
	v_permlane32_swap_b32_e32 v58, v59
	v_max_f32_e32 v58, v58, v59
	v_cmp_lt_f32_e32 vcc, s82, v58
	s_cmp_lg_u64 vcc, 0
	v_add_f32_e32 v213, v182, v60
	s_cselect_b64 s[60:61], -1, 0
	s_cbranch_vccnz .LBB0_2485

.LBB0_2480:
	s_add_i32 s15, s96, 0x2000
	s_cmpk_lg_i32 s96, 0x4000
	s_cselect_b32 s65, s15, 0
	v_add_u32_e32 v214, s64, v209
	ds_read_b64_tr_b16 v[126:127], v214 offset:24576
	ds_read_b64_tr_b16 v[128:129], v214 offset:25088
	v_mfma_f32_32x32x16_bf16 v[66:81], v[58:61], v[142:145], v[34:49]
	v_add_f32_e32 v50, v98, v99
	v_add_f32_e32 v50, v100, v50
	v_add_f32_e32 v50, v101, v50
	v_add_f32_e32 v50, v102, v50
	v_add_f32_e32 v50, v103, v50
	v_cvt_pk_bf16_f32 v158, v98, v99
	v_cvt_pk_bf16_f32 v159, v100, v101
	ds_read_b64_tr_b16 v[122:123], v214 offset:28672
	ds_read_b64_tr_b16 v[124:125], v214 offset:29184
	v_add_f32_e32 v50, v104, v50
	v_add_f32_e32 v50, v105, v50
	v_add_f32_e32 v50, v106, v50
	v_add_f32_e32 v98, v107, v50
	v_mfma_f32_32x32x16_bf16 v[50:65], v[114:117], v[142:145], v[34:49]
	v_cvt_pk_bf16_f32 v160, v102, v103
	v_cvt_pk_bf16_f32 v161, v104, v105
	ds_read_b64_tr_b16 v[118:119], v214 offset:25600
	ds_read_b64_tr_b16 v[120:121], v214 offset:26112
	v_mfma_f32_32x32x16_bf16 v[66:81], v[182:185], v[138:141], v[66:81]
	v_add_f32_e32 v98, v108, v98
	v_add_f32_e32 v98, v109, v98
	v_add_f32_e32 v98, v110, v98
	v_add_f32_e32 v98, v111, v98
	v_cvt_pk_bf16_f32 v154, v106, v107
	v_cvt_pk_bf16_f32 v155, v108, v109
	ds_read_b64_tr_b16 v[114:115], v214 offset:29696
	ds_read_b64_tr_b16 v[116:117], v214 offset:30208
	v_mfma_f32_32x32x16_bf16 v[50:65], v[174:177], v[138:141], v[50:65]
	v_add_f32_e32 v98, v112, v98
	v_add_f32_e32 v98, v113, v98
	v_add_f32_e32 v98, v82, v98
	v_add_f32_e32 v98, v83, v98
	v_cvt_pk_bf16_f32 v156, v110, v111
	v_cvt_pk_bf16_f32 v157, v112, v113
	ds_read_b64_tr_b16 v[106:107], v214 offset:26624
	ds_read_b64_tr_b16 v[108:109], v214 offset:27136
	v_mfma_f32_32x32x16_bf16 v[66:81], v[178:181], v[134:137], v[66:81]
	v_add_f32_e32 v98, v84, v98
	v_add_f32_e32 v98, v85, v98
	v_add_f32_e32 v98, v86, v98
	v_add_f32_e32 v98, v87, v98
	v_cvt_pk_bf16_f32 v150, v82, v83
	v_cvt_pk_bf16_f32 v151, v84, v85
	ds_read_b64_tr_b16 v[102:103], v214 offset:30720
	ds_read_b64_tr_b16 v[104:105], v214 offset:31232
	v_mfma_f32_32x32x16_bf16 v[50:65], v[166:169], v[134:137], v[50:65]
	v_add_f32_e32 v82, v88, v98
	v_add_f32_e32 v82, v89, v82
	v_add_f32_e32 v82, v90, v82
	v_add_f32_e32 v82, v91, v82
	v_cvt_pk_bf16_f32 v152, v86, v87
	v_cvt_pk_bf16_f32 v153, v88, v89
	ds_read_b64_tr_b16 v[98:99], v214 offset:27648
	ds_read_b64_tr_b16 v[100:101], v214 offset:28160
	v_mfma_f32_32x32x16_bf16 v[66:81], v[170:173], v[130:133], v[66:81]
	v_add_f32_e32 v82, v92, v82
	v_add_f32_e32 v82, v93, v82
	v_add_f32_e32 v82, v94, v82
	v_add_f32_e32 v82, v95, v82
	v_cvt_pk_bf16_f32 v146, v90, v91
	v_cvt_pk_bf16_f32 v147, v92, v93
	ds_read_b64_tr_b16 v[86:87], v214 offset:31744
	ds_read_b64_tr_b16 v[88:89], v214 offset:32256
	v_mfma_f32_32x32x16_bf16 v[50:65], v[162:165], v[130:133], v[50:65]
	v_add_f32_e32 v82, v96, v82
	v_add_f32_e32 v82, v97, v82
	v_add_f32_e32 v84, 0, v82
	v_cvt_pk_bf16_f32 v148, v94, v95
	v_cvt_pk_bf16_f32 v149, v96, v97
	v_lshl_add_u64 v[82:83], v[196:197], 0, s[34:35]
	s_add_i32 s15, s96, s94
	s_mov_b32 m0, s15
	s_nop 0
	global_load_lds_dwordx4 v[82:83], off
	v_max_f32_e32 v82, v66, v67
	s_nop 1
	v_max3_f32 v83, v68, v69, v51
	v_max3_f32 v82, v82, v50, v52
	v_max3_f32 v82, v82, v53, v70
	v_max3_f32 v83, v83, v72, v73
	v_max3_f32 v82, v82, v71, v54
	v_max3_f32 v83, v83, v56, v57
	v_max3_f32 v82, v82, v55, v74
	v_max3_f32 v83, v83, v76, v77
	v_max3_f32 v82, v82, v75, v58
	v_max3_f32 v83, v83, v60, v61
	v_max3_f32 v82, v82, v59, v78
	v_max3_f32 v83, v83, v80, v81
	v_max3_f32 v82, v82, v79, v62
	v_max3_f32 v83, v83, v64, v65
	v_max3_f32 v82, v82, v63, v83
	v_mov_b32_e32 v83, v82
	s_nop 1
	v_permlane32_swap_b32_e32 v82, v83
	v_max_f32_e32 v82, v82, v83
	v_lshl_add_u64 v[188:189], v[188:189], 0, s[28:29]
	s_add_i32 s15, s65, s93
	s_mov_b32 m0, s15
	s_nop 0
	global_load_lds_dwordx4 v[188:189], off
	v_cmp_lt_f32_e32 vcc, s82, v82
	s_cmp_lg_u64 vcc, 0
	v_add_f32_e32 v182, v213, v84
	s_cselect_b64 s[60:61], -1, 0
	s_cbranch_vccnz .LBB0_2488

.LBB0_2491:
	ds_read_b64_tr_b16 v[178:179], v209 offset:32768
	ds_read_b64_tr_b16 v[180:181], v209 offset:33280
	s_waitcnt lgkmcnt(9)
	v_mfma_f32_32x32x16_bf16 v[98:113], v[82:85], v[142:145], v[34:49]
	v_add_f32_e32 v86, v66, v67
	v_add_f32_e32 v86, v68, v86
	v_add_f32_e32 v86, v69, v86
	v_add_f32_e32 v86, v70, v86
	v_add_f32_e32 v86, v71, v86
	v_cvt_pk_bf16_f32 v158, v66, v67
	v_cvt_pk_bf16_f32 v159, v68, v69
	ds_read_b64_tr_b16 v[174:175], v209 offset:36864
	ds_read_b64_tr_b16 v[176:177], v209 offset:37376
	v_add_f32_e32 v66, v72, v86
	s_waitcnt lgkmcnt(10)
	v_mfma_f32_32x32x16_bf16 v[82:97], v[170:173], v[142:145], v[34:49]
	v_add_f32_e32 v66, v73, v66
	v_add_f32_e32 v66, v74, v66
	v_add_f32_e32 v66, v75, v66
	v_cvt_pk_bf16_f32 v160, v70, v71
	v_cvt_pk_bf16_f32 v161, v72, v73
	ds_read_b64_tr_b16 v[170:171], v209 offset:33792
	ds_read_b64_tr_b16 v[172:173], v209 offset:34304
	s_waitcnt lgkmcnt(11)
	v_mfma_f32_32x32x16_bf16 v[98:113], v[166:169], v[138:141], v[98:113]
	v_add_f32_e32 v66, v76, v66
	v_add_f32_e32 v66, v77, v66
	v_add_f32_e32 v66, v78, v66
	v_add_f32_e32 v66, v79, v66
	v_cvt_pk_bf16_f32 v154, v74, v75
	v_cvt_pk_bf16_f32 v155, v76, v77
	ds_read_b64_tr_b16 v[74:75], v209 offset:37888
	ds_read_b64_tr_b16 v[76:77], v209 offset:38400
	s_waitcnt lgkmcnt(12)
	v_mfma_f32_32x32x16_bf16 v[82:97], v[162:165], v[138:141], v[82:97]
	v_add_f32_e32 v66, v80, v66
	v_add_f32_e32 v66, v81, v66
	v_add_f32_e32 v66, v50, v66
	v_add_f32_e32 v66, v51, v66
	v_cvt_pk_bf16_f32 v156, v78, v79
	v_cvt_pk_bf16_f32 v157, v80, v81
	ds_read_b64_tr_b16 v[70:71], v209 offset:34816
	ds_read_b64_tr_b16 v[72:73], v209 offset:35328
	s_waitcnt lgkmcnt(13)
	v_mfma_f32_32x32x16_bf16 v[98:113], v[126:129], v[134:137], v[98:113]
	v_add_f32_e32 v66, v52, v66
	v_add_f32_e32 v66, v53, v66
	v_add_f32_e32 v66, v54, v66
	v_add_f32_e32 v78, v55, v66
	v_cvt_pk_bf16_f32 v150, v50, v51
	v_cvt_pk_bf16_f32 v151, v52, v53
	ds_read_b64_tr_b16 v[66:67], v209 offset:38912
	ds_read_b64_tr_b16 v[68:69], v209 offset:39424
	s_waitcnt lgkmcnt(14)
	v_mfma_f32_32x32x16_bf16 v[82:97], v[122:125], v[134:137], v[82:97]
	v_add_f32_e32 v50, v56, v78
	v_add_f32_e32 v50, v57, v50
	v_add_f32_e32 v50, v58, v50
	v_add_f32_e32 v50, v59, v50
	v_cvt_pk_bf16_f32 v152, v54, v55
	v_cvt_pk_bf16_f32 v153, v56, v57
	ds_read_b64_tr_b16 v[54:55], v209 offset:35840
	ds_read_b64_tr_b16 v[56:57], v209 offset:36352
	s_waitcnt lgkmcnt(14)
	v_mfma_f32_32x32x16_bf16 v[98:113], v[118:121], v[130:133], v[98:113]
	v_add_f32_e32 v50, v60, v50
	v_add_f32_e32 v50, v61, v50
	v_add_f32_e32 v50, v62, v50
	v_add_f32_e32 v78, v63, v50
	v_cvt_pk_bf16_f32 v146, v58, v59
	v_cvt_pk_bf16_f32 v147, v60, v61
	ds_read_b64_tr_b16 v[50:51], v209 offset:39936
	ds_read_b64_tr_b16 v[52:53], v209 offset:40448
	v_mfma_f32_32x32x16_bf16 v[82:97], v[114:117], v[130:133], v[82:97]
	v_add_f32_e32 v58, v64, v78
	v_add_f32_e32 v58, v65, v58
	v_add_f32_e32 v58, 0, v58
	v_cvt_pk_bf16_f32 v148, v62, v63
	v_cvt_pk_bf16_f32 v149, v64, v65
	s_cmp_lg_u32 0, -1
	s_cselect_b32 s15, 0, 0
	s_add_i32 s15, s15, s69
	v_add_f32_e32 v197, v182, v58
	v_lshl_add_u64 v[58:59], v[186:187], 0, s[36:37]
	s_addk_i32 s15, 0x4000
	s_mov_b32 m0, s15
	s_nop 0
	global_load_lds_dwordx4 v[58:59], off
	s_mov_b64 s[18:19], 0xf0000
	v_lshl_add_u64 v[58:59], v[194:195], 0, s[18:19]
	s_mov_b32 m0, s93
	s_nop 0
	global_load_lds_dwordx4 v[58:59], off
	v_max_f32_e32 v58, v98, v99
	v_max3_f32 v59, v100, v101, v83
	v_max3_f32 v58, v58, v82, v84
	v_max3_f32 v58, v58, v85, v102
	v_max3_f32 v59, v59, v104, v105
	v_max3_f32 v58, v58, v103, v86
	v_max3_f32 v59, v59, v88, v89
	v_max3_f32 v58, v58, v87, v106
	v_max3_f32 v59, v59, v108, v109
	v_max3_f32 v58, v58, v107, v90
	v_max3_f32 v59, v59, v92, v93
	v_max3_f32 v58, v58, v91, v110
	v_max3_f32 v59, v59, v112, v113
	v_max3_f32 v58, v58, v111, v94
	v_max3_f32 v59, v59, v96, v97
	v_max3_f32 v58, v58, v95, v59
	v_mov_b32_e32 v59, v58
	s_nop 1
	v_permlane32_swap_b32_e32 v58, v59
	v_max_f32_e32 v58, v58, v59
	v_cmp_lt_f32_e32 vcc, s82, v58
	s_cmp_lg_u64 vcc, 0
	s_cselect_b64 s[60:61], -1, 0
	s_cbranch_vccnz .LBB0_2598

.LBB0_2494:
	ds_read_b64_tr_b16 v[166:167], v209 offset:40960
	ds_read_b64_tr_b16 v[168:169], v209 offset:41472
	v_mfma_f32_32x32x16_bf16 v[114:129], v[58:61], v[142:145], v[34:49]
	v_add_f32_e32 v50, v98, v99
	v_add_f32_e32 v50, v100, v50
	v_add_f32_e32 v50, v101, v50
	v_add_f32_e32 v50, v102, v50
	v_add_f32_e32 v50, v103, v50
	v_cvt_pk_bf16_f32 v158, v98, v99
	v_cvt_pk_bf16_f32 v159, v100, v101
	ds_read_b64_tr_b16 v[162:163], v209 offset:45056
	ds_read_b64_tr_b16 v[164:165], v209 offset:45568
	v_add_f32_e32 v50, v104, v50
	v_add_f32_e32 v50, v105, v50
	v_add_f32_e32 v50, v106, v50
	v_add_f32_e32 v66, v107, v50
	v_mfma_f32_32x32x16_bf16 v[50:65], v[182:185], v[142:145], v[34:49]
	v_cvt_pk_bf16_f32 v160, v102, v103
	v_cvt_pk_bf16_f32 v161, v104, v105
	ds_read_b64_tr_b16 v[102:103], v209 offset:41984
	ds_read_b64_tr_b16 v[104:105], v209 offset:42496
	v_mfma_f32_32x32x16_bf16 v[114:129], v[186:189], v[138:141], v[114:129]
	v_add_f32_e32 v66, v108, v66
	v_add_f32_e32 v66, v109, v66
	v_add_f32_e32 v66, v110, v66
	v_add_f32_e32 v66, v111, v66
	v_cvt_pk_bf16_f32 v154, v106, v107
	v_cvt_pk_bf16_f32 v155, v108, v109
	ds_read_b64_tr_b16 v[98:99], v209 offset:46080
	ds_read_b64_tr_b16 v[100:101], v209 offset:46592
	v_mfma_f32_32x32x16_bf16 v[50:65], v[78:81], v[138:141], v[50:65]
	v_add_f32_e32 v66, v112, v66
	v_add_f32_e32 v66, v113, v66
	v_add_f32_e32 v66, v82, v66
	v_add_f32_e32 v66, v83, v66
	v_cvt_pk_bf16_f32 v156, v110, v111
	v_cvt_pk_bf16_f32 v157, v112, v113
	ds_read_b64_tr_b16 v[78:79], v209 offset:43008
	ds_read_b64_tr_b16 v[80:81], v209 offset:43520
	v_mfma_f32_32x32x16_bf16 v[114:129], v[74:77], v[134:137], v[114:129]
	v_add_f32_e32 v66, v84, v66
	v_add_f32_e32 v66, v85, v66
	v_add_f32_e32 v66, v86, v66
	v_add_f32_e32 v66, v87, v66
	v_cvt_pk_bf16_f32 v150, v82, v83
	v_cvt_pk_bf16_f32 v151, v84, v85
	ds_read_b64_tr_b16 v[74:75], v209 offset:47104
	ds_read_b64_tr_b16 v[76:77], v209 offset:47616
	v_mfma_f32_32x32x16_bf16 v[50:65], v[174:177], v[134:137], v[50:65]
	v_add_f32_e32 v66, v88, v66
	v_add_f32_e32 v66, v89, v66
	v_add_f32_e32 v66, v90, v66
	v_add_f32_e32 v66, v91, v66
	v_cvt_pk_bf16_f32 v152, v86, v87
	v_cvt_pk_bf16_f32 v153, v88, v89
	ds_read_b64_tr_b16 v[70:71], v209 offset:44032
	ds_read_b64_tr_b16 v[72:73], v209 offset:44544
	v_mfma_f32_32x32x16_bf16 v[114:129], v[178:181], v[130:133], v[114:129]
	v_add_f32_e32 v66, v92, v66
	v_add_f32_e32 v66, v93, v66
	v_add_f32_e32 v66, v94, v66
	v_add_f32_e32 v82, v95, v66
	v_cvt_pk_bf16_f32 v146, v90, v91
	v_cvt_pk_bf16_f32 v147, v92, v93
	ds_read_b64_tr_b16 v[66:67], v209 offset:48128
	ds_read_b64_tr_b16 v[68:69], v209 offset:48640
	v_mfma_f32_32x32x16_bf16 v[50:65], v[170:173], v[130:133], v[50:65]
	v_add_f32_e32 v82, v96, v82
	v_add_f32_e32 v82, v97, v82
	v_add_f32_e32 v82, 0, v82
	v_cvt_pk_bf16_f32 v148, v94, v95
	v_cvt_pk_bf16_f32 v149, v96, v97
	s_cmp_lg_u32 0, -1
	s_mov_b64 s[18:19], 0xf8000
	s_cselect_b32 s15, 0, 0
	v_add_f32_e32 v182, v197, v82
	v_lshl_add_u64 v[82:83], v[194:195], 0, s[18:19]
	s_add_i32 s15, s15, s69
	s_add_i32 s15, s15, 0x8000
	s_mov_b32 m0, s15
	s_nop 0
	global_load_lds_dwordx4 v[82:83], off
	v_max_f32_e32 v82, v114, v115
	v_max3_f32 v83, v116, v117, v51
	v_max3_f32 v82, v82, v50, v52
	v_max3_f32 v82, v82, v53, v118
	v_max3_f32 v83, v83, v120, v121
	v_max3_f32 v82, v82, v119, v54
	v_max3_f32 v83, v83, v56, v57
	v_max3_f32 v82, v82, v55, v122
	v_max3_f32 v83, v83, v124, v125
	v_max3_f32 v82, v82, v123, v58
	v_max3_f32 v83, v83, v60, v61
	v_max3_f32 v82, v82, v59, v126
	v_max3_f32 v83, v83, v128, v129
	v_max3_f32 v82, v82, v127, v62
	v_max3_f32 v83, v83, v64, v65
	v_max3_f32 v82, v82, v63, v83
	v_mov_b32_e32 v83, v82
	s_nop 1
	v_permlane32_swap_b32_e32 v82, v83
	v_max_f32_e32 v82, v82, v83
	v_cmp_lt_f32_e32 vcc, s82, v82
	s_cmp_lg_u64 vcc, 0
	s_cselect_b64 s[60:61], -1, 0
	s_cbranch_vccnz .LBB0_2601

.LBB0_2497:
	ds_read_b64_tr_b16 v[162:163], v209 offset:24576
	ds_read_b64_tr_b16 v[164:165], v209 offset:25088
	v_mfma_f32_32x32x16_bf16 v[82:97], v[110:113], v[142:145], v[34:49]
	v_add_f32_e32 v66, v114, v115
	v_add_f32_e32 v66, v116, v66
	v_add_f32_e32 v66, v117, v66
	v_add_f32_e32 v66, v118, v66
	v_add_f32_e32 v66, v119, v66
	v_cvt_pk_bf16_f32 v158, v114, v115
	v_cvt_pk_bf16_f32 v159, v116, v117
	ds_read_b64_tr_b16 v[114:115], v209 offset:28672
	ds_read_b64_tr_b16 v[116:117], v209 offset:29184
	v_add_f32_e32 v66, v120, v66
	v_add_f32_e32 v66, v121, v66
	v_add_f32_e32 v66, v122, v66
	v_add_f32_e32 v146, v123, v66
	v_mfma_f32_32x32x16_bf16 v[66:81], v[106:109], v[142:145], v[34:49]
	v_cvt_pk_bf16_f32 v160, v118, v119
	v_cvt_pk_bf16_f32 v161, v120, v121
	ds_read_b64_tr_b16 v[110:111], v209 offset:25600
	ds_read_b64_tr_b16 v[112:113], v209 offset:26112
	v_mfma_f32_32x32x16_bf16 v[82:97], v[178:181], v[138:141], v[82:97]
	v_add_f32_e32 v106, v124, v146
	v_add_f32_e32 v106, v125, v106
	v_add_f32_e32 v106, v126, v106
	v_add_f32_e32 v118, v127, v106
	v_cvt_pk_bf16_f32 v154, v122, v123
	v_cvt_pk_bf16_f32 v155, v124, v125
	ds_read_b64_tr_b16 v[106:107], v209 offset:29696
	ds_read_b64_tr_b16 v[108:109], v209 offset:30208
	v_mfma_f32_32x32x16_bf16 v[66:81], v[102:105], v[138:141], v[66:81]
	v_add_f32_e32 v118, v128, v118
	v_add_f32_e32 v118, v129, v118
	v_add_f32_e32 v118, v50, v118
	v_add_f32_e32 v118, v51, v118
	v_cvt_pk_bf16_f32 v156, v126, v127
	v_cvt_pk_bf16_f32 v157, v128, v129
	ds_read_b64_tr_b16 v[102:103], v209 offset:26624
	ds_read_b64_tr_b16 v[104:105], v209 offset:27136
	v_mfma_f32_32x32x16_bf16 v[82:97], v[98:101], v[134:137], v[82:97]
	v_add_f32_e32 v118, v52, v118
	v_add_f32_e32 v118, v53, v118
	v_add_f32_e32 v118, v54, v118
	v_add_f32_e32 v118, v55, v118
	v_cvt_pk_bf16_f32 v150, v50, v51
	v_cvt_pk_bf16_f32 v151, v52, v53
	ds_read_b64_tr_b16 v[98:99], v209 offset:30720
	ds_read_b64_tr_b16 v[100:101], v209 offset:31232
	v_mfma_f32_32x32x16_bf16 v[66:81], v[170:173], v[134:137], v[66:81]
	v_add_f32_e32 v50, v56, v118
	v_add_f32_e32 v50, v57, v50
	v_add_f32_e32 v50, v58, v50
	v_add_f32_e32 v50, v59, v50
	v_cvt_pk_bf16_f32 v152, v54, v55
	v_cvt_pk_bf16_f32 v153, v56, v57
	ds_read_b64_tr_b16 v[54:55], v209 offset:27648
	ds_read_b64_tr_b16 v[56:57], v209 offset:28160
	v_mfma_f32_32x32x16_bf16 v[82:97], v[174:177], v[130:133], v[82:97]
	v_add_f32_e32 v50, v60, v50
	v_add_f32_e32 v50, v61, v50
	v_add_f32_e32 v50, v62, v50
	v_add_f32_e32 v118, v63, v50
	v_cvt_pk_bf16_f32 v146, v58, v59
	v_cvt_pk_bf16_f32 v147, v60, v61
	ds_read_b64_tr_b16 v[50:51], v209 offset:31744
	ds_read_b64_tr_b16 v[52:53], v209 offset:32256
	v_mfma_f32_32x32x16_bf16 v[66:81], v[166:169], v[130:133], v[66:81]
	v_add_f32_e32 v58, v64, v118
	v_add_f32_e32 v58, v65, v58
	v_add_f32_e32 v58, 0, v58
	v_cvt_pk_bf16_f32 v148, v62, v63
	v_cvt_pk_bf16_f32 v149, v64, v65
	s_cmp_lg_u32 0, -1
	s_cselect_b32 s15, 0, 0
	v_add_f32_e32 v118, v182, v58
	v_lshl_add_u64 v[58:59], v[194:195], 0, s[36:37]
	s_add_i32 s15, s15, s69
	s_add_i32 s15, s15, 0xa000
	s_mov_b32 m0, s15
	s_nop 0
	global_load_lds_dwordx4 v[58:59], off
	v_max_f32_e32 v58, v82, v83
	v_max3_f32 v59, v84, v85, v67
	v_max3_f32 v58, v58, v66, v68
	v_max3_f32 v58, v58, v69, v86
	v_max3_f32 v59, v59, v88, v89
	v_max3_f32 v58, v58, v87, v70
	v_max3_f32 v59, v59, v72, v73
	v_max3_f32 v58, v58, v71, v90
	v_max3_f32 v59, v59, v92, v93
	v_max3_f32 v58, v58, v91, v74
	v_max3_f32 v59, v59, v76, v77
	v_max3_f32 v58, v58, v75, v94
	v_max3_f32 v59, v59, v96, v97
	v_max3_f32 v58, v58, v95, v78
	v_max3_f32 v59, v59, v80, v81
	v_max3_f32 v58, v58, v79, v59
	v_mov_b32_e32 v59, v58
	s_nop 1
	v_permlane32_swap_b32_e32 v58, v59
	v_max_f32_e32 v58, v58, v59
	v_cmp_lt_f32_e32 vcc, s82, v58
	s_cmp_lg_u64 vcc, 0
	s_cselect_b64 s[60:61], -1, 0
	s_cbranch_vccnz .LBB0_2604

; __device__ __forceinline__ void kmask(f32x16&p0,f32x16&p1,int rem,int hi){
;   const float NEG=-INFINITY;
;   #pragma unroll
;   for(int r=0;r<16;++r){int kv=4*hi+(r&3)+8*(r>>2); if(kv>=rem)p0[r]=NEG; if(kv+32>=rem)p1[r]=NEG;}
; }
.LBB0_2500:
	ds_read_b64_tr_b16 v[62:63], v209 offset:32768
	ds_read_b64_tr_b16 v[64:65], v209 offset:33280
	v_mfma_f32_32x32x16_bf16 v[34:49], v[114:117], v[142:145], v[34:49]
	v_add_f32_e32 v50, v82, v83
	v_add_f32_e32 v50, v84, v50
	v_add_f32_e32 v50, v85, v50
	v_add_f32_e32 v50, v86, v50
	v_add_f32_e32 v50, v87, v50
	v_cvt_pk_bf16_f32 v158, v82, v83
	v_cvt_pk_bf16_f32 v159, v84, v85
	ds_read_b64_tr_b16 v[102:103], v209 offset:36864
	ds_read_b64_tr_b16 v[104:105], v209 offset:37376
	v_add_f32_e32 v50, v88, v50
	v_add_f32_e32 v50, v89, v50
	v_add_f32_e32 v50, v90, v50
	v_add_f32_e32 v50, v91, v50
	v_cvt_pk_bf16_f32 v160, v86, v87
	v_cvt_pk_bf16_f32 v161, v88, v89
	ds_read_b64_tr_b16 v[98:99], v209 offset:33792
	ds_read_b64_tr_b16 v[100:101], v209 offset:34304
	v_mfma_f32_32x32x16_bf16 v[34:49], v[110:113], v[138:141], v[34:49]
	v_add_f32_e32 v50, v92, v50
	v_add_f32_e32 v50, v93, v50
	v_add_f32_e32 v50, v94, v50
	v_add_f32_e32 v50, v95, v50
	v_cvt_pk_bf16_f32 v154, v90, v91
	v_cvt_pk_bf16_f32 v155, v92, v93
	ds_read_b64_tr_b16 v[90:91], v209 offset:37888
	ds_read_b64_tr_b16 v[92:93], v209 offset:38400
	v_add_f32_e32 v50, v96, v50
	v_add_f32_e32 v50, v97, v50
	v_add_f32_e32 v50, v66, v50
	v_add_f32_e32 v50, v67, v50
	v_cvt_pk_bf16_f32 v156, v94, v95
	v_cvt_pk_bf16_f32 v157, v96, v97
	ds_read_b64_tr_b16 v[86:87], v209 offset:34816
	ds_read_b64_tr_b16 v[88:89], v209 offset:35328
	v_mfma_f32_32x32x16_bf16 v[34:49], v[106:109], v[134:137], v[34:49]
	v_add_f32_e32 v50, v68, v50
	v_add_f32_e32 v50, v69, v50
	v_add_f32_e32 v50, v70, v50
	v_add_f32_e32 v50, v71, v50
	v_cvt_pk_bf16_f32 v150, v66, v67
	v_cvt_pk_bf16_f32 v151, v68, v69
	ds_read_b64_tr_b16 v[82:83], v209 offset:38912
	ds_read_b64_tr_b16 v[84:85], v209 offset:39424
	v_add_f32_e32 v50, v72, v50
	v_add_f32_e32 v50, v73, v50
	v_add_f32_e32 v50, v74, v50
	v_add_f32_e32 v50, v75, v50
	v_cvt_pk_bf16_f32 v152, v70, v71
	v_cvt_pk_bf16_f32 v153, v72, v73
	ds_read_b64_tr_b16 v[70:71], v209 offset:35840
	ds_read_b64_tr_b16 v[72:73], v209 offset:36352
	v_mfma_f32_32x32x16_bf16 v[34:49], v[58:61], v[130:133], v[34:49]
	v_add_f32_e32 v50, v76, v50
	v_add_f32_e32 v50, v77, v50
	v_add_f32_e32 v50, v78, v50
	v_add_f32_e32 v50, v79, v50
	v_cvt_pk_bf16_f32 v146, v74, v75
	v_cvt_pk_bf16_f32 v147, v76, v77
	ds_read_b64_tr_b16 v[66:67], v209 offset:39936
	ds_read_b64_tr_b16 v[68:69], v209 offset:40448
	s_nop 3
	v_add_f32_e32 v42, v80, v50
	v_add_f32_e32 v42, v81, v42
	v_add_f32_e32 v42, 0, v42
	v_cvt_pk_bf16_f32 v148, v78, v79
	v_cvt_pk_bf16_f32 v149, v80, v81
	v_max_f32_e32 v44, v37, v37
	v_max_f32_e32 v45, v36, v36
	v_add_f32_e32 v74, v118, v42
	v_mov_b32_e32 v42, 0xff800000
	v_max_f32_e32 v44, v45, v44
	v_max3_f32 v43, v34, v35, v42
	v_max3_f32 v44, v44, v42, v40
	v_max3_f32 v43, v43, v38, v39
	v_max3_f32 v44, v44, v41, v42
	v_max3_f32 v43, v43, v42, v44
	v_mov_b32_e32 v44, v43
	s_nop 1
	v_permlane32_swap_b32_e32 v43, v44
	v_max_f32_e32 v43, v43, v44
	v_cmp_lt_f32_e32 vcc, s82, v43
	s_cmp_lg_u64 vcc, 0
	s_cselect_b64 s[60:61], -1, 0
	s_cbranch_vccnz .LBB0_2607

;   #define DMA_K(t,slot) glds16(ksrc+(long)(t)*KVBLK*KP,(unsigned)__builtin_amdgcn_readfirstlane(kdst+(slot)))
;   #define DMA_V(t,slot) glds16(vsrc+(long)(t)*KVBLK*KP,(unsigned)__builtin_amdgcn_readfirstlane(vdst+(slot)))
; template<int THRL,int L,int NT> __device__ __forceinline__ void attn_unit(long rowbase,int kvh,int qblk,const bf16*Q,const bf16*__restrict__ K,const bf16*__restrict__ V,bf16*O,char*shm,const int tid){
;   const int lane=tid&63,r32=lane&31,hi=lane>>5; const int wid=__builtin_amdgcn_readfirstlane(tid>>6);
;   const int q0=qblk*64, qh=wid>>1, rh=wid&1;
;   const bf16*Qw=Q+(rowbase+q0+rh*QBLK)*QP+(4*kvh+qh)*D;
;   const bf16*Kh=K+rowbase*KP+kvh*D,*Vh=V+rowbase*KP+kvh*D;
;   const unsigned lds0=(unsigned)(uintptr_t)shm;
;   float*wsf=(float*)(shm+LDS_WS)+wid*64;
;   const bf16*ksrc=Kh+(long)lane*KP+wid*8;
;   const bf16*vsrc=Vh+(long)(16*(wid&3)+(lane>>2))*KP+(wid>>2)*32+(lane&3)*8;
;   const unsigned kdst=lds0+LDS_K+wid*1024, vdst=lds0+LDS_V+wid*1024;
;     ...
;   const int vb0=(int)(lds0+LDS_V)+((lane>>4)&1)*32+(lane&3)*8+(4*hi+((lane&15)>>2))*64;
;   const char*Kbase=shm+LDS_K; bf16x8 kf[8];
;   const lds_cptr shm3=(lds_cptr)shm; const lds_cptr kp0=shm3+LDS_K+hi*1024+r32*16; const lds_cptr vp0=shm3+LDS_V+((lane>>4)&1)*32+(lane&3)*8+(4*hi+((lane&15)>>2))*64;
;   DMA_K(0,0);DMA_V(0,0);DMA_K(1,SLOTB);
;   bf16x8 qr[4];
;   #pragma unroll
;   for(int d0=0;d0<4;++d0)qr[d0]=*reinterpret_cast<const bf16x8*>(&Qw[(long)r32*QP+d0*16+hi*8]);
;   if(q0+rh*QBLK+r32>=L){
;     #pragma unroll
;     for(int d0=0;d0<4;++d0)qr[d0]=bf16x8{0,0,0,0,0,0,0,0}; }
; __device__ __forceinline__ void attention_phase(const PT a, unsigned char* ws, int l, unsigned char* lds_generic, int tid, bool dry = false) {
;     ...
;         if (u < ATT_UNITS_P) { const int s = u / 260, rem = u - s * 260, kvh = rem / 65, qblk = rem - kvh * 65;
;             attn_body::attn_unit<8, LP, 65>((long)s * LP, kvh, qblk, Q, K, V, O, (char*)lds_generic, tidu); }
.LBB0_2514:
	s_and_b64 vcc, exec, s[4:5]
	s_cbranch_vccz .LBB0_2555
	s_mul_hi_i32 s4, s66, 0x7e07e07f
	s_lshr_b32 s5, s4, 31
	s_ashr_i32 s4, s4, 7
	s_add_i32 s97, s4, s5
	s_mul_i32 s4, s97, 0xfffffefc
	s_add_i32 s4, s4, s66
	s_mul_hi_i32 s5, s4, 0x7e07e07f
	s_lshr_b32 s15, s5, 31
	s_ashr_i32 s5, s5, 5
	s_add_i32 s18, s5, s15
	s_mul_i32 s5, s18, 0xffffffbf
	s_add_i32 s5, s5, s4
	v_readfirstlane_b32 s15, v204
	s_lshl_b32 s66, s5, 6
	s_mul_i32 s19, s97, 0x1010
	s_ashr_i32 s67, s15, 6
	s_ashr_i32 s5, s66, 31
	s_mul_hi_i32 s4, s97, 0x1010
	s_add_u32 s19, s19, s66
	s_addc_u32 s5, s4, s5
	s_lshl_b32 s4, s67, 5
	s_and_b32 s92, s4, 32
	s_add_u32 s4, s19, s92
	s_addc_u32 s5, s5, 0
	s_lshl_b64 s[4:5], s[4:5], 11
	s_add_u32 s19, s6, s4
	s_addc_u32 s59, s71, s5
	s_ashr_i32 s5, s15, 1
	s_lshl_b32 s4, s18, 8
	s_andn2_b32 s5, s5, 63
	s_add_i32 s4, s5, s4
	s_ashr_i32 s5, s4, 31
	s_lshl_b64 s[4:5], s[4:5], 1
	s_add_u32 s58, s19, s4
	s_addc_u32 s59, s59, s5
	s_mul_hi_i32 s96, s97, 0x202000
	s_mul_i32 s97, s97, 0x202000
	s_add_u32 s19, s72, s97
	s_addc_u32 s62, s73, s96
	s_lshl_b32 s4, s18, 6
	s_ashr_i32 s5, s4, 31
	s_lshl_b64 s[60:61], s[4:5], 1
	s_add_u32 s4, s19, s60
	s_addc_u32 s5, s62, s61
	s_add_u32 s18, s74, s97
	s_addc_u32 s19, s75, s96
	s_add_u32 s18, s18, s60
	s_addc_u32 s19, s19, s61
	s_lshl_b32 s62, s67, 3
	v_lshl_add_u64 v[2:3], s[4:5], 0, v[192:193]
	s_ashr_i32 s63, s62, 31
	s_lshl_b32 s4, s67, 4
	v_lshl_add_u64 v[186:187], s[62:63], 1, v[2:3]
	v_and_or_b32 v2, s4, 48, v203
	s_ashr_i32 s4, s15, 3
	s_and_b32 s64, s4, 0xffffffe0
	s_ashr_i32 s65, s64, 31
	s_lshl_b32 s68, s67, 10
	v_lshlrev_b32_e32 v2, 9, v2
	v_mov_b32_e32 v3, v193
	s_cmp_lg_u32 0, -1
	v_lshl_add_u64 v[2:3], s[18:19], 0, v[2:3]
	s_cselect_b32 s4, 0, 0
	v_lshl_add_u64 v[2:3], s[64:65], 1, v[2:3]
	v_lshlrev_b32_e32 v4, 1, v202
	v_mov_b32_e32 v5, v193
	s_add_i32 s93, s68, s4
	s_mov_b32 m0, s93
	s_nop 0
	global_load_lds_dwordx4 v[186:187], off
	v_lshl_add_u64 v[194:195], v[2:3], 0, v[4:5]
	s_add_i32 s69, s93, 0x6000
	s_mov_b32 m0, s69
	s_nop 0
	global_load_lds_dwordx4 v[194:195], off
	v_lshl_add_u64 v[2:3], v[186:187], 0, s[26:27]
	s_add_i32 s4, s93, 0x2000
	s_mov_b32 m0, s4
	s_nop 0
	global_load_lds_dwordx4 v[2:3], off
	v_lshl_or_b32 v2, v201, 4, v205
	global_load_dwordx4 v[142:145], v2, s[58:59]
	global_load_dwordx4 v[138:141], v2, s[58:59] offset:32
	global_load_dwordx4 v[134:137], v2, s[58:59] offset:64
	global_load_dwordx4 v[130:133], v2, s[58:59] offset:96
	s_or_b32 s66, s92, s66
	v_or_b32_e32 v2, s66, v200
	s_movk_i32 s4, 0x100f
	v_cmp_lt_i32_e32 vcc, s4, v2
	s_and_saveexec_b64 s[4:5], vcc
	s_cbranch_execz .LBB0_2517
	s_waitcnt vmcnt(3)
	v_mov_b32_e32 v142, 0
	v_mov_b32_e32 v143, v142
	v_mov_b32_e32 v144, v142
	v_mov_b32_e32 v145, v142
	s_waitcnt vmcnt(2)
	v_mov_b32_e32 v138, v142
	v_mov_b32_e32 v139, v142
	v_mov_b32_e32 v140, v142
	v_mov_b32_e32 v141, v142
	s_waitcnt vmcnt(1)
	v_mov_b32_e32 v134, v142
	v_mov_b32_e32 v135, v142
	v_mov_b32_e32 v136, v142
	v_mov_b32_e32 v137, v142
	s_waitcnt vmcnt(0)
	v_mov_b32_e32 v130, v142
	v_mov_b32_e32 v131, v142
	v_mov_b32_e32 v132, v142
	v_mov_b32_e32 v133, v142

.LBB0_2518:
	v_add_u32_e32 v183, s18, v208
	ds_read_b64_tr_b16 v[178:179], v183 offset:24576
	ds_read_b64_tr_b16 v[180:181], v183 offset:25088
	v_mfma_f32_32x32x16_bf16 v[98:113], v[82:85], v[142:145], v[34:49]
	v_add_f32_e32 v86, v66, v67
	v_add_f32_e32 v86, v68, v86
	v_add_f32_e32 v86, v69, v86
	v_add_f32_e32 v86, v70, v86
	v_add_f32_e32 v86, v71, v86
	v_cvt_pk_bf16_f32 v158, v66, v67
	v_cvt_pk_bf16_f32 v159, v68, v69
	ds_read_b64_tr_b16 v[174:175], v183 offset:28672
	ds_read_b64_tr_b16 v[176:177], v183 offset:29184
	v_add_f32_e32 v66, v72, v86
	v_mfma_f32_32x32x16_bf16 v[82:97], v[170:173], v[142:145], v[34:49]
	v_add_f32_e32 v66, v73, v66
	v_add_f32_e32 v66, v74, v66
	v_add_f32_e32 v66, v75, v66
	v_cvt_pk_bf16_f32 v160, v70, v71
	v_cvt_pk_bf16_f32 v161, v72, v73
	ds_read_b64_tr_b16 v[170:171], v183 offset:25600
	ds_read_b64_tr_b16 v[172:173], v183 offset:26112
	v_mfma_f32_32x32x16_bf16 v[98:113], v[166:169], v[138:141], v[98:113]
	v_add_f32_e32 v66, v76, v66
	v_add_f32_e32 v66, v77, v66
	v_add_f32_e32 v66, v78, v66
	v_add_f32_e32 v66, v79, v66
	v_cvt_pk_bf16_f32 v154, v74, v75
	v_cvt_pk_bf16_f32 v155, v76, v77
	ds_read_b64_tr_b16 v[74:75], v183 offset:29696
	ds_read_b64_tr_b16 v[76:77], v183 offset:30208
	v_mfma_f32_32x32x16_bf16 v[82:97], v[162:165], v[138:141], v[82:97]
	v_add_f32_e32 v66, v80, v66
	v_add_f32_e32 v66, v81, v66
	v_add_f32_e32 v66, v50, v66
	v_add_f32_e32 v66, v51, v66
	v_cvt_pk_bf16_f32 v156, v78, v79
	v_cvt_pk_bf16_f32 v157, v80, v81
	ds_read_b64_tr_b16 v[70:71], v183 offset:26624
	ds_read_b64_tr_b16 v[72:73], v183 offset:27136
	v_mfma_f32_32x32x16_bf16 v[98:113], v[126:129], v[134:137], v[98:113]
	v_add_f32_e32 v66, v52, v66
	v_add_f32_e32 v66, v53, v66
	v_add_f32_e32 v66, v54, v66
	v_add_f32_e32 v78, v55, v66
	v_cvt_pk_bf16_f32 v150, v50, v51
	v_cvt_pk_bf16_f32 v151, v52, v53
	ds_read_b64_tr_b16 v[66:67], v183 offset:30720
	ds_read_b64_tr_b16 v[68:69], v183 offset:31232
	v_mfma_f32_32x32x16_bf16 v[82:97], v[122:125], v[134:137], v[82:97]
	v_add_f32_e32 v50, v56, v78
	v_add_f32_e32 v50, v57, v50
	v_add_f32_e32 v50, v58, v50
	v_add_f32_e32 v50, v59, v50
	v_cvt_pk_bf16_f32 v152, v54, v55
	v_cvt_pk_bf16_f32 v153, v56, v57
	ds_read_b64_tr_b16 v[54:55], v183 offset:27648
	ds_read_b64_tr_b16 v[56:57], v183 offset:28160
	v_mfma_f32_32x32x16_bf16 v[98:113], v[118:121], v[130:133], v[98:113]
	v_add_f32_e32 v50, v60, v50
	v_add_f32_e32 v50, v61, v50
	v_add_f32_e32 v50, v62, v50
	v_add_f32_e32 v78, v63, v50
	v_cvt_pk_bf16_f32 v146, v58, v59
	v_cvt_pk_bf16_f32 v147, v60, v61
	ds_read_b64_tr_b16 v[50:51], v183 offset:31744
	ds_read_b64_tr_b16 v[52:53], v183 offset:32256
	v_mfma_f32_32x32x16_bf16 v[82:97], v[114:117], v[130:133], v[82:97]
	v_add_f32_e32 v58, v64, v78
	v_add_f32_e32 v58, v65, v58
	v_add_f32_e32 v60, 0, v58
	v_cvt_pk_bf16_f32 v148, v62, v63
	v_cvt_pk_bf16_f32 v149, v64, v65
	v_lshl_add_u64 v[58:59], v[196:197], 0, s[30:31]
	s_add_i32 s15, s64, s93
	s_mov_b32 m0, s15
	s_nop 0
	global_load_lds_dwordx4 v[58:59], off
	v_lshl_add_u64 v[58:59], v[188:189], 0, s[26:27]
	s_add_i32 s15, s95, s69
	s_mov_b32 m0, s15
	s_nop 0
	global_load_lds_dwordx4 v[58:59], off
	v_max_f32_e32 v58, v98, v99
	v_max3_f32 v59, v100, v101, v83
	v_max3_f32 v58, v58, v82, v84
	v_max3_f32 v58, v58, v85, v102
	v_max3_f32 v59, v59, v104, v105
	v_max3_f32 v58, v58, v103, v86
	v_max3_f32 v59, v59, v88, v89
	v_max3_f32 v58, v58, v87, v106
	v_max3_f32 v59, v59, v108, v109
	v_max3_f32 v58, v58, v107, v90
	v_max3_f32 v59, v59, v92, v93
	v_max3_f32 v58, v58, v91, v110
	v_max3_f32 v59, v59, v112, v113
	v_max3_f32 v58, v58, v111, v94
	v_max3_f32 v59, v59, v96, v97
	v_max3_f32 v58, v58, v95, v59
	v_mov_b32_e32 v59, v58
	s_nop 1
	v_permlane32_swap_b32_e32 v58, v59
	v_max_f32_e32 v58, v58, v59
	v_cmp_lt_f32_e32 vcc, s82, v58
	s_cmp_lg_u64 vcc, 0
	v_add_f32_e32 v192, v182, v60
	s_cselect_b64 s[60:61], -1, 0
	s_cbranch_vccnz .LBB0_2526

.LBB0_2521:
	s_add_i32 s15, s95, 0x2000
	s_cmpk_lg_i32 s95, 0x4000
	s_cselect_b32 s65, s15, 0
	v_add_u32_e32 v203, s64, v208
	ds_read_b64_tr_b16 v[126:127], v203 offset:24576
	ds_read_b64_tr_b16 v[128:129], v203 offset:25088
	v_mfma_f32_32x32x16_bf16 v[66:81], v[58:61], v[142:145], v[34:49]
	v_add_f32_e32 v50, v98, v99
	v_add_f32_e32 v50, v100, v50
	v_add_f32_e32 v50, v101, v50
	v_add_f32_e32 v50, v102, v50
	v_add_f32_e32 v50, v103, v50
	v_cvt_pk_bf16_f32 v158, v98, v99
	v_cvt_pk_bf16_f32 v159, v100, v101
	ds_read_b64_tr_b16 v[122:123], v203 offset:28672
	ds_read_b64_tr_b16 v[124:125], v203 offset:29184
	v_add_f32_e32 v50, v104, v50
	v_add_f32_e32 v50, v105, v50
	v_add_f32_e32 v50, v106, v50
	v_add_f32_e32 v98, v107, v50
	v_mfma_f32_32x32x16_bf16 v[50:65], v[114:117], v[142:145], v[34:49]
	v_cvt_pk_bf16_f32 v160, v102, v103
	v_cvt_pk_bf16_f32 v161, v104, v105
	ds_read_b64_tr_b16 v[118:119], v203 offset:25600
	ds_read_b64_tr_b16 v[120:121], v203 offset:26112
	v_mfma_f32_32x32x16_bf16 v[66:81], v[182:185], v[138:141], v[66:81]
	v_add_f32_e32 v98, v108, v98
	v_add_f32_e32 v98, v109, v98
	v_add_f32_e32 v98, v110, v98
	v_add_f32_e32 v98, v111, v98
	v_cvt_pk_bf16_f32 v154, v106, v107
	v_cvt_pk_bf16_f32 v155, v108, v109
	ds_read_b64_tr_b16 v[114:115], v203 offset:29696
	ds_read_b64_tr_b16 v[116:117], v203 offset:30208
	v_mfma_f32_32x32x16_bf16 v[50:65], v[174:177], v[138:141], v[50:65]
	v_add_f32_e32 v98, v112, v98
	v_add_f32_e32 v98, v113, v98
	v_add_f32_e32 v98, v82, v98
	v_add_f32_e32 v98, v83, v98
	v_cvt_pk_bf16_f32 v156, v110, v111
	v_cvt_pk_bf16_f32 v157, v112, v113
	ds_read_b64_tr_b16 v[106:107], v203 offset:26624
	ds_read_b64_tr_b16 v[108:109], v203 offset:27136
	v_mfma_f32_32x32x16_bf16 v[66:81], v[178:181], v[134:137], v[66:81]
	v_add_f32_e32 v98, v84, v98
	v_add_f32_e32 v98, v85, v98
	v_add_f32_e32 v98, v86, v98
	v_add_f32_e32 v98, v87, v98
	v_cvt_pk_bf16_f32 v150, v82, v83
	v_cvt_pk_bf16_f32 v151, v84, v85
	ds_read_b64_tr_b16 v[102:103], v203 offset:30720
	ds_read_b64_tr_b16 v[104:105], v203 offset:31232
	v_mfma_f32_32x32x16_bf16 v[50:65], v[166:169], v[134:137], v[50:65]
	v_add_f32_e32 v82, v88, v98
	v_add_f32_e32 v82, v89, v82
	v_add_f32_e32 v82, v90, v82
	v_add_f32_e32 v82, v91, v82
	v_cvt_pk_bf16_f32 v152, v86, v87
	v_cvt_pk_bf16_f32 v153, v88, v89
	ds_read_b64_tr_b16 v[98:99], v203 offset:27648
	ds_read_b64_tr_b16 v[100:101], v203 offset:28160
	v_mfma_f32_32x32x16_bf16 v[66:81], v[170:173], v[130:133], v[66:81]
	v_add_f32_e32 v82, v92, v82
	v_add_f32_e32 v82, v93, v82
	v_add_f32_e32 v82, v94, v82
	v_add_f32_e32 v82, v95, v82
	v_cvt_pk_bf16_f32 v146, v90, v91
	v_cvt_pk_bf16_f32 v147, v92, v93
	ds_read_b64_tr_b16 v[86:87], v203 offset:31744
	ds_read_b64_tr_b16 v[88:89], v203 offset:32256
	v_mfma_f32_32x32x16_bf16 v[50:65], v[162:165], v[130:133], v[50:65]
	v_add_f32_e32 v82, v96, v82
	v_add_f32_e32 v82, v97, v82
	v_add_f32_e32 v84, 0, v82
	v_cvt_pk_bf16_f32 v148, v94, v95
	v_cvt_pk_bf16_f32 v149, v96, v97
	v_lshl_add_u64 v[82:83], v[196:197], 0, s[34:35]
	s_add_i32 s15, s95, s93
	s_mov_b32 m0, s15
	s_nop 0
	global_load_lds_dwordx4 v[82:83], off
	v_max_f32_e32 v82, v66, v67
	s_nop 1
	v_max3_f32 v83, v68, v69, v51
	v_max3_f32 v82, v82, v50, v52
	v_max3_f32 v82, v82, v53, v70
	v_max3_f32 v83, v83, v72, v73
	v_max3_f32 v82, v82, v71, v54
	v_max3_f32 v83, v83, v56, v57
	v_max3_f32 v82, v82, v55, v74
	v_max3_f32 v83, v83, v76, v77
	v_max3_f32 v82, v82, v75, v58
	v_max3_f32 v83, v83, v60, v61
	v_max3_f32 v82, v82, v59, v78
	v_max3_f32 v83, v83, v80, v81
	v_max3_f32 v82, v82, v79, v62
	v_max3_f32 v83, v83, v64, v65
	v_max3_f32 v82, v82, v63, v83
	v_mov_b32_e32 v83, v82
	s_nop 1
	v_permlane32_swap_b32_e32 v82, v83
	v_max_f32_e32 v82, v82, v83
	v_lshl_add_u64 v[188:189], v[188:189], 0, s[28:29]
	s_add_i32 s15, s65, s69
	s_mov_b32 m0, s15
	s_nop 0
	global_load_lds_dwordx4 v[188:189], off
	v_cmp_lt_f32_e32 vcc, s82, v82
	s_cmp_lg_u64 vcc, 0
	v_add_f32_e32 v182, v192, v84
	s_cselect_b64 s[60:61], -1, 0
	s_cbranch_vccnz .LBB0_2529

.LBB0_2532:
	ds_read_b64_tr_b16 v[178:179], v208 offset:24576
	ds_read_b64_tr_b16 v[180:181], v208 offset:25088
	s_waitcnt lgkmcnt(9)
	v_mfma_f32_32x32x16_bf16 v[98:113], v[82:85], v[142:145], v[34:49]
	v_add_f32_e32 v86, v66, v67
	v_add_f32_e32 v86, v68, v86
	v_add_f32_e32 v86, v69, v86
	v_add_f32_e32 v86, v70, v86
	v_add_f32_e32 v86, v71, v86
	v_cvt_pk_bf16_f32 v158, v66, v67
	v_cvt_pk_bf16_f32 v159, v68, v69
	ds_read_b64_tr_b16 v[174:175], v208 offset:28672
	ds_read_b64_tr_b16 v[176:177], v208 offset:29184
	v_add_f32_e32 v66, v72, v86
	s_waitcnt lgkmcnt(10)
	v_mfma_f32_32x32x16_bf16 v[82:97], v[170:173], v[142:145], v[34:49]
	v_add_f32_e32 v66, v73, v66
	v_add_f32_e32 v66, v74, v66
	v_add_f32_e32 v66, v75, v66
	v_cvt_pk_bf16_f32 v160, v70, v71
	v_cvt_pk_bf16_f32 v161, v72, v73
	ds_read_b64_tr_b16 v[170:171], v208 offset:25600
	ds_read_b64_tr_b16 v[172:173], v208 offset:26112
	s_waitcnt lgkmcnt(11)
	v_mfma_f32_32x32x16_bf16 v[98:113], v[166:169], v[138:141], v[98:113]
	v_add_f32_e32 v66, v76, v66
	v_add_f32_e32 v66, v77, v66
	v_add_f32_e32 v66, v78, v66
	v_add_f32_e32 v66, v79, v66
	v_cvt_pk_bf16_f32 v154, v74, v75
	v_cvt_pk_bf16_f32 v155, v76, v77
	ds_read_b64_tr_b16 v[74:75], v208 offset:29696
	ds_read_b64_tr_b16 v[76:77], v208 offset:30208
	s_waitcnt lgkmcnt(12)
	v_mfma_f32_32x32x16_bf16 v[82:97], v[162:165], v[138:141], v[82:97]
	v_add_f32_e32 v66, v80, v66
	v_add_f32_e32 v66, v81, v66
	v_add_f32_e32 v66, v50, v66
	v_add_f32_e32 v66, v51, v66
	v_cvt_pk_bf16_f32 v156, v78, v79
	v_cvt_pk_bf16_f32 v157, v80, v81
	ds_read_b64_tr_b16 v[70:71], v208 offset:26624
	ds_read_b64_tr_b16 v[72:73], v208 offset:27136
	s_waitcnt lgkmcnt(13)
	v_mfma_f32_32x32x16_bf16 v[98:113], v[126:129], v[134:137], v[98:113]
	v_add_f32_e32 v66, v52, v66
	v_add_f32_e32 v66, v53, v66
	v_add_f32_e32 v66, v54, v66
	v_add_f32_e32 v78, v55, v66
	v_cvt_pk_bf16_f32 v150, v50, v51
	v_cvt_pk_bf16_f32 v151, v52, v53
	ds_read_b64_tr_b16 v[66:67], v208 offset:30720
	ds_read_b64_tr_b16 v[68:69], v208 offset:31232
	s_waitcnt lgkmcnt(14)
	v_mfma_f32_32x32x16_bf16 v[82:97], v[122:125], v[134:137], v[82:97]
	v_add_f32_e32 v50, v56, v78
	v_add_f32_e32 v50, v57, v50
	v_add_f32_e32 v50, v58, v50
	v_add_f32_e32 v50, v59, v50
	v_cvt_pk_bf16_f32 v152, v54, v55
	v_cvt_pk_bf16_f32 v153, v56, v57
	ds_read_b64_tr_b16 v[54:55], v208 offset:27648
	ds_read_b64_tr_b16 v[56:57], v208 offset:28160
	s_waitcnt lgkmcnt(14)
	v_mfma_f32_32x32x16_bf16 v[98:113], v[118:121], v[130:133], v[98:113]
	v_add_f32_e32 v50, v60, v50
	v_add_f32_e32 v50, v61, v50
	v_add_f32_e32 v50, v62, v50
	v_add_f32_e32 v78, v63, v50
	v_cvt_pk_bf16_f32 v146, v58, v59
	v_cvt_pk_bf16_f32 v147, v60, v61
	ds_read_b64_tr_b16 v[50:51], v208 offset:31744
	ds_read_b64_tr_b16 v[52:53], v208 offset:32256
	v_mfma_f32_32x32x16_bf16 v[82:97], v[114:117], v[130:133], v[82:97]
	v_add_f32_e32 v58, v64, v78
	v_add_f32_e32 v58, v65, v58
	v_add_f32_e32 v58, 0, v58
	v_cvt_pk_bf16_f32 v148, v62, v63
	v_cvt_pk_bf16_f32 v149, v64, v65
	s_cmp_lg_u32 0, -1
	s_cselect_b32 s15, 0, 0
	v_add_f32_e32 v196, v182, v58
	v_lshl_add_u64 v[58:59], v[186:187], 0, s[38:39]
	s_add_i32 s15, s15, s68
	s_add_i32 s18, s15, 0x2000
	s_mov_b32 m0, s18
	s_nop 0
	global_load_lds_dwordx4 v[58:59], off
	v_lshl_add_u64 v[58:59], v[194:195], 0, s[40:41]
	s_add_i32 s15, s15, 0xa000
	s_mov_b32 m0, s15
	s_nop 0
	global_load_lds_dwordx4 v[58:59], off
	v_max_f32_e32 v58, v98, v99
	v_max3_f32 v59, v100, v101, v83
	v_max3_f32 v58, v58, v82, v84
	v_max3_f32 v58, v58, v85, v102
	v_max3_f32 v59, v59, v104, v105
	v_max3_f32 v58, v58, v103, v86
	v_max3_f32 v59, v59, v88, v89
	v_max3_f32 v58, v58, v87, v106
	v_max3_f32 v59, v59, v108, v109
	v_max3_f32 v58, v58, v107, v90
	v_max3_f32 v59, v59, v92, v93
	v_max3_f32 v58, v58, v91, v110
	v_max3_f32 v59, v59, v112, v113
	v_max3_f32 v58, v58, v111, v94
	v_max3_f32 v59, v59, v96, v97
	v_max3_f32 v58, v58, v95, v59
	v_mov_b32_e32 v59, v58
	s_nop 1
	v_permlane32_swap_b32_e32 v58, v59
	v_max_f32_e32 v58, v58, v59
	v_cmp_lt_f32_e32 vcc, s82, v58
	s_cmp_lg_u64 vcc, 0
	s_cselect_b64 s[60:61], -1, 0
	s_cbranch_vccnz .LBB0_2610

.LBB0_2535:
	ds_read_b64_tr_b16 v[166:167], v208 offset:32768
	ds_read_b64_tr_b16 v[168:169], v208 offset:33280
	v_mfma_f32_32x32x16_bf16 v[114:129], v[58:61], v[142:145], v[34:49]
	v_add_f32_e32 v50, v98, v99
	v_add_f32_e32 v50, v100, v50
	v_add_f32_e32 v50, v101, v50
	v_add_f32_e32 v50, v102, v50
	v_add_f32_e32 v50, v103, v50
	v_cvt_pk_bf16_f32 v158, v98, v99
	v_cvt_pk_bf16_f32 v159, v100, v101
	ds_read_b64_tr_b16 v[162:163], v208 offset:36864
	ds_read_b64_tr_b16 v[164:165], v208 offset:37376
	v_add_f32_e32 v50, v104, v50
	v_add_f32_e32 v50, v105, v50
	v_add_f32_e32 v50, v106, v50
	v_add_f32_e32 v66, v107, v50
	v_mfma_f32_32x32x16_bf16 v[50:65], v[182:185], v[142:145], v[34:49]
	v_cvt_pk_bf16_f32 v160, v102, v103
	v_cvt_pk_bf16_f32 v161, v104, v105
	ds_read_b64_tr_b16 v[102:103], v208 offset:33792
	ds_read_b64_tr_b16 v[104:105], v208 offset:34304
	v_mfma_f32_32x32x16_bf16 v[114:129], v[186:189], v[138:141], v[114:129]
	v_add_f32_e32 v66, v108, v66
	v_add_f32_e32 v66, v109, v66
	v_add_f32_e32 v66, v110, v66
	v_add_f32_e32 v66, v111, v66
	v_cvt_pk_bf16_f32 v154, v106, v107
	v_cvt_pk_bf16_f32 v155, v108, v109
	ds_read_b64_tr_b16 v[98:99], v208 offset:37888
	ds_read_b64_tr_b16 v[100:101], v208 offset:38400
	v_mfma_f32_32x32x16_bf16 v[50:65], v[78:81], v[138:141], v[50:65]
	v_add_f32_e32 v66, v112, v66
	v_add_f32_e32 v66, v113, v66
	v_add_f32_e32 v66, v82, v66
	v_add_f32_e32 v66, v83, v66
	v_cvt_pk_bf16_f32 v156, v110, v111
	v_cvt_pk_bf16_f32 v157, v112, v113
	ds_read_b64_tr_b16 v[78:79], v208 offset:34816
	ds_read_b64_tr_b16 v[80:81], v208 offset:35328
	v_mfma_f32_32x32x16_bf16 v[114:129], v[74:77], v[134:137], v[114:129]
	v_add_f32_e32 v66, v84, v66
	v_add_f32_e32 v66, v85, v66
	v_add_f32_e32 v66, v86, v66
	v_add_f32_e32 v66, v87, v66
	v_cvt_pk_bf16_f32 v150, v82, v83
	v_cvt_pk_bf16_f32 v151, v84, v85
	ds_read_b64_tr_b16 v[74:75], v208 offset:38912
	ds_read_b64_tr_b16 v[76:77], v208 offset:39424
	v_mfma_f32_32x32x16_bf16 v[50:65], v[174:177], v[134:137], v[50:65]
	v_add_f32_e32 v66, v88, v66
	v_add_f32_e32 v66, v89, v66
	v_add_f32_e32 v66, v90, v66
	v_add_f32_e32 v66, v91, v66
	v_cvt_pk_bf16_f32 v152, v86, v87
	v_cvt_pk_bf16_f32 v153, v88, v89
	ds_read_b64_tr_b16 v[70:71], v208 offset:35840
	ds_read_b64_tr_b16 v[72:73], v208 offset:36352
	v_mfma_f32_32x32x16_bf16 v[114:129], v[178:181], v[130:133], v[114:129]
	v_add_f32_e32 v66, v92, v66
	v_add_f32_e32 v66, v93, v66
	v_add_f32_e32 v66, v94, v66
	v_add_f32_e32 v82, v95, v66
	v_cvt_pk_bf16_f32 v146, v90, v91
	v_cvt_pk_bf16_f32 v147, v92, v93
	ds_read_b64_tr_b16 v[66:67], v208 offset:39936
	ds_read_b64_tr_b16 v[68:69], v208 offset:40448
	v_mfma_f32_32x32x16_bf16 v[50:65], v[170:173], v[130:133], v[50:65]
	v_add_f32_e32 v82, v96, v82
	v_add_f32_e32 v82, v97, v82
	v_add_f32_e32 v82, 0, v82
	v_cvt_pk_bf16_f32 v148, v94, v95
	v_cvt_pk_bf16_f32 v149, v96, v97
	s_nop 0
	v_add_f32_e32 v182, v196, v82
	v_lshl_add_u64 v[82:83], v[194:195], 0, s[42:43]
	s_mov_b32 m0, s69
	s_nop 0
	global_load_lds_dwordx4 v[82:83], off
	v_max_f32_e32 v82, v114, v115
	s_nop 0
	v_max3_f32 v83, v116, v117, v51
	v_max3_f32 v82, v82, v50, v52
	v_max3_f32 v82, v82, v53, v118
	v_max3_f32 v83, v83, v120, v121
	v_max3_f32 v82, v82, v119, v54
	v_max3_f32 v83, v83, v56, v57
	v_max3_f32 v82, v82, v55, v122
	v_max3_f32 v83, v83, v124, v125
	v_max3_f32 v82, v82, v123, v58
	v_max3_f32 v83, v83, v60, v61
	v_max3_f32 v82, v82, v59, v126
	v_max3_f32 v83, v83, v128, v129
	v_max3_f32 v82, v82, v127, v62
	v_max3_f32 v83, v83, v64, v65
	v_max3_f32 v82, v82, v63, v83
	v_mov_b32_e32 v83, v82
	s_nop 1
	v_permlane32_swap_b32_e32 v82, v83
	v_max_f32_e32 v82, v82, v83
	v_cmp_lt_f32_e32 vcc, s82, v82
	s_cmp_lg_u64 vcc, 0
	s_cselect_b64 s[60:61], -1, 0
	s_cbranch_vccnz .LBB0_2613

.LBB0_2538:
	ds_read_b64_tr_b16 v[162:163], v208 offset:40960
	ds_read_b64_tr_b16 v[164:165], v208 offset:41472
	v_mfma_f32_32x32x16_bf16 v[82:97], v[110:113], v[142:145], v[34:49]
	v_add_f32_e32 v66, v114, v115
	v_add_f32_e32 v66, v116, v66
	v_add_f32_e32 v66, v117, v66
	v_add_f32_e32 v66, v118, v66
	v_add_f32_e32 v66, v119, v66
	v_cvt_pk_bf16_f32 v158, v114, v115
	v_cvt_pk_bf16_f32 v159, v116, v117
	ds_read_b64_tr_b16 v[114:115], v208 offset:45056
	ds_read_b64_tr_b16 v[116:117], v208 offset:45568
	v_add_f32_e32 v66, v120, v66
	v_add_f32_e32 v66, v121, v66
	v_add_f32_e32 v66, v122, v66
	v_add_f32_e32 v146, v123, v66
	v_mfma_f32_32x32x16_bf16 v[66:81], v[106:109], v[142:145], v[34:49]
	v_cvt_pk_bf16_f32 v160, v118, v119
	v_cvt_pk_bf16_f32 v161, v120, v121
	ds_read_b64_tr_b16 v[110:111], v208 offset:41984
	ds_read_b64_tr_b16 v[112:113], v208 offset:42496
	v_mfma_f32_32x32x16_bf16 v[82:97], v[178:181], v[138:141], v[82:97]
	v_add_f32_e32 v106, v124, v146
	v_add_f32_e32 v106, v125, v106
	v_add_f32_e32 v106, v126, v106
	v_add_f32_e32 v118, v127, v106
	v_cvt_pk_bf16_f32 v154, v122, v123
	v_cvt_pk_bf16_f32 v155, v124, v125
	ds_read_b64_tr_b16 v[106:107], v208 offset:46080
	ds_read_b64_tr_b16 v[108:109], v208 offset:46592
	v_mfma_f32_32x32x16_bf16 v[66:81], v[102:105], v[138:141], v[66:81]
	v_add_f32_e32 v118, v128, v118
	v_add_f32_e32 v118, v129, v118
	v_add_f32_e32 v118, v50, v118
	v_add_f32_e32 v118, v51, v118
	v_cvt_pk_bf16_f32 v156, v126, v127
	v_cvt_pk_bf16_f32 v157, v128, v129
	ds_read_b64_tr_b16 v[102:103], v208 offset:43008
	ds_read_b64_tr_b16 v[104:105], v208 offset:43520
	v_mfma_f32_32x32x16_bf16 v[82:97], v[98:101], v[134:137], v[82:97]
	v_add_f32_e32 v118, v52, v118
	v_add_f32_e32 v118, v53, v118
	v_add_f32_e32 v118, v54, v118
	v_add_f32_e32 v118, v55, v118
	v_cvt_pk_bf16_f32 v150, v50, v51
	v_cvt_pk_bf16_f32 v151, v52, v53
	ds_read_b64_tr_b16 v[98:99], v208 offset:47104
	ds_read_b64_tr_b16 v[100:101], v208 offset:47616
	v_mfma_f32_32x32x16_bf16 v[66:81], v[170:173], v[134:137], v[66:81]
	v_add_f32_e32 v50, v56, v118
	v_add_f32_e32 v50, v57, v50
	v_add_f32_e32 v50, v58, v50
	v_add_f32_e32 v50, v59, v50
	v_cvt_pk_bf16_f32 v152, v54, v55
	v_cvt_pk_bf16_f32 v153, v56, v57
	ds_read_b64_tr_b16 v[54:55], v208 offset:44032
	ds_read_b64_tr_b16 v[56:57], v208 offset:44544
	v_mfma_f32_32x32x16_bf16 v[82:97], v[174:177], v[130:133], v[82:97]
	v_add_f32_e32 v50, v60, v50
	v_add_f32_e32 v50, v61, v50
	v_add_f32_e32 v50, v62, v50
	v_add_f32_e32 v118, v63, v50
	v_cvt_pk_bf16_f32 v146, v58, v59
	v_cvt_pk_bf16_f32 v147, v60, v61
	ds_read_b64_tr_b16 v[50:51], v208 offset:48128
	ds_read_b64_tr_b16 v[52:53], v208 offset:48640
	v_mfma_f32_32x32x16_bf16 v[66:81], v[166:169], v[130:133], v[66:81]
	v_add_f32_e32 v58, v64, v118
	v_add_f32_e32 v58, v65, v58
	v_add_f32_e32 v58, 0, v58
	v_cvt_pk_bf16_f32 v148, v62, v63
	v_cvt_pk_bf16_f32 v149, v64, v65
	s_cmp_lg_u32 0, -1
	s_cselect_b32 s15, 0, 0
	v_add_f32_e32 v118, v182, v58
	v_lshl_add_u64 v[58:59], v[194:195], 0, s[38:39]
	s_add_i32 s15, s15, s68
	s_add_i32 s15, s15, 0x8000
	s_mov_b32 m0, s15
	s_nop 0
	global_load_lds_dwordx4 v[58:59], off
	v_max_f32_e32 v58, v82, v83
	v_max3_f32 v59, v84, v85, v67
	v_max3_f32 v58, v58, v66, v68
	v_max3_f32 v58, v58, v69, v86
	v_max3_f32 v59, v59, v88, v89
	v_max3_f32 v58, v58, v87, v70
	v_max3_f32 v59, v59, v72, v73
	v_max3_f32 v58, v58, v71, v90
	v_max3_f32 v59, v59, v92, v93
	v_max3_f32 v58, v58, v91, v74
	v_max3_f32 v59, v59, v76, v77
	v_max3_f32 v58, v58, v75, v94
	v_max3_f32 v59, v59, v96, v97
	v_max3_f32 v58, v58, v95, v78
	v_max3_f32 v59, v59, v80, v81
	v_max3_f32 v58, v58, v79, v59
	v_mov_b32_e32 v59, v58
	s_nop 1
	v_permlane32_swap_b32_e32 v58, v59
	v_max_f32_e32 v58, v58, v59
	v_cmp_lt_f32_e32 vcc, s82, v58
	s_cmp_lg_u64 vcc, 0
	s_cselect_b64 s[60:61], -1, 0
	s_cbranch_vccnz .LBB0_2616

; __device__ __forceinline__ void kmask(f32x16&p0,f32x16&p1,int rem,int hi){
;   const float NEG=-INFINITY;
;   #pragma unroll
;   for(int r=0;r<16;++r){int kv=4*hi+(r&3)+8*(r>>2); if(kv>=rem)p0[r]=NEG; if(kv+32>=rem)p1[r]=NEG;}
; }
.LBB0_2541:
	ds_read_b64_tr_b16 v[62:63], v208 offset:24576
	ds_read_b64_tr_b16 v[64:65], v208 offset:25088
	v_mfma_f32_32x32x16_bf16 v[34:49], v[114:117], v[142:145], v[34:49]
	v_add_f32_e32 v50, v82, v83
	v_add_f32_e32 v50, v84, v50
	v_add_f32_e32 v50, v85, v50
	v_add_f32_e32 v50, v86, v50
	v_add_f32_e32 v50, v87, v50
	v_cvt_pk_bf16_f32 v158, v82, v83
	v_cvt_pk_bf16_f32 v159, v84, v85
	ds_read_b64_tr_b16 v[102:103], v208 offset:28672
	ds_read_b64_tr_b16 v[104:105], v208 offset:29184
	v_add_f32_e32 v50, v88, v50
	v_add_f32_e32 v50, v89, v50
	v_add_f32_e32 v50, v90, v50
	v_add_f32_e32 v50, v91, v50
	v_cvt_pk_bf16_f32 v160, v86, v87
	v_cvt_pk_bf16_f32 v161, v88, v89
	ds_read_b64_tr_b16 v[98:99], v208 offset:25600
	ds_read_b64_tr_b16 v[100:101], v208 offset:26112
	v_mfma_f32_32x32x16_bf16 v[34:49], v[110:113], v[138:141], v[34:49]
	v_add_f32_e32 v50, v92, v50
	v_add_f32_e32 v50, v93, v50
	v_add_f32_e32 v50, v94, v50
	v_add_f32_e32 v50, v95, v50
	v_cvt_pk_bf16_f32 v154, v90, v91
	v_cvt_pk_bf16_f32 v155, v92, v93
	ds_read_b64_tr_b16 v[90:91], v208 offset:29696
	ds_read_b64_tr_b16 v[92:93], v208 offset:30208
	v_add_f32_e32 v50, v96, v50
	v_add_f32_e32 v50, v97, v50
	v_add_f32_e32 v50, v66, v50
	v_add_f32_e32 v50, v67, v50
	v_cvt_pk_bf16_f32 v156, v94, v95
	v_cvt_pk_bf16_f32 v157, v96, v97
	ds_read_b64_tr_b16 v[86:87], v208 offset:26624
	ds_read_b64_tr_b16 v[88:89], v208 offset:27136
	v_mfma_f32_32x32x16_bf16 v[34:49], v[106:109], v[134:137], v[34:49]
	v_add_f32_e32 v50, v68, v50
	v_add_f32_e32 v50, v69, v50
	v_add_f32_e32 v50, v70, v50
	v_add_f32_e32 v50, v71, v50
	v_cvt_pk_bf16_f32 v150, v66, v67
	v_cvt_pk_bf16_f32 v151, v68, v69
	ds_read_b64_tr_b16 v[82:83], v208 offset:30720
	ds_read_b64_tr_b16 v[84:85], v208 offset:31232
	v_add_f32_e32 v50, v72, v50
	v_add_f32_e32 v50, v73, v50
	v_add_f32_e32 v50, v74, v50
	v_add_f32_e32 v50, v75, v50
	v_cvt_pk_bf16_f32 v152, v70, v71
	v_cvt_pk_bf16_f32 v153, v72, v73
	ds_read_b64_tr_b16 v[70:71], v208 offset:27648
	ds_read_b64_tr_b16 v[72:73], v208 offset:28160
	v_mfma_f32_32x32x16_bf16 v[34:49], v[58:61], v[130:133], v[34:49]
	v_add_f32_e32 v50, v76, v50
	v_add_f32_e32 v50, v77, v50
	v_add_f32_e32 v50, v78, v50
	v_add_f32_e32 v50, v79, v50
	v_cvt_pk_bf16_f32 v146, v74, v75
	v_cvt_pk_bf16_f32 v147, v76, v77
	ds_read_b64_tr_b16 v[66:67], v208 offset:31744
	ds_read_b64_tr_b16 v[68:69], v208 offset:32256
	s_nop 3
	v_add_f32_e32 v42, v80, v50
	v_add_f32_e32 v42, v81, v42
	v_add_f32_e32 v42, 0, v42
	v_cvt_pk_bf16_f32 v148, v78, v79
	v_cvt_pk_bf16_f32 v149, v80, v81
	v_max_f32_e32 v44, v37, v37
	v_max_f32_e32 v45, v36, v36
	v_add_f32_e32 v74, v118, v42
	v_mov_b32_e32 v42, 0xff800000
	v_max_f32_e32 v44, v45, v44
	v_max3_f32 v43, v34, v35, v42
	v_max3_f32 v44, v44, v42, v40
	v_max3_f32 v43, v43, v38, v39
	v_max3_f32 v44, v44, v41, v42
	v_max3_f32 v43, v43, v42, v44
	v_mov_b32_e32 v44, v43
	s_nop 1
	v_permlane32_swap_b32_e32 v43, v44
	v_max_f32_e32 v43, v43, v44
	v_cmp_lt_f32_e32 vcc, s82, v43
	s_cmp_lg_u64 vcc, 0
	s_cselect_b64 s[60:61], -1, 0
	s_cbranch_vccnz .LBB0_2619

.LBB0_4093:
	ds_read_b64_tr_b16 v[166:167], v209 offset:40960
	ds_read_b64_tr_b16 v[168:169], v209 offset:41472
	v_mfma_f32_32x32x16_bf16 v[114:129], v[58:61], v[142:145], v[34:49]
	v_add_f32_e32 v50, v98, v99
	v_add_f32_e32 v50, v100, v50
	v_add_f32_e32 v50, v101, v50
	v_add_f32_e32 v50, v102, v50
	v_add_f32_e32 v50, v103, v50
	v_cvt_pk_bf16_f32 v158, v98, v99
	v_cvt_pk_bf16_f32 v159, v100, v101
	ds_read_b64_tr_b16 v[162:163], v209 offset:45056
	ds_read_b64_tr_b16 v[164:165], v209 offset:45568
	v_add_f32_e32 v50, v104, v50
	v_add_f32_e32 v50, v105, v50
	v_add_f32_e32 v50, v106, v50
	v_add_f32_e32 v66, v107, v50
	v_mfma_f32_32x32x16_bf16 v[50:65], v[182:185], v[142:145], v[34:49]
	v_cvt_pk_bf16_f32 v160, v102, v103
	v_cvt_pk_bf16_f32 v161, v104, v105
	ds_read_b64_tr_b16 v[102:103], v209 offset:41984
	ds_read_b64_tr_b16 v[104:105], v209 offset:42496
	v_mfma_f32_32x32x16_bf16 v[114:129], v[186:189], v[138:141], v[114:129]
	v_add_f32_e32 v66, v108, v66
	v_add_f32_e32 v66, v109, v66
	v_add_f32_e32 v66, v110, v66
	v_add_f32_e32 v66, v111, v66
	v_cvt_pk_bf16_f32 v154, v106, v107
	v_cvt_pk_bf16_f32 v155, v108, v109
	ds_read_b64_tr_b16 v[98:99], v209 offset:46080
	ds_read_b64_tr_b16 v[100:101], v209 offset:46592
	v_mfma_f32_32x32x16_bf16 v[50:65], v[78:81], v[138:141], v[50:65]
	v_add_f32_e32 v66, v112, v66
	v_add_f32_e32 v66, v113, v66
	v_add_f32_e32 v66, v82, v66
	v_add_f32_e32 v66, v83, v66
	v_cvt_pk_bf16_f32 v156, v110, v111
	v_cvt_pk_bf16_f32 v157, v112, v113
	ds_read_b64_tr_b16 v[78:79], v209 offset:43008
	ds_read_b64_tr_b16 v[80:81], v209 offset:43520
	v_mfma_f32_32x32x16_bf16 v[114:129], v[74:77], v[134:137], v[114:129]
	v_add_f32_e32 v66, v84, v66
	v_add_f32_e32 v66, v85, v66
	v_add_f32_e32 v66, v86, v66
	v_add_f32_e32 v66, v87, v66
	v_cvt_pk_bf16_f32 v150, v82, v83
	v_cvt_pk_bf16_f32 v151, v84, v85
	ds_read_b64_tr_b16 v[74:75], v209 offset:47104
	ds_read_b64_tr_b16 v[76:77], v209 offset:47616
	v_mfma_f32_32x32x16_bf16 v[50:65], v[174:177], v[134:137], v[50:65]
	v_add_f32_e32 v66, v88, v66
	v_add_f32_e32 v66, v89, v66
	v_add_f32_e32 v66, v90, v66
	v_add_f32_e32 v66, v91, v66
	v_cvt_pk_bf16_f32 v152, v86, v87
	v_cvt_pk_bf16_f32 v153, v88, v89
	ds_read_b64_tr_b16 v[70:71], v209 offset:44032
	ds_read_b64_tr_b16 v[72:73], v209 offset:44544
	v_mfma_f32_32x32x16_bf16 v[114:129], v[178:181], v[130:133], v[114:129]
	v_add_f32_e32 v66, v92, v66
	v_add_f32_e32 v66, v93, v66
	v_add_f32_e32 v66, v94, v66
	v_add_f32_e32 v82, v95, v66
	v_cvt_pk_bf16_f32 v146, v90, v91
	v_cvt_pk_bf16_f32 v147, v92, v93
	ds_read_b64_tr_b16 v[66:67], v209 offset:48128
	ds_read_b64_tr_b16 v[68:69], v209 offset:48640
	v_mfma_f32_32x32x16_bf16 v[50:65], v[170:173], v[130:133], v[50:65]
	v_add_f32_e32 v82, v96, v82
	v_add_f32_e32 v82, v97, v82
	v_add_f32_e32 v82, 0, v82
	v_cvt_pk_bf16_f32 v148, v94, v95
	v_cvt_pk_bf16_f32 v149, v96, v97
	s_cmp_lg_u32 0, -1
	s_cselect_b32 s15, 0, 0
	v_add_f32_e32 v182, v197, v82
	v_lshl_add_u64 v[82:83], v[194:195], 0, s[38:39]
	s_add_i32 s15, s15, s69
	s_add_i32 s15, s15, 0x8000
	s_mov_b32 m0, s15
	s_nop 0
	global_load_lds_dwordx4 v[82:83], off
	v_max_f32_e32 v82, v114, v115
	v_max3_f32 v83, v116, v117, v51
	v_max3_f32 v82, v82, v50, v52
	v_max3_f32 v82, v82, v53, v118
	v_max3_f32 v83, v83, v120, v121
	v_max3_f32 v82, v82, v119, v54
	v_max3_f32 v83, v83, v56, v57
	v_max3_f32 v82, v82, v55, v122
	v_max3_f32 v83, v83, v124, v125
	v_max3_f32 v82, v82, v123, v58
	v_max3_f32 v83, v83, v60, v61
	v_max3_f32 v82, v82, v59, v126
	v_max3_f32 v83, v83, v128, v129
	v_max3_f32 v82, v82, v127, v62
	v_max3_f32 v83, v83, v64, v65
	v_max3_f32 v82, v82, v63, v83
	v_mov_b32_e32 v83, v82
	s_nop 1
	v_permlane32_swap_b32_e32 v82, v83
	v_max_f32_e32 v82, v82, v83
	v_cmp_lt_f32_e32 vcc, s82, v82
	s_cmp_lg_u64 vcc, 0
	s_cselect_b64 s[60:61], -1, 0
	s_cbranch_vccnz .LBB0_4200

;   #define DMA_K(t,slot) glds16(ksrc+(long)(t)*KVBLK*KP,(unsigned)__builtin_amdgcn_readfirstlane(kdst+(slot)))
;   #define DMA_V(t,slot) glds16(vsrc+(long)(t)*KVBLK*KP,(unsigned)__builtin_amdgcn_readfirstlane(vdst+(slot)))
; template<int THRL,int L,int NT> __device__ __forceinline__ void attn_unit(long rowbase,int kvh,int qblk,const bf16*Q,const bf16*__restrict__ K,const bf16*__restrict__ V,bf16*O,char*shm,const int tid){
;   const int lane=tid&63,r32=lane&31,hi=lane>>5; const int wid=__builtin_amdgcn_readfirstlane(tid>>6);
;   const int q0=qblk*64, qh=wid>>1, rh=wid&1;
;   const bf16*Qw=Q+(rowbase+q0+rh*QBLK)*QP+(4*kvh+qh)*D;
;   const bf16*Kh=K+rowbase*KP+kvh*D,*Vh=V+rowbase*KP+kvh*D;
;   const unsigned lds0=(unsigned)(uintptr_t)shm;
;   float*wsf=(float*)(shm+LDS_WS)+wid*64;
;   const bf16*ksrc=Kh+(long)lane*KP+wid*8;
;   const bf16*vsrc=Vh+(long)(16*(wid&3)+(lane>>2))*KP+(wid>>2)*32+(lane&3)*8;
;   const unsigned kdst=lds0+LDS_K+wid*1024, vdst=lds0+LDS_V+wid*1024;
;     ...
;   const int vb0=(int)(lds0+LDS_V)+((lane>>4)&1)*32+(lane&3)*8+(4*hi+((lane&15)>>2))*64;
;   const char*Kbase=shm+LDS_K; bf16x8 kf[8];
;   const lds_cptr shm3=(lds_cptr)shm; const lds_cptr kp0=shm3+LDS_K+hi*1024+r32*16; const lds_cptr vp0=shm3+LDS_V+((lane>>4)&1)*32+(lane&3)*8+(4*hi+((lane&15)>>2))*64;
;   DMA_K(0,0);DMA_V(0,0);DMA_K(1,SLOTB);
;   bf16x8 qr[4];
;   #pragma unroll
;   for(int d0=0;d0<4;++d0)qr[d0]=*reinterpret_cast<const bf16x8*>(&Qw[(long)r32*QP+d0*16+hi*8]);
;   if(q0+rh*QBLK+r32>=L){
;     #pragma unroll
;     for(int d0=0;d0<4;++d0)qr[d0]=bf16x8{0,0,0,0,0,0,0,0}; }
; __device__ __forceinline__ void attention_phase(const PT a, unsigned char* ws, int l, unsigned char* lds_generic, int tid, bool dry = false) {
;     ...
;         if (u < ATT_UNITS_P) { const int s = u / 260, rem = u - s * 260, kvh = rem / 65, qblk = rem - kvh * 65;
;             attn_body::attn_unit<8, LP, 65>((long)s * LP, kvh, qblk, Q, K, V, O, (char*)lds_generic, tidu); }
.LBB0_4113:
	s_and_b64 vcc, exec, s[4:5]
	s_cbranch_vccz .LBB0_4154
	s_mul_hi_i32 s4, s66, 0x7e07e07f
	s_lshr_b32 s5, s4, 31
	s_ashr_i32 s4, s4, 7
	s_add_i32 s97, s4, s5
	s_mul_i32 s4, s97, 0xfffffefc
	s_add_i32 s4, s4, s66
	s_mul_hi_i32 s5, s4, 0x7e07e07f
	s_lshr_b32 s15, s5, 31
	s_ashr_i32 s5, s5, 5
	s_add_i32 s18, s5, s15
	s_mul_i32 s5, s18, 0xffffffbf
	s_add_i32 s5, s5, s4
	v_readfirstlane_b32 s15, v204
	s_lshl_b32 s66, s5, 6
	s_mul_i32 s19, s97, 0x1010
	s_ashr_i32 s67, s15, 6
	s_ashr_i32 s5, s66, 31
	s_mul_hi_i32 s4, s97, 0x1010
	s_add_u32 s19, s19, s66
	s_addc_u32 s5, s4, s5
	s_lshl_b32 s4, s67, 5
	s_and_b32 s92, s4, 32
	s_add_u32 s4, s19, s92
	s_addc_u32 s5, s5, 0
	s_lshl_b64 s[4:5], s[4:5], 11
	s_add_u32 s19, s6, s4
	s_addc_u32 s59, s71, s5
	s_ashr_i32 s5, s15, 1
	s_lshl_b32 s4, s18, 8
	s_andn2_b32 s5, s5, 63
	s_add_i32 s4, s5, s4
	s_ashr_i32 s5, s4, 31
	s_lshl_b64 s[4:5], s[4:5], 1
	s_add_u32 s58, s19, s4
	s_addc_u32 s59, s59, s5
	s_mul_hi_i32 s96, s97, 0x202000
	s_mul_i32 s97, s97, 0x202000
	s_add_u32 s19, s72, s97
	s_addc_u32 s62, s73, s96
	s_lshl_b32 s4, s18, 6
	s_ashr_i32 s5, s4, 31
	s_lshl_b64 s[60:61], s[4:5], 1
	s_add_u32 s4, s19, s60
	s_addc_u32 s5, s62, s61
	s_add_u32 s18, s74, s97
	s_addc_u32 s19, s75, s96
	s_add_u32 s18, s18, s60
	s_addc_u32 s19, s19, s61
	s_lshl_b32 s62, s67, 3
	v_lshl_add_u64 v[2:3], s[4:5], 0, v[192:193]
	s_ashr_i32 s63, s62, 31
	s_lshl_b32 s4, s67, 4
	v_lshl_add_u64 v[186:187], s[62:63], 1, v[2:3]
	v_and_or_b32 v2, s4, 48, v203
	s_ashr_i32 s4, s15, 3
	s_and_b32 s64, s4, 0xffffffe0
	s_ashr_i32 s65, s64, 31
	s_lshl_b32 s68, s67, 10
	v_lshlrev_b32_e32 v2, 9, v2
	v_mov_b32_e32 v3, v193
	s_cmp_lg_u32 0, -1
	v_lshl_add_u64 v[2:3], s[18:19], 0, v[2:3]
	s_cselect_b32 s4, 0, 0
	v_lshl_add_u64 v[2:3], s[64:65], 1, v[2:3]
	v_lshlrev_b32_e32 v4, 1, v202
	v_mov_b32_e32 v5, v193
	s_add_i32 s93, s68, s4
	s_mov_b32 m0, s93
	s_nop 0
	global_load_lds_dwordx4 v[186:187], off
	v_lshl_add_u64 v[194:195], v[2:3], 0, v[4:5]
	s_add_i32 s69, s93, 0x6000
	s_mov_b32 m0, s69
	s_nop 0
	global_load_lds_dwordx4 v[194:195], off
	v_lshl_add_u64 v[2:3], v[186:187], 0, s[26:27]
	s_add_i32 s4, s93, 0x2000
	s_mov_b32 m0, s4
	s_nop 0
	global_load_lds_dwordx4 v[2:3], off
	v_lshl_or_b32 v2, v201, 4, v205
	global_load_dwordx4 v[142:145], v2, s[58:59]
	global_load_dwordx4 v[138:141], v2, s[58:59] offset:32
	global_load_dwordx4 v[134:137], v2, s[58:59] offset:64
	global_load_dwordx4 v[130:133], v2, s[58:59] offset:96
	s_or_b32 s66, s92, s66
	v_or_b32_e32 v2, s66, v200
	v_cmp_lt_i32_e32 vcc, s84, v2
	s_and_saveexec_b64 s[4:5], vcc
	s_cbranch_execz .LBB0_4116
	s_waitcnt vmcnt(3)
	v_mov_b32_e32 v142, 0
	v_mov_b32_e32 v143, v142
	v_mov_b32_e32 v144, v142
	v_mov_b32_e32 v145, v142
	s_waitcnt vmcnt(2)
	v_mov_b32_e32 v138, v142
	v_mov_b32_e32 v139, v142
	v_mov_b32_e32 v140, v142
	v_mov_b32_e32 v141, v142
	s_waitcnt vmcnt(1)
	v_mov_b32_e32 v134, v142
	v_mov_b32_e32 v135, v142
	v_mov_b32_e32 v136, v142
	v_mov_b32_e32 v137, v142
	s_waitcnt vmcnt(0)
	v_mov_b32_e32 v130, v142
	v_mov_b32_e32 v131, v142
	v_mov_b32_e32 v132, v142
	v_mov_b32_e32 v133, v142

.LBB0_4131:
	ds_read_b64_tr_b16 v[178:179], v208 offset:24576
	ds_read_b64_tr_b16 v[180:181], v208 offset:25088
	s_waitcnt lgkmcnt(9)
	v_mfma_f32_32x32x16_bf16 v[98:113], v[82:85], v[142:145], v[34:49]
	v_add_f32_e32 v86, v66, v67
	v_add_f32_e32 v86, v68, v86
	v_add_f32_e32 v86, v69, v86
	v_add_f32_e32 v86, v70, v86
	v_add_f32_e32 v86, v71, v86
	v_cvt_pk_bf16_f32 v158, v66, v67
	v_cvt_pk_bf16_f32 v159, v68, v69
	ds_read_b64_tr_b16 v[174:175], v208 offset:28672
	ds_read_b64_tr_b16 v[176:177], v208 offset:29184
	v_add_f32_e32 v66, v72, v86
	s_waitcnt lgkmcnt(10)
	v_mfma_f32_32x32x16_bf16 v[82:97], v[170:173], v[142:145], v[34:49]
	v_add_f32_e32 v66, v73, v66
	v_add_f32_e32 v66, v74, v66
	v_add_f32_e32 v66, v75, v66
	v_cvt_pk_bf16_f32 v160, v70, v71
	v_cvt_pk_bf16_f32 v161, v72, v73
	ds_read_b64_tr_b16 v[170:171], v208 offset:25600
	ds_read_b64_tr_b16 v[172:173], v208 offset:26112
	s_waitcnt lgkmcnt(11)
	v_mfma_f32_32x32x16_bf16 v[98:113], v[166:169], v[138:141], v[98:113]
	v_add_f32_e32 v66, v76, v66
	v_add_f32_e32 v66, v77, v66
	v_add_f32_e32 v66, v78, v66
	v_add_f32_e32 v66, v79, v66
	v_cvt_pk_bf16_f32 v154, v74, v75
	v_cvt_pk_bf16_f32 v155, v76, v77
	ds_read_b64_tr_b16 v[74:75], v208 offset:29696
	ds_read_b64_tr_b16 v[76:77], v208 offset:30208
	s_waitcnt lgkmcnt(12)
	v_mfma_f32_32x32x16_bf16 v[82:97], v[162:165], v[138:141], v[82:97]
	v_add_f32_e32 v66, v80, v66
	v_add_f32_e32 v66, v81, v66
	v_add_f32_e32 v66, v50, v66
	v_add_f32_e32 v66, v51, v66
	v_cvt_pk_bf16_f32 v156, v78, v79
	v_cvt_pk_bf16_f32 v157, v80, v81
	ds_read_b64_tr_b16 v[70:71], v208 offset:26624
	ds_read_b64_tr_b16 v[72:73], v208 offset:27136
	s_waitcnt lgkmcnt(13)
	v_mfma_f32_32x32x16_bf16 v[98:113], v[126:129], v[134:137], v[98:113]
	v_add_f32_e32 v66, v52, v66
	v_add_f32_e32 v66, v53, v66
	v_add_f32_e32 v66, v54, v66
	v_add_f32_e32 v78, v55, v66
	v_cvt_pk_bf16_f32 v150, v50, v51
	v_cvt_pk_bf16_f32 v151, v52, v53
	ds_read_b64_tr_b16 v[66:67], v208 offset:30720
	ds_read_b64_tr_b16 v[68:69], v208 offset:31232
	s_waitcnt lgkmcnt(14)
	v_mfma_f32_32x32x16_bf16 v[82:97], v[122:125], v[134:137], v[82:97]
	v_add_f32_e32 v50, v56, v78
	v_add_f32_e32 v50, v57, v50
	v_add_f32_e32 v50, v58, v50
	v_add_f32_e32 v50, v59, v50
	v_cvt_pk_bf16_f32 v152, v54, v55
	v_cvt_pk_bf16_f32 v153, v56, v57
	ds_read_b64_tr_b16 v[54:55], v208 offset:27648
	ds_read_b64_tr_b16 v[56:57], v208 offset:28160
	s_waitcnt lgkmcnt(14)
	v_mfma_f32_32x32x16_bf16 v[98:113], v[118:121], v[130:133], v[98:113]
	v_add_f32_e32 v50, v60, v50
	v_add_f32_e32 v50, v61, v50
	v_add_f32_e32 v50, v62, v50
	v_add_f32_e32 v78, v63, v50
	v_cvt_pk_bf16_f32 v146, v58, v59
	v_cvt_pk_bf16_f32 v147, v60, v61
	ds_read_b64_tr_b16 v[50:51], v208 offset:31744
	ds_read_b64_tr_b16 v[52:53], v208 offset:32256
	v_mfma_f32_32x32x16_bf16 v[82:97], v[114:117], v[130:133], v[82:97]
	v_add_f32_e32 v58, v64, v78
	v_add_f32_e32 v58, v65, v58
	v_add_f32_e32 v58, 0, v58
	v_cvt_pk_bf16_f32 v148, v62, v63
	v_cvt_pk_bf16_f32 v149, v64, v65
	s_cmp_lg_u32 0, -1
	s_cselect_b32 s15, 0, 0
	v_add_f32_e32 v196, v182, v58
	v_lshl_add_u64 v[58:59], v[186:187], 0, s[40:41]
	s_add_i32 s15, s15, s68
	s_add_i32 s18, s15, 0x2000
	s_mov_b32 m0, s18
	s_nop 0
	global_load_lds_dwordx4 v[58:59], off
	v_lshl_add_u64 v[58:59], v[194:195], 0, s[42:43]
	s_add_i32 s15, s15, 0xa000
	s_mov_b32 m0, s15
	s_nop 0
	global_load_lds_dwordx4 v[58:59], off
	v_max_f32_e32 v58, v98, v99
	v_max3_f32 v59, v100, v101, v83
	v_max3_f32 v58, v58, v82, v84
	v_max3_f32 v58, v58, v85, v102
	v_max3_f32 v59, v59, v104, v105
	v_max3_f32 v58, v58, v103, v86
	v_max3_f32 v59, v59, v88, v89
	v_max3_f32 v58, v58, v87, v106
	v_max3_f32 v59, v59, v108, v109
	v_max3_f32 v58, v58, v107, v90
	v_max3_f32 v59, v59, v92, v93
	v_max3_f32 v58, v58, v91, v110
	v_max3_f32 v59, v59, v112, v113
	v_max3_f32 v58, v58, v111, v94
	v_max3_f32 v59, v59, v96, v97
	v_max3_f32 v58, v58, v95, v59
	v_mov_b32_e32 v59, v58
	s_nop 1
	v_permlane32_swap_b32_e32 v58, v59
	v_max_f32_e32 v58, v58, v59
	v_cmp_lt_f32_e32 vcc, s82, v58
	s_cmp_lg_u64 vcc, 0
	s_cselect_b64 s[60:61], -1, 0
	s_cbranch_vccnz .LBB0_4209

.LBB0_4134:
	ds_read_b64_tr_b16 v[166:167], v208 offset:32768
	ds_read_b64_tr_b16 v[168:169], v208 offset:33280
	v_mfma_f32_32x32x16_bf16 v[114:129], v[58:61], v[142:145], v[34:49]
	v_add_f32_e32 v50, v98, v99
	v_add_f32_e32 v50, v100, v50
	v_add_f32_e32 v50, v101, v50
	v_add_f32_e32 v50, v102, v50
	v_add_f32_e32 v50, v103, v50
	v_cvt_pk_bf16_f32 v158, v98, v99
	v_cvt_pk_bf16_f32 v159, v100, v101
	ds_read_b64_tr_b16 v[162:163], v208 offset:36864
	ds_read_b64_tr_b16 v[164:165], v208 offset:37376
	v_add_f32_e32 v50, v104, v50
	v_add_f32_e32 v50, v105, v50
	v_add_f32_e32 v50, v106, v50
	v_add_f32_e32 v66, v107, v50
	v_mfma_f32_32x32x16_bf16 v[50:65], v[182:185], v[142:145], v[34:49]
	v_cvt_pk_bf16_f32 v160, v102, v103
	v_cvt_pk_bf16_f32 v161, v104, v105
	ds_read_b64_tr_b16 v[102:103], v208 offset:33792
	ds_read_b64_tr_b16 v[104:105], v208 offset:34304
	v_mfma_f32_32x32x16_bf16 v[114:129], v[186:189], v[138:141], v[114:129]
	v_add_f32_e32 v66, v108, v66
	v_add_f32_e32 v66, v109, v66
	v_add_f32_e32 v66, v110, v66
	v_add_f32_e32 v66, v111, v66
	v_cvt_pk_bf16_f32 v154, v106, v107
	v_cvt_pk_bf16_f32 v155, v108, v109
	ds_read_b64_tr_b16 v[98:99], v208 offset:37888
	ds_read_b64_tr_b16 v[100:101], v208 offset:38400
	v_mfma_f32_32x32x16_bf16 v[50:65], v[78:81], v[138:141], v[50:65]
	v_add_f32_e32 v66, v112, v66
	v_add_f32_e32 v66, v113, v66
	v_add_f32_e32 v66, v82, v66
	v_add_f32_e32 v66, v83, v66
	v_cvt_pk_bf16_f32 v156, v110, v111
	v_cvt_pk_bf16_f32 v157, v112, v113
	ds_read_b64_tr_b16 v[78:79], v208 offset:34816
	ds_read_b64_tr_b16 v[80:81], v208 offset:35328
	v_mfma_f32_32x32x16_bf16 v[114:129], v[74:77], v[134:137], v[114:129]
	v_add_f32_e32 v66, v84, v66
	v_add_f32_e32 v66, v85, v66
	v_add_f32_e32 v66, v86, v66
	v_add_f32_e32 v66, v87, v66
	v_cvt_pk_bf16_f32 v150, v82, v83
	v_cvt_pk_bf16_f32 v151, v84, v85
	ds_read_b64_tr_b16 v[74:75], v208 offset:38912
	ds_read_b64_tr_b16 v[76:77], v208 offset:39424
	v_mfma_f32_32x32x16_bf16 v[50:65], v[174:177], v[134:137], v[50:65]
	v_add_f32_e32 v66, v88, v66
	v_add_f32_e32 v66, v89, v66
	v_add_f32_e32 v66, v90, v66
	v_add_f32_e32 v66, v91, v66
	v_cvt_pk_bf16_f32 v152, v86, v87
	v_cvt_pk_bf16_f32 v153, v88, v89
	ds_read_b64_tr_b16 v[70:71], v208 offset:35840
	ds_read_b64_tr_b16 v[72:73], v208 offset:36352
	v_mfma_f32_32x32x16_bf16 v[114:129], v[178:181], v[130:133], v[114:129]
	v_add_f32_e32 v66, v92, v66
	v_add_f32_e32 v66, v93, v66
	v_add_f32_e32 v66, v94, v66
	v_add_f32_e32 v82, v95, v66
	v_cvt_pk_bf16_f32 v146, v90, v91
	v_cvt_pk_bf16_f32 v147, v92, v93
	ds_read_b64_tr_b16 v[66:67], v208 offset:39936
	ds_read_b64_tr_b16 v[68:69], v208 offset:40448
	v_mfma_f32_32x32x16_bf16 v[50:65], v[170:173], v[130:133], v[50:65]
	v_add_f32_e32 v82, v96, v82
	v_add_f32_e32 v82, v97, v82
	v_add_f32_e32 v82, 0, v82
	v_cvt_pk_bf16_f32 v148, v94, v95
	v_cvt_pk_bf16_f32 v149, v96, v97
	s_nop 0
	v_add_f32_e32 v182, v196, v82
	v_lshl_add_u64 v[82:83], v[194:195], 0, s[44:45]
	s_mov_b32 m0, s69
	s_nop 0
	global_load_lds_dwordx4 v[82:83], off
	v_max_f32_e32 v82, v114, v115
	s_nop 0
	v_max3_f32 v83, v116, v117, v51
	v_max3_f32 v82, v82, v50, v52
	v_max3_f32 v82, v82, v53, v118
	v_max3_f32 v83, v83, v120, v121
	v_max3_f32 v82, v82, v119, v54
	v_max3_f32 v83, v83, v56, v57
	v_max3_f32 v82, v82, v55, v122
	v_max3_f32 v83, v83, v124, v125
	v_max3_f32 v82, v82, v123, v58
	v_max3_f32 v83, v83, v60, v61
	v_max3_f32 v82, v82, v59, v126
	v_max3_f32 v83, v83, v128, v129
	v_max3_f32 v82, v82, v127, v62
	v_max3_f32 v83, v83, v64, v65
	v_max3_f32 v82, v82, v63, v83
	v_mov_b32_e32 v83, v82
	s_nop 1
	v_permlane32_swap_b32_e32 v82, v83
	v_max_f32_e32 v82, v82, v83
	v_cmp_lt_f32_e32 vcc, s82, v82
	s_cmp_lg_u64 vcc, 0
	s_cselect_b64 s[60:61], -1, 0
	s_cbranch_vccnz .LBB0_4212

.LBB0_4137:
	ds_read_b64_tr_b16 v[162:163], v208 offset:40960
	ds_read_b64_tr_b16 v[164:165], v208 offset:41472
	v_mfma_f32_32x32x16_bf16 v[82:97], v[110:113], v[142:145], v[34:49]
	v_add_f32_e32 v66, v114, v115
	v_add_f32_e32 v66, v116, v66
	v_add_f32_e32 v66, v117, v66
	v_add_f32_e32 v66, v118, v66
	v_add_f32_e32 v66, v119, v66
	v_cvt_pk_bf16_f32 v158, v114, v115
	v_cvt_pk_bf16_f32 v159, v116, v117
	ds_read_b64_tr_b16 v[114:115], v208 offset:45056
	ds_read_b64_tr_b16 v[116:117], v208 offset:45568
	v_add_f32_e32 v66, v120, v66
	v_add_f32_e32 v66, v121, v66
	v_add_f32_e32 v66, v122, v66
	v_add_f32_e32 v146, v123, v66
	v_mfma_f32_32x32x16_bf16 v[66:81], v[106:109], v[142:145], v[34:49]
	v_cvt_pk_bf16_f32 v160, v118, v119
	v_cvt_pk_bf16_f32 v161, v120, v121
	ds_read_b64_tr_b16 v[110:111], v208 offset:41984
	ds_read_b64_tr_b16 v[112:113], v208 offset:42496
	v_mfma_f32_32x32x16_bf16 v[82:97], v[178:181], v[138:141], v[82:97]
	v_add_f32_e32 v106, v124, v146
	v_add_f32_e32 v106, v125, v106
	v_add_f32_e32 v106, v126, v106
	v_add_f32_e32 v118, v127, v106
	v_cvt_pk_bf16_f32 v154, v122, v123
	v_cvt_pk_bf16_f32 v155, v124, v125
	ds_read_b64_tr_b16 v[106:107], v208 offset:46080
	ds_read_b64_tr_b16 v[108:109], v208 offset:46592
	v_mfma_f32_32x32x16_bf16 v[66:81], v[102:105], v[138:141], v[66:81]
	v_add_f32_e32 v118, v128, v118
	v_add_f32_e32 v118, v129, v118
	v_add_f32_e32 v118, v50, v118
	v_add_f32_e32 v118, v51, v118
	v_cvt_pk_bf16_f32 v156, v126, v127
	v_cvt_pk_bf16_f32 v157, v128, v129
	ds_read_b64_tr_b16 v[102:103], v208 offset:43008
	ds_read_b64_tr_b16 v[104:105], v208 offset:43520
	v_mfma_f32_32x32x16_bf16 v[82:97], v[98:101], v[134:137], v[82:97]
	v_add_f32_e32 v118, v52, v118
	v_add_f32_e32 v118, v53, v118
	v_add_f32_e32 v118, v54, v118
	v_add_f32_e32 v118, v55, v118
	v_cvt_pk_bf16_f32 v150, v50, v51
	v_cvt_pk_bf16_f32 v151, v52, v53
	ds_read_b64_tr_b16 v[98:99], v208 offset:47104
	ds_read_b64_tr_b16 v[100:101], v208 offset:47616
	v_mfma_f32_32x32x16_bf16 v[66:81], v[170:173], v[134:137], v[66:81]
	v_add_f32_e32 v50, v56, v118
	v_add_f32_e32 v50, v57, v50
	v_add_f32_e32 v50, v58, v50
	v_add_f32_e32 v50, v59, v50
	v_cvt_pk_bf16_f32 v152, v54, v55
	v_cvt_pk_bf16_f32 v153, v56, v57
	ds_read_b64_tr_b16 v[54:55], v208 offset:44032
	ds_read_b64_tr_b16 v[56:57], v208 offset:44544
	v_mfma_f32_32x32x16_bf16 v[82:97], v[174:177], v[130:133], v[82:97]
	v_add_f32_e32 v50, v60, v50
	v_add_f32_e32 v50, v61, v50
	v_add_f32_e32 v50, v62, v50
	v_add_f32_e32 v118, v63, v50
	v_cvt_pk_bf16_f32 v146, v58, v59
	v_cvt_pk_bf16_f32 v147, v60, v61
	ds_read_b64_tr_b16 v[50:51], v208 offset:48128
	ds_read_b64_tr_b16 v[52:53], v208 offset:48640
	v_mfma_f32_32x32x16_bf16 v[66:81], v[166:169], v[130:133], v[66:81]
	v_add_f32_e32 v58, v64, v118
	v_add_f32_e32 v58, v65, v58
	v_add_f32_e32 v58, 0, v58
	v_cvt_pk_bf16_f32 v148, v62, v63
	v_cvt_pk_bf16_f32 v149, v64, v65
	s_cmp_lg_u32 0, -1
	s_cselect_b32 s15, 0, 0
	v_add_f32_e32 v118, v182, v58
	v_lshl_add_u64 v[58:59], v[194:195], 0, s[40:41]
	s_add_i32 s15, s15, s68
	s_add_i32 s15, s15, 0x8000
	s_mov_b32 m0, s15
	s_nop 0
	global_load_lds_dwordx4 v[58:59], off
	v_max_f32_e32 v58, v82, v83
	v_max3_f32 v59, v84, v85, v67
	v_max3_f32 v58, v58, v66, v68
	v_max3_f32 v58, v58, v69, v86
	v_max3_f32 v59, v59, v88, v89
	v_max3_f32 v58, v58, v87, v70
	v_max3_f32 v59, v59, v72, v73
	v_max3_f32 v58, v58, v71, v90
	v_max3_f32 v59, v59, v92, v93
	v_max3_f32 v58, v58, v91, v74
	v_max3_f32 v59, v59, v76, v77
	v_max3_f32 v58, v58, v75, v94
	v_max3_f32 v59, v59, v96, v97
	v_max3_f32 v58, v58, v95, v78
	v_max3_f32 v59, v59, v80, v81
	v_max3_f32 v58, v58, v79, v59
	v_mov_b32_e32 v59, v58
	s_nop 1
	v_permlane32_swap_b32_e32 v58, v59
	v_max_f32_e32 v58, v58, v59
	v_cmp_lt_f32_e32 vcc, s82, v58
	s_cmp_lg_u64 vcc, 0
	s_cselect_b64 s[60:61], -1, 0
	s_cbranch_vccnz .LBB0_4215
